# baseline (speedup 1.0000x reference)
; #define PG8_STAGE(bufoff, gbase, voff) do { _Pragma("unroll") for (int _i = 0; _i < 2; ++_i) \
;         __builtin_amdgcn_global_load_lds((const unsigned*)((const char*)(gbase) + (voff)[_i]), (LAS unsigned*)(lds + (bufoff) + ldsw + _i * 8192), 16, 0, 0); } while (0)
; #define PG8_LDA(dst, b, h) do { _Pragma("unroll") for (int m = 0; m < 4; ++m) _Pragma("unroll") for (int k = 0; k < 2; ++k) dst[m][k] = *(const LAS bf16x8*)(lds + PG8_SA(b, h) + aoff + m * 2048 + k * 1024); } while (0)
; #define PG8_LDB(dst, b, h) do { _Pragma("unroll") for (int n = 0; n < 2; ++n) _Pragma("unroll") for (int k = 0; k < 2; ++k) dst[n][k] = *(const LAS bf16x8*)(lds + PG8_SB(b, h) + boff + n * 2048 + k * 1024); } while (0)
; #define PG8_MMA(ai, bj, At, Bt) do { __builtin_amdgcn_s_setprio(1); _Pragma("unroll") for (int m = 0; m < 4; ++m) _Pragma("unroll") for (int n = 0; n < 2; ++n) _Pragma("unroll") for (int k = 0; k < 2; ++k) \
;         acc[ai][bj][m][n] = __builtin_amdgcn_mfma_f32_16x16x32_bf16(Bt[n][k], At[m][k], acc[ai][bj][m][n], 0, 0, 0); __builtin_amdgcn_s_setprio(0); } while (0)
; #define PG8_WAIT_V(n) asm volatile("s_waitcnt vmcnt(" #n ")" ::: "memory")
; #define PG8_WAIT_L(n) asm volatile("s_waitcnt lgkmcnt(" #n ")" ::: "memory")
; #define PG8_BAR __builtin_amdgcn_s_barrier()
; #define PG8_SCHED __builtin_amdgcn_sched_barrier(0)
; template <class Epi, class Sched>
; __device__ __forceinline__ void gemm_phase(const int tid, LAS unsigned char* lds, const Gemm g, const Sched& S, const Epi& E) {
;     ...
;     for (;;) {
;         const bool has_next = S.next(ui + 1, nxt);
;         const char* nA = has_next ? (const char*)g.A + (size_t)nxt.pm * tstep : cA; const char* nB = has_next ? (const char*)g.Bt + (size_t)nxt.pn * tstep : cB;
;         for (int t = 0; t < nt; t += 2) {
;             const bool last = (t == nt - 2);
;             const char* a1 = cA + (size_t)(t + 1) * kstep;
;             const char* a2 = last ? nA : cA + (size_t)(t + 2) * kstep; const char* b2 = last ? nB : cB + (size_t)(t + 2) * kstep;
;             const char* a3 = a2 + kstep; const char* b3 = b2 + kstep;
;             if (last && has_next) S.a_ready(nxt);
;             PG8_LDB(B0, 0, 0); PG8_LDB(B1, 0, 1); PG8_SCHED; PG8_LDA(At, 0, 0); PG8_STAGE(PG8_SA(1, 1), a1 + hstep, voffA);
;             PG8_WAIT_V(8); PG8_WAIT_L(0); PG8_BAR; PG8_MMA(0, 0, At, B0); PG8_MMA(0, 1, At, B1); PG8_BAR; PG8_SCHED;
.LBB0_49:
	s_ashr_i32 s15, s14, 31
	s_lshl_b64 s[16:17], s[14:15], 20
	s_add_u32 s16, s41, s16
	s_addc_u32 s17, s55, s17
	s_and_b64 s[18:19], s[0:1], exec
	s_cselect_b32 s15, s17, s23
	s_cselect_b32 s66, s16, s22
	s_ashr_i32 s13, s12, 31
	s_lshl_b64 s[18:19], s[12:13], 20
	v_readlane_b32 s13, v243, 16
	s_add_u32 s18, s13, s18
	v_readlane_b32 s13, v243, 17
	s_addc_u32 s19, s13, s19
	s_and_b64 s[26:27], s[0:1], exec
	s_cselect_b32 s13, s19, s25
	s_cselect_b32 s67, s18, s24
	s_add_u32 s22, s22, 0x80080
	s_addc_u32 s23, s23, 0
	s_add_u32 s68, s24, 0x100
	v_mov_b32_e32 v0, 0
	s_addc_u32 s69, s25, 0
	s_mov_b32 s70, -2
	s_add_u32 s24, s22, 0xfff80080
	s_addc_u32 s25, s23, -1
	s_add_i32 s71, 0, 0x10000
	s_cmp_eq_u32 s70, 28
	s_cselect_b32 s27, s15, s25
	s_cselect_b32 s26, s66, s24
	v_add_u32_e32 v150, s71, v148
	s_cselect_b32 s25, s13, s69
	s_cselect_b32 s24, s67, s68
	s_add_i32 s74, 0, 0x14000
	ds_read_b128 v[138:141], v150
	ds_read_b128 v[142:145], v150 offset:1024
	ds_read_b128 v[170:173], v150 offset:2048
	ds_read_b128 v[174:177], v150 offset:3072
	v_add_u32_e32 v150, s74, v148
	ds_read_b128 v[178:181], v150
	ds_read_b128 v[182:185], v150 offset:1024
	ds_read_b128 v[186:189], v150 offset:2048
	ds_read_b128 v[200:203], v150 offset:3072
	v_lshl_add_u64 v[150:151], s[22:23], 0, v[134:135]
	s_add_i32 m0, s21, 0xc000
	ds_read_b128 v[204:207], v149
	ds_read_b128 v[208:211], v149 offset:1024
	ds_read_b128 v[212:215], v149 offset:2048
	ds_read_b128 v[216:219], v149 offset:3072
	ds_read_b128 v[220:223], v149 offset:4096
	ds_read_b128 v[224:227], v149 offset:5120
	ds_read_b128 v[228:231], v149 offset:6144
	ds_read_b128 v[232:235], v149 offset:7168
	global_load_lds_dwordx4 v[150:151], off
	v_lshl_add_u64 v[150:151], s[22:23], 0, v[136:137]
	s_add_i32 m0, s21, 0xe000
	s_nop 0
	global_load_lds_dwordx4 v[150:151], off
	s_waitcnt vmcnt(8)
	s_waitcnt lgkmcnt(0)
	s_barrier
	s_setprio 1
	s_waitcnt lgkmcnt(0)
	v_mfma_f32_16x16x32_bf16 v[124:127], v[138:141], v[204:207], 0
	v_mfma_f32_16x16x32_bf16 v[120:123], v[170:173], v[204:207], 0
	v_mfma_f32_16x16x32_bf16 v[112:115], v[138:141], v[212:215], 0
	v_mfma_f32_16x16x32_bf16 v[104:107], v[170:173], v[212:215], 0
	v_mfma_f32_16x16x32_bf16 v[96:99], v[138:141], v[220:223], 0
	v_mfma_f32_16x16x32_bf16 v[88:91], v[170:173], v[220:223], 0
	v_mfma_f32_16x16x32_bf16 v[80:83], v[138:141], v[228:231], 0
	v_mfma_f32_16x16x32_bf16 v[72:75], v[170:173], v[228:231], 0
	v_mfma_f32_16x16x32_bf16 v[124:127], v[142:145], v[208:211], v[124:127]
	v_mfma_f32_16x16x32_bf16 v[120:123], v[174:177], v[208:211], v[120:123]
	v_mfma_f32_16x16x32_bf16 v[112:115], v[142:145], v[216:219], v[112:115]
	v_mfma_f32_16x16x32_bf16 v[104:107], v[174:177], v[216:219], v[104:107]
	v_mfma_f32_16x16x32_bf16 v[96:99], v[142:145], v[224:227], v[96:99]
	v_mfma_f32_16x16x32_bf16 v[88:91], v[174:177], v[224:227], v[88:91]
	v_mfma_f32_16x16x32_bf16 v[80:83], v[142:145], v[232:235], v[80:83]
	v_mfma_f32_16x16x32_bf16 v[72:75], v[174:177], v[232:235], v[72:75]
	s_setprio 0
	s_setprio 1
	v_mfma_f32_16x16x32_bf16 v[116:119], v[178:181], v[204:207], 0
	v_mfma_f32_16x16x32_bf16 v[108:111], v[186:189], v[204:207], 0
	v_mfma_f32_16x16x32_bf16 v[100:103], v[178:181], v[212:215], 0
	v_mfma_f32_16x16x32_bf16 v[92:95], v[186:189], v[212:215], 0
	v_mfma_f32_16x16x32_bf16 v[84:87], v[178:181], v[220:223], 0
	v_mfma_f32_16x16x32_bf16 v[76:79], v[186:189], v[220:223], 0
	v_mfma_f32_16x16x32_bf16 v[68:71], v[178:181], v[228:231], 0
	v_mfma_f32_16x16x32_bf16 v[64:67], v[186:189], v[228:231], 0
	v_mfma_f32_16x16x32_bf16 v[116:119], v[182:185], v[208:211], v[116:119]
	v_mfma_f32_16x16x32_bf16 v[108:111], v[200:203], v[208:211], v[108:111]
	v_mfma_f32_16x16x32_bf16 v[100:103], v[182:185], v[216:219], v[100:103]
	v_mfma_f32_16x16x32_bf16 v[92:95], v[200:203], v[216:219], v[92:95]
	v_mfma_f32_16x16x32_bf16 v[84:87], v[182:185], v[224:227], v[84:87]
	v_mfma_f32_16x16x32_bf16 v[76:79], v[200:203], v[224:227], v[76:79]
	v_mfma_f32_16x16x32_bf16 v[68:71], v[182:185], v[232:235], v[68:71]
	v_mfma_f32_16x16x32_bf16 v[64:67], v[200:203], v[232:235], v[64:67]
	s_setprio 0
	s_barrier
	s_add_i32 s71, s71, s40
	v_lshl_add_u64 v[150:151], s[24:25], 0, v[152:153]
	s_mov_b32 m0, s71
	ds_read_b128 v[204:207], v149 offset:16384
	ds_read_b128 v[208:211], v149 offset:17408
	ds_read_b128 v[212:215], v149 offset:18432
	ds_read_b128 v[216:219], v149 offset:19456
	ds_read_b128 v[220:223], v149 offset:20480
	ds_read_b128 v[224:227], v149 offset:21504
	ds_read_b128 v[228:231], v149 offset:22528
	ds_read_b128 v[232:235], v149 offset:23552
	global_load_lds_dwordx4 v[150:151], off
	s_add_i32 m0, s71, 0x2000
	s_add_u32 s72, s24, 0x80000
	v_lshl_add_u64 v[190:191], s[24:25], 0, v[128:129]
	s_addc_u32 s73, s25, 0
	s_add_i32 s71, s74, s40
	global_load_lds_dwordx4 v[190:191], off
	v_lshl_add_u64 v[236:237], s[72:73], 0, v[152:153]
	s_mov_b32 m0, s71
	v_lshl_add_u64 v[238:239], s[26:27], 0, v[130:131]
	global_load_lds_dwordx4 v[236:237], off
	v_lshl_add_u64 v[236:237], s[72:73], 0, v[128:129]
	s_add_i32 m0, s71, 0x2000
	s_nop 0
	global_load_lds_dwordx4 v[236:237], off
	v_lshl_add_u64 v[236:237], s[26:27], 0, v[132:133]
	s_mov_b32 m0, s21
	s_nop 0
	global_load_lds_dwordx4 v[236:237], off
	s_mov_b32 m0, s56
	s_nop 0
	global_load_lds_dwordx4 v[238:239], off
	s_waitcnt vmcnt(8)
	s_waitcnt lgkmcnt(0)
	s_barrier
; #define PG8_STAGE(bufoff, gbase, voff) do { _Pragma("unroll") for (int _i = 0; _i < 2; ++_i) \
;         __builtin_amdgcn_global_load_lds((const unsigned*)((const char*)(gbase) + (voff)[_i]), (LAS unsigned*)(lds + (bufoff) + ldsw + _i * 8192), 16, 0, 0); } while (0)
; #define PG8_LDA(dst, b, h) do { _Pragma("unroll") for (int m = 0; m < 4; ++m) _Pragma("unroll") for (int k = 0; k < 2; ++k) dst[m][k] = *(const LAS bf16x8*)(lds + PG8_SA(b, h) + aoff + m * 2048 + k * 1024); } while (0)
; #define PG8_LDB(dst, b, h) do { _Pragma("unroll") for (int n = 0; n < 2; ++n) _Pragma("unroll") for (int k = 0; k < 2; ++k) dst[n][k] = *(const LAS bf16x8*)(lds + PG8_SB(b, h) + boff + n * 2048 + k * 1024); } while (0)
; #define PG8_MMA(ai, bj, At, Bt) do { __builtin_amdgcn_s_setprio(1); _Pragma("unroll") for (int m = 0; m < 4; ++m) _Pragma("unroll") for (int n = 0; n < 2; ++n) _Pragma("unroll") for (int k = 0; k < 2; ++k) \
;         acc[ai][bj][m][n] = __builtin_amdgcn_mfma_f32_16x16x32_bf16(Bt[n][k], At[m][k], acc[ai][bj][m][n], 0, 0, 0); __builtin_amdgcn_s_setprio(0); } while (0)
; #define PG8_WAIT_V(n) asm volatile("s_waitcnt vmcnt(" #n ")" ::: "memory")
; #define PG8_WAIT_L(n) asm volatile("s_waitcnt lgkmcnt(" #n ")" ::: "memory")
; #define PG8_BAR __builtin_amdgcn_s_barrier()
; #define PG8_SCHED __builtin_amdgcn_sched_barrier(0)
; template <class Epi, class Sched>
; __device__ __forceinline__ void gemm_phase(const int tid, LAS unsigned char* lds, const Gemm g, const Sched& S, const Epi& E) {
;     ...
;             PG8_WAIT_V(8); PG8_WAIT_L(0); PG8_BAR; PG8_MMA(0, 0, At, B0); PG8_MMA(0, 1, At, B1); PG8_BAR; PG8_SCHED;
;             PG8_LDA(At, 0, 1); PG8_STAGE(PG8_SB(0, 0), b2, voffB); PG8_STAGE(PG8_SB(0, 1), b2 + hstep, voffB); PG8_STAGE(PG8_SA(0, 0), a2, voffA);
;             PG8_WAIT_V(8); PG8_WAIT_L(0); PG8_BAR; PG8_MMA(1, 0, At, B0); PG8_MMA(1, 1, At, B1); PG8_BAR; PG8_SCHED;
;             PG8_LDB(B0, 1, 0); PG8_LDB(B1, 1, 1); PG8_SCHED; PG8_LDA(At, 1, 0); PG8_STAGE(PG8_SA(0, 1), a2 + hstep, voffA);
;             PG8_WAIT_V(8); PG8_WAIT_L(0); PG8_BAR; PG8_MMA(0, 0, At, B0); PG8_MMA(0, 1, At, B1); PG8_BAR; PG8_SCHED;
	s_setprio 1
	s_waitcnt lgkmcnt(0)
	v_mfma_f32_16x16x32_bf16 v[60:63], v[138:141], v[204:207], 0
	v_mfma_f32_16x16x32_bf16 v[56:59], v[170:173], v[204:207], 0
	v_mfma_f32_16x16x32_bf16 v[48:51], v[138:141], v[212:215], 0
	v_mfma_f32_16x16x32_bf16 v[40:43], v[170:173], v[212:215], 0
	v_mfma_f32_16x16x32_bf16 v[32:35], v[138:141], v[220:223], 0
	v_mfma_f32_16x16x32_bf16 v[24:27], v[170:173], v[220:223], 0
	v_mfma_f32_16x16x32_bf16 v[16:19], v[138:141], v[228:231], 0
	v_mfma_f32_16x16x32_bf16 v[8:11], v[170:173], v[228:231], 0
	v_mfma_f32_16x16x32_bf16 v[60:63], v[142:145], v[208:211], v[60:63]
	v_mfma_f32_16x16x32_bf16 v[56:59], v[174:177], v[208:211], v[56:59]
	v_mfma_f32_16x16x32_bf16 v[48:51], v[142:145], v[216:219], v[48:51]
	v_mfma_f32_16x16x32_bf16 v[40:43], v[174:177], v[216:219], v[40:43]
	v_mfma_f32_16x16x32_bf16 v[32:35], v[142:145], v[224:227], v[32:35]
	v_mfma_f32_16x16x32_bf16 v[24:27], v[174:177], v[224:227], v[24:27]
	v_mfma_f32_16x16x32_bf16 v[16:19], v[142:145], v[232:235], v[16:19]
	v_mfma_f32_16x16x32_bf16 v[8:11], v[174:177], v[232:235], v[8:11]
	s_setprio 0
	s_setprio 1
	v_mfma_f32_16x16x32_bf16 v[52:55], v[178:181], v[204:207], 0
	v_mfma_f32_16x16x32_bf16 v[44:47], v[186:189], v[204:207], 0
	v_mfma_f32_16x16x32_bf16 v[36:39], v[178:181], v[212:215], 0
	v_mfma_f32_16x16x32_bf16 v[28:31], v[186:189], v[212:215], 0
	v_mfma_f32_16x16x32_bf16 v[20:23], v[178:181], v[220:223], 0
	v_mfma_f32_16x16x32_bf16 v[12:15], v[186:189], v[220:223], 0
	v_mfma_f32_16x16x32_bf16 v[4:7], v[178:181], v[228:231], 0
	v_mfma_f32_16x16x32_bf16 v[0:3], v[186:189], v[228:231], 0
	v_mfma_f32_16x16x32_bf16 v[52:55], v[182:185], v[208:211], v[52:55]
	v_mfma_f32_16x16x32_bf16 v[44:47], v[200:203], v[208:211], v[44:47]
	v_mfma_f32_16x16x32_bf16 v[36:39], v[182:185], v[216:219], v[36:39]
	v_mfma_f32_16x16x32_bf16 v[28:31], v[200:203], v[216:219], v[28:31]
	v_mfma_f32_16x16x32_bf16 v[20:23], v[182:185], v[224:227], v[20:23]
	v_mfma_f32_16x16x32_bf16 v[12:15], v[200:203], v[224:227], v[12:15]
	v_mfma_f32_16x16x32_bf16 v[4:7], v[182:185], v[232:235], v[4:7]
	v_mfma_f32_16x16x32_bf16 v[0:3], v[200:203], v[232:235], v[0:3]
	s_setprio 0
	s_barrier
	s_add_i32 s71, 0, 0x18000
	s_add_i32 s72, 0, 0x1c000
	v_add_u32_e32 v174, s71, v148
	v_add_u32_e32 v199, s72, v148
	ds_read_b128 v[138:141], v174
	ds_read_b128 v[142:145], v174 offset:1024
	ds_read_b128 v[170:173], v174 offset:2048
	ds_read_b128 v[174:177], v174 offset:3072
	ds_read_b128 v[178:181], v199
	ds_read_b128 v[182:185], v199 offset:1024
	ds_read_b128 v[186:189], v199 offset:2048
	ds_read_b128 v[200:203], v199 offset:3072
	s_add_u32 s26, s26, 0x80000
	s_addc_u32 s27, s27, 0
	s_mov_b32 m0, s57
	v_lshl_add_u64 v[240:241], s[26:27], 0, v[132:133]
	ds_read_b128 v[204:207], v149 offset:32768
	ds_read_b128 v[208:211], v149 offset:33792
	ds_read_b128 v[212:215], v149 offset:34816
	ds_read_b128 v[216:219], v149 offset:35840
	ds_read_b128 v[220:223], v149 offset:36864
	ds_read_b128 v[224:227], v149 offset:37888
	ds_read_b128 v[228:231], v149 offset:38912
	ds_read_b128 v[232:235], v149 offset:39936
	global_load_lds_dwordx4 v[240:241], off
	v_lshl_add_u64 v[240:241], s[26:27], 0, v[130:131]
	s_mov_b32 m0, s58
	s_nop 0
	global_load_lds_dwordx4 v[240:241], off
	s_waitcnt vmcnt(8)
	s_waitcnt lgkmcnt(0)
	s_barrier
	s_setprio 1
	s_waitcnt lgkmcnt(0)
	v_mfma_f32_16x16x32_bf16 v[124:127], v[138:141], v[204:207], v[124:127]
	v_mfma_f32_16x16x32_bf16 v[120:123], v[170:173], v[204:207], v[120:123]
	v_mfma_f32_16x16x32_bf16 v[112:115], v[138:141], v[212:215], v[112:115]
	v_mfma_f32_16x16x32_bf16 v[104:107], v[170:173], v[212:215], v[104:107]
	v_mfma_f32_16x16x32_bf16 v[96:99], v[138:141], v[220:223], v[96:99]
	v_mfma_f32_16x16x32_bf16 v[88:91], v[170:173], v[220:223], v[88:91]
	v_mfma_f32_16x16x32_bf16 v[80:83], v[138:141], v[228:231], v[80:83]
	v_mfma_f32_16x16x32_bf16 v[72:75], v[170:173], v[228:231], v[72:75]
	v_mfma_f32_16x16x32_bf16 v[124:127], v[142:145], v[208:211], v[124:127]
	v_mfma_f32_16x16x32_bf16 v[120:123], v[174:177], v[208:211], v[120:123]
	v_mfma_f32_16x16x32_bf16 v[112:115], v[142:145], v[216:219], v[112:115]
	v_mfma_f32_16x16x32_bf16 v[104:107], v[174:177], v[216:219], v[104:107]
	v_mfma_f32_16x16x32_bf16 v[96:99], v[142:145], v[224:227], v[96:99]
	v_mfma_f32_16x16x32_bf16 v[88:91], v[174:177], v[224:227], v[88:91]
	v_mfma_f32_16x16x32_bf16 v[80:83], v[142:145], v[232:235], v[80:83]
	v_mfma_f32_16x16x32_bf16 v[72:75], v[174:177], v[232:235], v[72:75]
	s_setprio 0
	s_setprio 1
	v_mfma_f32_16x16x32_bf16 v[116:119], v[178:181], v[204:207], v[116:119]
	v_mfma_f32_16x16x32_bf16 v[108:111], v[186:189], v[204:207], v[108:111]
	v_mfma_f32_16x16x32_bf16 v[100:103], v[178:181], v[212:215], v[100:103]
	v_mfma_f32_16x16x32_bf16 v[92:95], v[186:189], v[212:215], v[92:95]
	v_mfma_f32_16x16x32_bf16 v[84:87], v[178:181], v[220:223], v[84:87]
	v_mfma_f32_16x16x32_bf16 v[76:79], v[186:189], v[220:223], v[76:79]
	v_mfma_f32_16x16x32_bf16 v[68:71], v[178:181], v[228:231], v[68:71]
	v_mfma_f32_16x16x32_bf16 v[64:67], v[186:189], v[228:231], v[64:67]
	v_mfma_f32_16x16x32_bf16 v[116:119], v[182:185], v[208:211], v[116:119]
	v_mfma_f32_16x16x32_bf16 v[108:111], v[200:203], v[208:211], v[108:111]
	v_mfma_f32_16x16x32_bf16 v[100:103], v[182:185], v[216:219], v[100:103]
	v_mfma_f32_16x16x32_bf16 v[92:95], v[200:203], v[216:219], v[92:95]
	v_mfma_f32_16x16x32_bf16 v[84:87], v[182:185], v[224:227], v[84:87]
	v_mfma_f32_16x16x32_bf16 v[76:79], v[200:203], v[224:227], v[76:79]
	v_mfma_f32_16x16x32_bf16 v[68:71], v[182:185], v[232:235], v[68:71]
	v_mfma_f32_16x16x32_bf16 v[64:67], v[200:203], v[232:235], v[64:67]
	s_setprio 0
	s_barrier
; #define PG8_STAGE(bufoff, gbase, voff) do { _Pragma("unroll") for (int _i = 0; _i < 2; ++_i) \
;         __builtin_amdgcn_global_load_lds((const unsigned*)((const char*)(gbase) + (voff)[_i]), (LAS unsigned*)(lds + (bufoff) + ldsw + _i * 8192), 16, 0, 0); } while (0)
; #define PG8_LDA(dst, b, h) do { _Pragma("unroll") for (int m = 0; m < 4; ++m) _Pragma("unroll") for (int k = 0; k < 2; ++k) dst[m][k] = *(const LAS bf16x8*)(lds + PG8_SA(b, h) + aoff + m * 2048 + k * 1024); } while (0)
; #define PG8_WAIT_V(n) asm volatile("s_waitcnt vmcnt(" #n ")" ::: "memory")
; template <class Epi, class Sched>
; __device__ __forceinline__ void gemm_phase(const int tid, LAS unsigned char* lds, const Gemm g, const Sched& S, const Epi& E) {
;     ...
;         const bool has_next = S.next(ui + 1, nxt);
;         const char* nA = has_next ? (const char*)g.A + (size_t)nxt.pm * tstep : cA; const char* nB = has_next ? (const char*)g.Bt + (size_t)nxt.pn * tstep : cB;
;         for (int t = 0; t < nt; t += 2) {
;             const bool last = (t == nt - 2);
;             const char* a1 = cA + (size_t)(t + 1) * kstep;
;             const char* a2 = last ? nA : cA + (size_t)(t + 2) * kstep; const char* b2 = last ? nB : cB + (size_t)(t + 2) * kstep;
;             const char* a3 = a2 + kstep; const char* b3 = b2 + kstep;
;             if (last && has_next) S.a_ready(nxt);
;             PG8_LDB(B0, 0, 0); PG8_LDB(B1, 0, 1); PG8_SCHED; PG8_LDA(At, 0, 0); PG8_STAGE(PG8_SA(1, 1), a1 + hstep, voffA);
;             PG8_WAIT_V(8); PG8_WAIT_L(0); PG8_BAR; PG8_MMA(0, 0, At, B0); PG8_MMA(0, 1, At, B1); PG8_BAR; PG8_SCHED;
;             PG8_LDA(At, 0, 1); PG8_STAGE(PG8_SB(0, 0), b2, voffB); PG8_STAGE(PG8_SB(0, 1), b2 + hstep, voffB); PG8_STAGE(PG8_SA(0, 0), a2, voffA);
;             PG8_WAIT_V(8); PG8_WAIT_L(0); PG8_BAR; PG8_MMA(1, 0, At, B0); PG8_MMA(1, 1, At, B1); PG8_BAR; PG8_SCHED;
;             PG8_LDB(B0, 1, 0); PG8_LDB(B1, 1, 1); PG8_SCHED; PG8_LDA(At, 1, 0); PG8_STAGE(PG8_SA(0, 1), a2 + hstep, voffA);
;             PG8_WAIT_V(8); PG8_WAIT_L(0); PG8_BAR; PG8_MMA(0, 0, At, B0); PG8_MMA(0, 1, At, B1); PG8_BAR; PG8_SCHED;
;             PG8_LDA(At, 1, 1); PG8_STAGE(PG8_SB(1, 0), b3, voffB); PG8_STAGE(PG8_SB(1, 1), b3 + hstep, voffB); PG8_STAGE(PG8_SA(1, 0), a3, voffA);
;             PG8_WAIT_V(8); PG8_WAIT_L(0); PG8_BAR; PG8_MMA(1, 0, At, B0); PG8_MMA(1, 1, At, B1); PG8_BAR; PG8_SCHED;
	s_add_i32 s26, s71, s40
	v_lshl_add_u64 v[150:151], v[150:151], 0, s[34:35]
	s_mov_b32 m0, s26
	ds_read_b128 v[204:207], v149 offset:49152
	ds_read_b128 v[208:211], v149 offset:50176
	ds_read_b128 v[212:215], v149 offset:51200
	ds_read_b128 v[216:219], v149 offset:52224
	ds_read_b128 v[220:223], v149 offset:53248
	ds_read_b128 v[224:227], v149 offset:54272
	ds_read_b128 v[228:231], v149 offset:55296
	ds_read_b128 v[232:235], v149 offset:56320
	global_load_lds_dwordx4 v[150:151], off
	s_add_i32 m0, s26, 0x2000
	s_add_u32 s24, s24, 0x80080
	v_lshl_add_u64 v[150:151], v[190:191], 0, s[34:35]
	s_addc_u32 s25, s25, 0
	s_add_i32 s26, s72, s40
	global_load_lds_dwordx4 v[150:151], off
	v_lshl_add_u64 v[150:151], s[24:25], 0, v[152:153]
	s_mov_b32 m0, s26
	s_nop 0
	global_load_lds_dwordx4 v[150:151], off
	v_lshl_add_u64 v[150:151], s[24:25], 0, v[128:129]
	s_add_i32 m0, s26, 0x2000
	s_nop 0
	global_load_lds_dwordx4 v[150:151], off
	v_lshl_add_u64 v[150:151], v[236:237], 0, s[34:35]
	s_mov_b32 m0, s61
	s_nop 0
	global_load_lds_dwordx4 v[150:151], off
	v_lshl_add_u64 v[150:151], v[238:239], 0, s[34:35]
	s_mov_b32 m0, s62
	s_nop 0
	global_load_lds_dwordx4 v[150:151], off
	s_waitcnt vmcnt(8)
	s_waitcnt lgkmcnt(0)
	s_barrier
	s_setprio 1
	s_waitcnt lgkmcnt(0)
	v_mfma_f32_16x16x32_bf16 v[60:63], v[138:141], v[204:207], v[60:63]
	v_mfma_f32_16x16x32_bf16 v[56:59], v[170:173], v[204:207], v[56:59]
	v_mfma_f32_16x16x32_bf16 v[48:51], v[138:141], v[212:215], v[48:51]
	v_mfma_f32_16x16x32_bf16 v[40:43], v[170:173], v[212:215], v[40:43]
	v_mfma_f32_16x16x32_bf16 v[32:35], v[138:141], v[220:223], v[32:35]
	v_mfma_f32_16x16x32_bf16 v[24:27], v[170:173], v[220:223], v[24:27]
	v_mfma_f32_16x16x32_bf16 v[16:19], v[138:141], v[228:231], v[16:19]
	v_mfma_f32_16x16x32_bf16 v[8:11], v[170:173], v[228:231], v[8:11]
	v_mfma_f32_16x16x32_bf16 v[60:63], v[142:145], v[208:211], v[60:63]
	v_mfma_f32_16x16x32_bf16 v[56:59], v[174:177], v[208:211], v[56:59]
	v_mfma_f32_16x16x32_bf16 v[48:51], v[142:145], v[216:219], v[48:51]
	v_mfma_f32_16x16x32_bf16 v[40:43], v[174:177], v[216:219], v[40:43]
	v_mfma_f32_16x16x32_bf16 v[32:35], v[142:145], v[224:227], v[32:35]
	v_mfma_f32_16x16x32_bf16 v[24:27], v[174:177], v[224:227], v[24:27]
	v_mfma_f32_16x16x32_bf16 v[16:19], v[142:145], v[232:235], v[16:19]
	v_mfma_f32_16x16x32_bf16 v[8:11], v[174:177], v[232:235], v[8:11]
	s_setprio 0
	s_setprio 1
	v_mfma_f32_16x16x32_bf16 v[52:55], v[178:181], v[204:207], v[52:55]
	v_mfma_f32_16x16x32_bf16 v[44:47], v[186:189], v[204:207], v[44:47]
	v_mfma_f32_16x16x32_bf16 v[36:39], v[178:181], v[212:215], v[36:39]
	v_mfma_f32_16x16x32_bf16 v[28:31], v[186:189], v[212:215], v[28:31]
	s_add_i32 s70, s70, 2
	s_add_u32 s22, s22, 0x100
	s_addc_u32 s23, s23, 0
	s_add_u32 s68, s68, 0x100
	s_addc_u32 s69, s69, 0
	v_mfma_f32_16x16x32_bf16 v[20:23], v[178:181], v[220:223], v[20:23]
	v_mfma_f32_16x16x32_bf16 v[12:15], v[186:189], v[220:223], v[12:15]
	v_mfma_f32_16x16x32_bf16 v[4:7], v[178:181], v[228:231], v[4:7]
	v_mfma_f32_16x16x32_bf16 v[0:3], v[186:189], v[228:231], v[0:3]
	v_mfma_f32_16x16x32_bf16 v[52:55], v[182:185], v[208:211], v[52:55]
	v_mfma_f32_16x16x32_bf16 v[44:47], v[200:203], v[208:211], v[44:47]
	v_mfma_f32_16x16x32_bf16 v[36:39], v[182:185], v[216:219], v[36:39]
	v_mfma_f32_16x16x32_bf16 v[28:31], v[200:203], v[216:219], v[28:31]
	v_mfma_f32_16x16x32_bf16 v[20:23], v[182:185], v[224:227], v[20:23]
	v_mfma_f32_16x16x32_bf16 v[12:15], v[200:203], v[224:227], v[12:15]
	v_mfma_f32_16x16x32_bf16 v[4:7], v[182:185], v[232:235], v[4:7]
	v_mfma_f32_16x16x32_bf16 v[0:3], v[200:203], v[232:235], v[0:3]
	s_setprio 0
	s_barrier
	s_cmp_gt_u32 s70, 29
.LBB0_50:
	s_add_u32 s24, s22, 0xfff80080
	s_addc_u32 s25, s23, -1
	s_add_i32 s71, 0, 0x10000
	s_cmp_eq_u32 s70, 28
	s_cselect_b32 s27, s15, s25
	s_cselect_b32 s26, s66, s24
	v_add_u32_e32 v150, s71, v148
	s_cselect_b32 s25, s13, s69
	s_cselect_b32 s24, s67, s68
	s_add_i32 s74, 0, 0x14000
	ds_read_b128 v[138:141], v150
	ds_read_b128 v[142:145], v150 offset:1024
	ds_read_b128 v[170:173], v150 offset:2048
	ds_read_b128 v[174:177], v150 offset:3072
	v_add_u32_e32 v150, s74, v148
	ds_read_b128 v[178:181], v150
	ds_read_b128 v[182:185], v150 offset:1024
	ds_read_b128 v[186:189], v150 offset:2048
	ds_read_b128 v[200:203], v150 offset:3072
	v_lshl_add_u64 v[150:151], s[22:23], 0, v[134:135]
	s_add_i32 m0, s21, 0xc000
	ds_read_b128 v[204:207], v149
	ds_read_b128 v[208:211], v149 offset:1024
	ds_read_b128 v[212:215], v149 offset:2048
	ds_read_b128 v[216:219], v149 offset:3072
	ds_read_b128 v[220:223], v149 offset:4096
	ds_read_b128 v[224:227], v149 offset:5120
	ds_read_b128 v[228:231], v149 offset:6144
	ds_read_b128 v[232:235], v149 offset:7168
	global_load_lds_dwordx4 v[150:151], off
	v_lshl_add_u64 v[150:151], s[22:23], 0, v[136:137]
	s_add_i32 m0, s21, 0xe000
	s_nop 0
	global_load_lds_dwordx4 v[150:151], off
	s_waitcnt vmcnt(8)
	s_waitcnt lgkmcnt(0)
	s_barrier
; #define PG8_STAGE(bufoff, gbase, voff) do { _Pragma("unroll") for (int _i = 0; _i < 2; ++_i) \
;         __builtin_amdgcn_global_load_lds((const unsigned*)((const char*)(gbase) + (voff)[_i]), (LAS unsigned*)(lds + (bufoff) + ldsw + _i * 8192), 16, 0, 0); } while (0)
; #define PG8_LDA(dst, b, h) do { _Pragma("unroll") for (int m = 0; m < 4; ++m) _Pragma("unroll") for (int k = 0; k < 2; ++k) dst[m][k] = *(const LAS bf16x8*)(lds + PG8_SA(b, h) + aoff + m * 2048 + k * 1024); } while (0)
; #define PG8_LDB(dst, b, h) do { _Pragma("unroll") for (int n = 0; n < 2; ++n) _Pragma("unroll") for (int k = 0; k < 2; ++k) dst[n][k] = *(const LAS bf16x8*)(lds + PG8_SB(b, h) + boff + n * 2048 + k * 1024); } while (0)
; #define PG8_MMA(ai, bj, At, Bt) do { __builtin_amdgcn_s_setprio(1); _Pragma("unroll") for (int m = 0; m < 4; ++m) _Pragma("unroll") for (int n = 0; n < 2; ++n) _Pragma("unroll") for (int k = 0; k < 2; ++k) \
;         acc[ai][bj][m][n] = __builtin_amdgcn_mfma_f32_16x16x32_bf16(Bt[n][k], At[m][k], acc[ai][bj][m][n], 0, 0, 0); __builtin_amdgcn_s_setprio(0); } while (0)
; #define PG8_WAIT_V(n) asm volatile("s_waitcnt vmcnt(" #n ")" ::: "memory")
; #define PG8_WAIT_L(n) asm volatile("s_waitcnt lgkmcnt(" #n ")" ::: "memory")
; #define PG8_BAR __builtin_amdgcn_s_barrier()
; #define PG8_SCHED __builtin_amdgcn_sched_barrier(0)
; template <class Epi, class Sched>
; __device__ __forceinline__ void gemm_phase(const int tid, LAS unsigned char* lds, const Gemm g, const Sched& S, const Epi& E) {
;     ...
;             PG8_WAIT_V(8); PG8_WAIT_L(0); PG8_BAR; PG8_MMA(0, 0, At, B0); PG8_MMA(0, 1, At, B1); PG8_BAR; PG8_SCHED;
;             PG8_LDA(At, 0, 1); PG8_STAGE(PG8_SB(0, 0), b2, voffB); PG8_STAGE(PG8_SB(0, 1), b2 + hstep, voffB); PG8_STAGE(PG8_SA(0, 0), a2, voffA);
;             PG8_WAIT_V(8); PG8_WAIT_L(0); PG8_BAR; PG8_MMA(1, 0, At, B0); PG8_MMA(1, 1, At, B1); PG8_BAR; PG8_SCHED;
;             PG8_LDB(B0, 1, 0); PG8_LDB(B1, 1, 1); PG8_SCHED; PG8_LDA(At, 1, 0); PG8_STAGE(PG8_SA(0, 1), a2 + hstep, voffA);
;             PG8_WAIT_V(8); PG8_WAIT_L(0); PG8_BAR; PG8_MMA(0, 0, At, B0); PG8_MMA(0, 1, At, B1); PG8_BAR; PG8_SCHED;
	s_setprio 1
	s_waitcnt lgkmcnt(0)
	v_mfma_f32_16x16x32_bf16 v[124:127], v[138:141], v[204:207], v[124:127]
	v_mfma_f32_16x16x32_bf16 v[120:123], v[170:173], v[204:207], v[120:123]
	v_mfma_f32_16x16x32_bf16 v[112:115], v[138:141], v[212:215], v[112:115]
	v_mfma_f32_16x16x32_bf16 v[104:107], v[170:173], v[212:215], v[104:107]
	v_mfma_f32_16x16x32_bf16 v[96:99], v[138:141], v[220:223], v[96:99]
	v_mfma_f32_16x16x32_bf16 v[88:91], v[170:173], v[220:223], v[88:91]
	v_mfma_f32_16x16x32_bf16 v[80:83], v[138:141], v[228:231], v[80:83]
	v_mfma_f32_16x16x32_bf16 v[72:75], v[170:173], v[228:231], v[72:75]
	v_mfma_f32_16x16x32_bf16 v[124:127], v[142:145], v[208:211], v[124:127]
	v_mfma_f32_16x16x32_bf16 v[120:123], v[174:177], v[208:211], v[120:123]
	v_mfma_f32_16x16x32_bf16 v[112:115], v[142:145], v[216:219], v[112:115]
	v_mfma_f32_16x16x32_bf16 v[104:107], v[174:177], v[216:219], v[104:107]
	v_mfma_f32_16x16x32_bf16 v[96:99], v[142:145], v[224:227], v[96:99]
	v_mfma_f32_16x16x32_bf16 v[88:91], v[174:177], v[224:227], v[88:91]
	v_mfma_f32_16x16x32_bf16 v[80:83], v[142:145], v[232:235], v[80:83]
	v_mfma_f32_16x16x32_bf16 v[72:75], v[174:177], v[232:235], v[72:75]
	s_setprio 0
	s_setprio 1
	v_mfma_f32_16x16x32_bf16 v[116:119], v[178:181], v[204:207], v[116:119]
	v_mfma_f32_16x16x32_bf16 v[108:111], v[186:189], v[204:207], v[108:111]
	v_mfma_f32_16x16x32_bf16 v[100:103], v[178:181], v[212:215], v[100:103]
	v_mfma_f32_16x16x32_bf16 v[92:95], v[186:189], v[212:215], v[92:95]
	v_mfma_f32_16x16x32_bf16 v[84:87], v[178:181], v[220:223], v[84:87]
	v_mfma_f32_16x16x32_bf16 v[76:79], v[186:189], v[220:223], v[76:79]
	v_mfma_f32_16x16x32_bf16 v[68:71], v[178:181], v[228:231], v[68:71]
	v_mfma_f32_16x16x32_bf16 v[64:67], v[186:189], v[228:231], v[64:67]
	v_mfma_f32_16x16x32_bf16 v[116:119], v[182:185], v[208:211], v[116:119]
	v_mfma_f32_16x16x32_bf16 v[108:111], v[200:203], v[208:211], v[108:111]
	v_mfma_f32_16x16x32_bf16 v[100:103], v[182:185], v[216:219], v[100:103]
	v_mfma_f32_16x16x32_bf16 v[92:95], v[200:203], v[216:219], v[92:95]
	v_mfma_f32_16x16x32_bf16 v[84:87], v[182:185], v[224:227], v[84:87]
	v_mfma_f32_16x16x32_bf16 v[76:79], v[200:203], v[224:227], v[76:79]
	v_mfma_f32_16x16x32_bf16 v[68:71], v[182:185], v[232:235], v[68:71]
	v_mfma_f32_16x16x32_bf16 v[64:67], v[200:203], v[232:235], v[64:67]
	s_setprio 0
	s_barrier
	s_add_i32 s71, s71, s40
	v_lshl_add_u64 v[150:151], s[24:25], 0, v[152:153]
	s_mov_b32 m0, s71
	ds_read_b128 v[204:207], v149 offset:16384
	ds_read_b128 v[208:211], v149 offset:17408
	ds_read_b128 v[212:215], v149 offset:18432
	ds_read_b128 v[216:219], v149 offset:19456
	ds_read_b128 v[220:223], v149 offset:20480
	ds_read_b128 v[224:227], v149 offset:21504
	ds_read_b128 v[228:231], v149 offset:22528
	ds_read_b128 v[232:235], v149 offset:23552
	global_load_lds_dwordx4 v[150:151], off
	s_add_i32 m0, s71, 0x2000
	s_add_u32 s72, s24, 0x80000
	v_lshl_add_u64 v[190:191], s[24:25], 0, v[128:129]
	s_addc_u32 s73, s25, 0
	s_add_i32 s71, s74, s40
	global_load_lds_dwordx4 v[190:191], off
	v_lshl_add_u64 v[236:237], s[72:73], 0, v[152:153]
	s_mov_b32 m0, s71
	v_lshl_add_u64 v[238:239], s[26:27], 0, v[130:131]
	global_load_lds_dwordx4 v[236:237], off
	v_lshl_add_u64 v[236:237], s[72:73], 0, v[128:129]
	s_add_i32 m0, s71, 0x2000
	s_nop 0
	global_load_lds_dwordx4 v[236:237], off
	v_lshl_add_u64 v[236:237], s[26:27], 0, v[132:133]
	s_mov_b32 m0, s21
	s_nop 0
	global_load_lds_dwordx4 v[236:237], off
	s_mov_b32 m0, s56
	s_nop 0
	global_load_lds_dwordx4 v[238:239], off
	s_waitcnt vmcnt(8)
	s_waitcnt lgkmcnt(0)
	s_barrier
	s_setprio 1
	s_waitcnt lgkmcnt(0)
	v_mfma_f32_16x16x32_bf16 v[60:63], v[138:141], v[204:207], v[60:63]
	v_mfma_f32_16x16x32_bf16 v[56:59], v[170:173], v[204:207], v[56:59]
	v_mfma_f32_16x16x32_bf16 v[48:51], v[138:141], v[212:215], v[48:51]
	v_mfma_f32_16x16x32_bf16 v[40:43], v[170:173], v[212:215], v[40:43]
	v_mfma_f32_16x16x32_bf16 v[32:35], v[138:141], v[220:223], v[32:35]
	v_mfma_f32_16x16x32_bf16 v[24:27], v[170:173], v[220:223], v[24:27]
	v_mfma_f32_16x16x32_bf16 v[16:19], v[138:141], v[228:231], v[16:19]
	v_mfma_f32_16x16x32_bf16 v[8:11], v[170:173], v[228:231], v[8:11]
	v_mfma_f32_16x16x32_bf16 v[60:63], v[142:145], v[208:211], v[60:63]
	v_mfma_f32_16x16x32_bf16 v[56:59], v[174:177], v[208:211], v[56:59]
	v_mfma_f32_16x16x32_bf16 v[48:51], v[142:145], v[216:219], v[48:51]
	v_mfma_f32_16x16x32_bf16 v[40:43], v[174:177], v[216:219], v[40:43]
	v_mfma_f32_16x16x32_bf16 v[32:35], v[142:145], v[224:227], v[32:35]
	v_mfma_f32_16x16x32_bf16 v[24:27], v[174:177], v[224:227], v[24:27]
	v_mfma_f32_16x16x32_bf16 v[16:19], v[142:145], v[232:235], v[16:19]
	v_mfma_f32_16x16x32_bf16 v[8:11], v[174:177], v[232:235], v[8:11]
	s_setprio 0
	s_setprio 1
	v_mfma_f32_16x16x32_bf16 v[52:55], v[178:181], v[204:207], v[52:55]
	v_mfma_f32_16x16x32_bf16 v[44:47], v[186:189], v[204:207], v[44:47]
	v_mfma_f32_16x16x32_bf16 v[36:39], v[178:181], v[212:215], v[36:39]
	v_mfma_f32_16x16x32_bf16 v[28:31], v[186:189], v[212:215], v[28:31]
	v_mfma_f32_16x16x32_bf16 v[20:23], v[178:181], v[220:223], v[20:23]
	v_mfma_f32_16x16x32_bf16 v[12:15], v[186:189], v[220:223], v[12:15]
	v_mfma_f32_16x16x32_bf16 v[4:7], v[178:181], v[228:231], v[4:7]
	v_mfma_f32_16x16x32_bf16 v[0:3], v[186:189], v[228:231], v[0:3]
	v_mfma_f32_16x16x32_bf16 v[52:55], v[182:185], v[208:211], v[52:55]
	v_mfma_f32_16x16x32_bf16 v[44:47], v[200:203], v[208:211], v[44:47]
	v_mfma_f32_16x16x32_bf16 v[36:39], v[182:185], v[216:219], v[36:39]
	v_mfma_f32_16x16x32_bf16 v[28:31], v[200:203], v[216:219], v[28:31]
	v_mfma_f32_16x16x32_bf16 v[20:23], v[182:185], v[224:227], v[20:23]
	v_mfma_f32_16x16x32_bf16 v[12:15], v[200:203], v[224:227], v[12:15]
	v_mfma_f32_16x16x32_bf16 v[4:7], v[182:185], v[232:235], v[4:7]
	v_mfma_f32_16x16x32_bf16 v[0:3], v[200:203], v[232:235], v[0:3]
	s_setprio 0
	s_barrier
; #define PG8_STAGE(bufoff, gbase, voff) do { _Pragma("unroll") for (int _i = 0; _i < 2; ++_i) \
;         __builtin_amdgcn_global_load_lds((const unsigned*)((const char*)(gbase) + (voff)[_i]), (LAS unsigned*)(lds + (bufoff) + ldsw + _i * 8192), 16, 0, 0); } while (0)
; #define PG8_LDA(dst, b, h) do { _Pragma("unroll") for (int m = 0; m < 4; ++m) _Pragma("unroll") for (int k = 0; k < 2; ++k) dst[m][k] = *(const LAS bf16x8*)(lds + PG8_SA(b, h) + aoff + m * 2048 + k * 1024); } while (0)
; #define PG8_LDB(dst, b, h) do { _Pragma("unroll") for (int n = 0; n < 2; ++n) _Pragma("unroll") for (int k = 0; k < 2; ++k) dst[n][k] = *(const LAS bf16x8*)(lds + PG8_SB(b, h) + boff + n * 2048 + k * 1024); } while (0)
; #define PG8_MMA(ai, bj, At, Bt) do { __builtin_amdgcn_s_setprio(1); _Pragma("unroll") for (int m = 0; m < 4; ++m) _Pragma("unroll") for (int n = 0; n < 2; ++n) _Pragma("unroll") for (int k = 0; k < 2; ++k) \
;         acc[ai][bj][m][n] = __builtin_amdgcn_mfma_f32_16x16x32_bf16(Bt[n][k], At[m][k], acc[ai][bj][m][n], 0, 0, 0); __builtin_amdgcn_s_setprio(0); } while (0)
; #define PG8_WAIT_V(n) asm volatile("s_waitcnt vmcnt(" #n ")" ::: "memory")
; #define PG8_WAIT_L(n) asm volatile("s_waitcnt lgkmcnt(" #n ")" ::: "memory")
; #define PG8_BAR __builtin_amdgcn_s_barrier()
; #define PG8_SCHED __builtin_amdgcn_sched_barrier(0)
; template <class Epi, class Sched>
; __device__ __forceinline__ void gemm_phase(const int tid, LAS unsigned char* lds, const Gemm g, const Sched& S, const Epi& E) {
;     ...
;             PG8_LDB(B0, 1, 0); PG8_LDB(B1, 1, 1); PG8_SCHED; PG8_LDA(At, 1, 0); PG8_STAGE(PG8_SA(0, 1), a2 + hstep, voffA);
;             PG8_WAIT_V(8); PG8_WAIT_L(0); PG8_BAR; PG8_MMA(0, 0, At, B0); PG8_MMA(0, 1, At, B1); PG8_BAR; PG8_SCHED;
	s_add_i32 s71, 0, 0x18000
	s_add_i32 s72, 0, 0x1c000
	v_add_u32_e32 v174, s71, v148
	v_add_u32_e32 v199, s72, v148
	ds_read_b128 v[138:141], v174
	ds_read_b128 v[142:145], v174 offset:1024
	ds_read_b128 v[170:173], v174 offset:2048
	ds_read_b128 v[174:177], v174 offset:3072
	ds_read_b128 v[178:181], v199
	ds_read_b128 v[182:185], v199 offset:1024
	ds_read_b128 v[186:189], v199 offset:2048
	ds_read_b128 v[200:203], v199 offset:3072
	s_add_u32 s26, s26, 0x80000
	s_addc_u32 s27, s27, 0
	s_mov_b32 m0, s57
	v_lshl_add_u64 v[240:241], s[26:27], 0, v[132:133]
	ds_read_b128 v[204:207], v149 offset:32768
	ds_read_b128 v[208:211], v149 offset:33792
	ds_read_b128 v[212:215], v149 offset:34816
	ds_read_b128 v[216:219], v149 offset:35840
	ds_read_b128 v[220:223], v149 offset:36864
	ds_read_b128 v[224:227], v149 offset:37888
	ds_read_b128 v[228:231], v149 offset:38912
	ds_read_b128 v[232:235], v149 offset:39936
	global_load_lds_dwordx4 v[240:241], off
	v_lshl_add_u64 v[240:241], s[26:27], 0, v[130:131]
	s_mov_b32 m0, s58
	s_nop 0
	global_load_lds_dwordx4 v[240:241], off
	s_waitcnt vmcnt(8)
	s_waitcnt lgkmcnt(0)
	s_barrier
	s_setprio 1
	s_waitcnt lgkmcnt(0)
	v_mfma_f32_16x16x32_bf16 v[124:127], v[138:141], v[204:207], v[124:127]
	v_mfma_f32_16x16x32_bf16 v[120:123], v[170:173], v[204:207], v[120:123]
	v_mfma_f32_16x16x32_bf16 v[112:115], v[138:141], v[212:215], v[112:115]
	v_mfma_f32_16x16x32_bf16 v[104:107], v[170:173], v[212:215], v[104:107]
	v_mfma_f32_16x16x32_bf16 v[96:99], v[138:141], v[220:223], v[96:99]
	v_mfma_f32_16x16x32_bf16 v[88:91], v[170:173], v[220:223], v[88:91]
	v_mfma_f32_16x16x32_bf16 v[80:83], v[138:141], v[228:231], v[80:83]
	v_mfma_f32_16x16x32_bf16 v[72:75], v[170:173], v[228:231], v[72:75]
	v_mfma_f32_16x16x32_bf16 v[124:127], v[142:145], v[208:211], v[124:127]
	v_mfma_f32_16x16x32_bf16 v[120:123], v[174:177], v[208:211], v[120:123]
	v_mfma_f32_16x16x32_bf16 v[112:115], v[142:145], v[216:219], v[112:115]
	v_mfma_f32_16x16x32_bf16 v[104:107], v[174:177], v[216:219], v[104:107]
	v_mfma_f32_16x16x32_bf16 v[96:99], v[142:145], v[224:227], v[96:99]
	v_mfma_f32_16x16x32_bf16 v[88:91], v[174:177], v[224:227], v[88:91]
	v_mfma_f32_16x16x32_bf16 v[80:83], v[142:145], v[232:235], v[80:83]
	v_mfma_f32_16x16x32_bf16 v[72:75], v[174:177], v[232:235], v[72:75]
	s_setprio 0
	s_setprio 1
	v_mfma_f32_16x16x32_bf16 v[116:119], v[178:181], v[204:207], v[116:119]
	v_mfma_f32_16x16x32_bf16 v[108:111], v[186:189], v[204:207], v[108:111]
	v_mfma_f32_16x16x32_bf16 v[100:103], v[178:181], v[212:215], v[100:103]
	v_mfma_f32_16x16x32_bf16 v[92:95], v[186:189], v[212:215], v[92:95]
	v_mfma_f32_16x16x32_bf16 v[84:87], v[178:181], v[220:223], v[84:87]
	v_mfma_f32_16x16x32_bf16 v[76:79], v[186:189], v[220:223], v[76:79]
	v_mfma_f32_16x16x32_bf16 v[68:71], v[178:181], v[228:231], v[68:71]
	v_mfma_f32_16x16x32_bf16 v[64:67], v[186:189], v[228:231], v[64:67]
	v_mfma_f32_16x16x32_bf16 v[116:119], v[182:185], v[208:211], v[116:119]
	v_mfma_f32_16x16x32_bf16 v[108:111], v[200:203], v[208:211], v[108:111]
	v_mfma_f32_16x16x32_bf16 v[100:103], v[182:185], v[216:219], v[100:103]
	v_mfma_f32_16x16x32_bf16 v[92:95], v[200:203], v[216:219], v[92:95]
	v_mfma_f32_16x16x32_bf16 v[84:87], v[182:185], v[224:227], v[84:87]
	v_mfma_f32_16x16x32_bf16 v[76:79], v[200:203], v[224:227], v[76:79]
	v_mfma_f32_16x16x32_bf16 v[68:71], v[182:185], v[232:235], v[68:71]
	v_mfma_f32_16x16x32_bf16 v[64:67], v[200:203], v[232:235], v[64:67]
	s_setprio 0
	s_barrier
; #define PG8_STAGE(bufoff, gbase, voff) do { _Pragma("unroll") for (int _i = 0; _i < 2; ++_i) \
;         __builtin_amdgcn_global_load_lds((const unsigned*)((const char*)(gbase) + (voff)[_i]), (LAS unsigned*)(lds + (bufoff) + ldsw + _i * 8192), 16, 0, 0); } while (0)
; #define PG8_LDA(dst, b, h) do { _Pragma("unroll") for (int m = 0; m < 4; ++m) _Pragma("unroll") for (int k = 0; k < 2; ++k) dst[m][k] = *(const LAS bf16x8*)(lds + PG8_SA(b, h) + aoff + m * 2048 + k * 1024); } while (0)
; #define PG8_MMA(ai, bj, At, Bt) do { __builtin_amdgcn_s_setprio(1); _Pragma("unroll") for (int m = 0; m < 4; ++m) _Pragma("unroll") for (int n = 0; n < 2; ++n) _Pragma("unroll") for (int k = 0; k < 2; ++k) \
;         acc[ai][bj][m][n] = __builtin_amdgcn_mfma_f32_16x16x32_bf16(Bt[n][k], At[m][k], acc[ai][bj][m][n], 0, 0, 0); __builtin_amdgcn_s_setprio(0); } while (0)
; #define PG8_WAIT_V(n) asm volatile("s_waitcnt vmcnt(" #n ")" ::: "memory")
; #define PG8_WAIT_L(n) asm volatile("s_waitcnt lgkmcnt(" #n ")" ::: "memory")
; #define PG8_BAR __builtin_amdgcn_s_barrier()
; #define PG8_SCHED __builtin_amdgcn_sched_barrier(0)
; template <class Epi, class Sched>
; __device__ __forceinline__ void gemm_phase(const int tid, LAS unsigned char* lds, const Gemm g, const Sched& S, const Epi& E) {
;     ...
;             PG8_LDA(At, 1, 1); PG8_STAGE(PG8_SB(1, 0), b3, voffB); PG8_STAGE(PG8_SB(1, 1), b3 + hstep, voffB); PG8_STAGE(PG8_SA(1, 0), a3, voffA);
;             PG8_WAIT_V(8); PG8_WAIT_L(0); PG8_BAR; PG8_MMA(1, 0, At, B0); PG8_MMA(1, 1, At, B1); PG8_BAR; PG8_SCHED;
;         }
;         if (wr == 0) PG8_BAR;
	s_add_i32 s26, s71, s40
	v_lshl_add_u64 v[150:151], v[150:151], 0, s[34:35]
	s_mov_b32 m0, s26
	ds_read_b128 v[204:207], v149 offset:49152
	ds_read_b128 v[208:211], v149 offset:50176
	ds_read_b128 v[212:215], v149 offset:51200
	ds_read_b128 v[216:219], v149 offset:52224
	ds_read_b128 v[220:223], v149 offset:53248
	ds_read_b128 v[224:227], v149 offset:54272
	ds_read_b128 v[228:231], v149 offset:55296
	ds_read_b128 v[232:235], v149 offset:56320
	global_load_lds_dwordx4 v[150:151], off
	s_add_i32 m0, s26, 0x2000
	s_add_u32 s24, s24, 0x80080
	v_lshl_add_u64 v[150:151], v[190:191], 0, s[34:35]
	s_addc_u32 s25, s25, 0
	s_add_i32 s26, s72, s40
	global_load_lds_dwordx4 v[150:151], off
	v_lshl_add_u64 v[150:151], s[24:25], 0, v[152:153]
	s_mov_b32 m0, s26
	s_nop 0
	global_load_lds_dwordx4 v[150:151], off
	v_lshl_add_u64 v[150:151], s[24:25], 0, v[128:129]
	s_add_i32 m0, s26, 0x2000
	s_nop 0
	global_load_lds_dwordx4 v[150:151], off
	v_lshl_add_u64 v[150:151], v[236:237], 0, s[34:35]
	s_mov_b32 m0, s61
	s_nop 0
	global_load_lds_dwordx4 v[150:151], off
	v_lshl_add_u64 v[150:151], v[238:239], 0, s[34:35]
	s_mov_b32 m0, s62
	s_nop 0
	global_load_lds_dwordx4 v[150:151], off
	s_waitcnt vmcnt(8)
	s_waitcnt lgkmcnt(0)
	s_barrier
	s_setprio 1
	s_waitcnt lgkmcnt(0)
	v_mfma_f32_16x16x32_bf16 v[60:63], v[138:141], v[204:207], v[60:63]
	v_mfma_f32_16x16x32_bf16 v[56:59], v[170:173], v[204:207], v[56:59]
	v_mfma_f32_16x16x32_bf16 v[48:51], v[138:141], v[212:215], v[48:51]
	v_mfma_f32_16x16x32_bf16 v[40:43], v[170:173], v[212:215], v[40:43]
	v_mfma_f32_16x16x32_bf16 v[32:35], v[138:141], v[220:223], v[32:35]
	v_mfma_f32_16x16x32_bf16 v[24:27], v[170:173], v[220:223], v[24:27]
	v_mfma_f32_16x16x32_bf16 v[16:19], v[138:141], v[228:231], v[16:19]
	v_mfma_f32_16x16x32_bf16 v[8:11], v[170:173], v[228:231], v[8:11]
	v_mfma_f32_16x16x32_bf16 v[60:63], v[142:145], v[208:211], v[60:63]
	v_mfma_f32_16x16x32_bf16 v[56:59], v[174:177], v[208:211], v[56:59]
	v_mfma_f32_16x16x32_bf16 v[48:51], v[142:145], v[216:219], v[48:51]
	v_mfma_f32_16x16x32_bf16 v[40:43], v[174:177], v[216:219], v[40:43]
	v_mfma_f32_16x16x32_bf16 v[32:35], v[142:145], v[224:227], v[32:35]
	v_mfma_f32_16x16x32_bf16 v[24:27], v[174:177], v[224:227], v[24:27]
	v_mfma_f32_16x16x32_bf16 v[16:19], v[142:145], v[232:235], v[16:19]
	v_mfma_f32_16x16x32_bf16 v[8:11], v[174:177], v[232:235], v[8:11]
	s_setprio 0
	s_setprio 1
	v_mfma_f32_16x16x32_bf16 v[52:55], v[178:181], v[204:207], v[52:55]
	v_mfma_f32_16x16x32_bf16 v[44:47], v[186:189], v[204:207], v[44:47]
	v_mfma_f32_16x16x32_bf16 v[36:39], v[178:181], v[212:215], v[36:39]
	v_mfma_f32_16x16x32_bf16 v[28:31], v[186:189], v[212:215], v[28:31]
	s_add_i32 s70, s70, 2
	s_add_u32 s22, s22, 0x100
	s_addc_u32 s23, s23, 0
	s_add_u32 s68, s68, 0x100
	s_addc_u32 s69, s69, 0
	v_mfma_f32_16x16x32_bf16 v[20:23], v[178:181], v[220:223], v[20:23]
	v_mfma_f32_16x16x32_bf16 v[12:15], v[186:189], v[220:223], v[12:15]
	v_mfma_f32_16x16x32_bf16 v[4:7], v[178:181], v[228:231], v[4:7]
	v_mfma_f32_16x16x32_bf16 v[0:3], v[186:189], v[228:231], v[0:3]
	v_mfma_f32_16x16x32_bf16 v[52:55], v[182:185], v[208:211], v[52:55]
	v_mfma_f32_16x16x32_bf16 v[44:47], v[200:203], v[208:211], v[44:47]
	v_mfma_f32_16x16x32_bf16 v[36:39], v[182:185], v[216:219], v[36:39]
	v_mfma_f32_16x16x32_bf16 v[28:31], v[200:203], v[216:219], v[28:31]
	v_mfma_f32_16x16x32_bf16 v[20:23], v[182:185], v[224:227], v[20:23]
	v_mfma_f32_16x16x32_bf16 v[12:15], v[200:203], v[224:227], v[12:15]
	v_mfma_f32_16x16x32_bf16 v[4:7], v[182:185], v[232:235], v[4:7]
	v_mfma_f32_16x16x32_bf16 v[0:3], v[200:203], v[232:235], v[0:3]
	s_setprio 0
	s_barrier
	s_cmp_gt_u32 s70, 29
	s_cbranch_scc0 .LBB0_50
	s_and_b64 vcc, exec, s[10:11]
	s_cbranch_vccz .LBB0_53
	s_barrier

; #define PG8_STAGE(bufoff, gbase, voff) do { _Pragma("unroll") for (int _i = 0; _i < 2; ++_i) \
;         __builtin_amdgcn_global_load_lds((const unsigned*)((const char*)(gbase) + (voff)[_i]), (LAS unsigned*)(lds + (bufoff) + ldsw + _i * 8192), 16, 0, 0); } while (0)
; #define PG8_LDA(dst, b, h) do { _Pragma("unroll") for (int m = 0; m < 4; ++m) _Pragma("unroll") for (int k = 0; k < 2; ++k) dst[m][k] = *(const LAS bf16x8*)(lds + PG8_SA(b, h) + aoff + m * 2048 + k * 1024); } while (0)
; #define PG8_LDB(dst, b, h) do { _Pragma("unroll") for (int n = 0; n < 2; ++n) _Pragma("unroll") for (int k = 0; k < 2; ++k) dst[n][k] = *(const LAS bf16x8*)(lds + PG8_SB(b, h) + boff + n * 2048 + k * 1024); } while (0)
; #define PG8_MMA(ai, bj, At, Bt) do { __builtin_amdgcn_s_setprio(1); _Pragma("unroll") for (int m = 0; m < 4; ++m) _Pragma("unroll") for (int n = 0; n < 2; ++n) _Pragma("unroll") for (int k = 0; k < 2; ++k) \
;         acc[ai][bj][m][n] = __builtin_amdgcn_mfma_f32_16x16x32_bf16(Bt[n][k], At[m][k], acc[ai][bj][m][n], 0, 0, 0); __builtin_amdgcn_s_setprio(0); } while (0)
; template <class Epi, class Sched>
; __device__ __forceinline__ void gemm_phase(const int tid, LAS unsigned char* lds, const Gemm g, const Sched& S, const Epi& E) {
;     ...
;         const bool has_next = S.next(ui + 1, nxt);
;         const char* nA = has_next ? (const char*)g.A + (size_t)nxt.pm * tstep : cA; const char* nB = has_next ? (const char*)g.Bt + (size_t)nxt.pn * tstep : cB;
;         for (int t = 0; t < nt; t += 2) {
;             const bool last = (t == nt - 2);
;             const char* a1 = cA + (size_t)(t + 1) * kstep;
;             const char* a2 = last ? nA : cA + (size_t)(t + 2) * kstep; const char* b2 = last ? nB : cB + (size_t)(t + 2) * kstep;
;             const char* a3 = a2 + kstep; const char* b3 = b2 + kstep;
;             if (last && has_next) S.a_ready(nxt);
;             PG8_LDB(B0, 0, 0); PG8_LDB(B1, 0, 1); PG8_SCHED; PG8_LDA(At, 0, 0); PG8_STAGE(PG8_SA(1, 1), a1 + hstep, voffA);
;             PG8_WAIT_V(8); PG8_WAIT_L(0); PG8_BAR; PG8_MMA(0, 0, At, B0); PG8_MMA(0, 1, At, B1); PG8_BAR; PG8_SCHED;
;             PG8_LDA(At, 0, 1); PG8_STAGE(PG8_SB(0, 0), b2, voffB); PG8_STAGE(PG8_SB(0, 1), b2 + hstep, voffB); PG8_STAGE(PG8_SA(0, 0), a2, voffA);
;             PG8_WAIT_V(8); PG8_WAIT_L(0); PG8_BAR; PG8_MMA(1, 0, At, B0); PG8_MMA(1, 1, At, B1); PG8_BAR; PG8_SCHED;
.LBB0_394:
	s_ashr_i32 s15, s14, 31
	s_lshl_b64 s[16:17], s[14:15], 18
	s_add_u32 s16, s40, s16
	s_addc_u32 s17, s41, s17
	s_and_b64 s[18:19], s[0:1], exec
	s_cselect_b32 s15, s17, s23
	s_cselect_b32 s66, s16, s22
	s_ashr_i32 s13, s12, 31
	s_lshl_b64 s[18:19], s[12:13], 18
	s_add_u32 s18, s38, s18
	s_addc_u32 s19, s39, s19
	s_and_b64 s[26:27], s[0:1], exec
	s_cselect_b32 s13, s19, s25
	s_cselect_b32 s67, s18, s24
	s_add_u32 s22, s22, 0x20080
	s_addc_u32 s23, s23, 0
	s_add_u32 s68, s24, 0x100
	v_mov_b32_e32 v0, 0
	s_addc_u32 s69, s25, 0
	s_mov_b32 s70, -2
	s_add_u32 s24, s22, 0xfffe0080
	s_addc_u32 s25, s23, -1
	s_add_i32 s71, 0, 0x10000
	s_cmp_eq_u32 s70, 4
	s_cselect_b32 s27, s15, s25
	s_cselect_b32 s26, s66, s24
	v_add_u32_e32 v150, s71, v144
	s_cselect_b32 s25, s13, s69
	s_cselect_b32 s24, s67, s68
	s_add_i32 s74, 0, 0x14000
	ds_read_b128 v[138:141], v150
	ds_read_b128 v[146:149], v150 offset:1024
	ds_read_b128 v[170:173], v150 offset:2048
	ds_read_b128 v[174:177], v150 offset:3072
	v_add_u32_e32 v150, s74, v144
	ds_read_b128 v[178:181], v150
	ds_read_b128 v[182:185], v150 offset:1024
	ds_read_b128 v[186:189], v150 offset:2048
	ds_read_b128 v[200:203], v150 offset:3072
	v_lshl_add_u64 v[150:151], s[22:23], 0, v[134:135]
	s_add_i32 m0, s21, 0xc000
	ds_read_b128 v[204:207], v145
	ds_read_b128 v[208:211], v145 offset:1024
	ds_read_b128 v[212:215], v145 offset:2048
	ds_read_b128 v[216:219], v145 offset:3072
	ds_read_b128 v[220:223], v145 offset:4096
	ds_read_b128 v[224:227], v145 offset:5120
	ds_read_b128 v[228:231], v145 offset:6144
	ds_read_b128 v[232:235], v145 offset:7168
	global_load_lds_dwordx4 v[150:151], off
	v_lshl_add_u64 v[150:151], s[22:23], 0, v[136:137]
	s_add_i32 m0, s21, 0xe000
	s_nop 0
	global_load_lds_dwordx4 v[150:151], off
	s_waitcnt vmcnt(8)
	s_waitcnt lgkmcnt(0)
	s_barrier
	s_setprio 1
	s_waitcnt lgkmcnt(0)
	v_mfma_f32_16x16x32_bf16 v[124:127], v[138:141], v[204:207], 0
	v_mfma_f32_16x16x32_bf16 v[120:123], v[170:173], v[204:207], 0
	v_mfma_f32_16x16x32_bf16 v[108:111], v[138:141], v[212:215], 0
	v_mfma_f32_16x16x32_bf16 v[104:107], v[170:173], v[212:215], 0
	v_mfma_f32_16x16x32_bf16 v[92:95], v[138:141], v[220:223], 0
	v_mfma_f32_16x16x32_bf16 v[88:91], v[170:173], v[220:223], 0
	v_mfma_f32_16x16x32_bf16 v[76:79], v[138:141], v[228:231], 0
	v_mfma_f32_16x16x32_bf16 v[72:75], v[170:173], v[228:231], 0
	v_mfma_f32_16x16x32_bf16 v[124:127], v[146:149], v[208:211], v[124:127]
	v_mfma_f32_16x16x32_bf16 v[120:123], v[174:177], v[208:211], v[120:123]
	v_mfma_f32_16x16x32_bf16 v[108:111], v[146:149], v[216:219], v[108:111]
	v_mfma_f32_16x16x32_bf16 v[104:107], v[174:177], v[216:219], v[104:107]
	v_mfma_f32_16x16x32_bf16 v[92:95], v[146:149], v[224:227], v[92:95]
	v_mfma_f32_16x16x32_bf16 v[88:91], v[174:177], v[224:227], v[88:91]
	v_mfma_f32_16x16x32_bf16 v[76:79], v[146:149], v[232:235], v[76:79]
	v_mfma_f32_16x16x32_bf16 v[72:75], v[174:177], v[232:235], v[72:75]
	s_setprio 0
	s_setprio 1
	v_mfma_f32_16x16x32_bf16 v[116:119], v[178:181], v[204:207], 0
	v_mfma_f32_16x16x32_bf16 v[112:115], v[186:189], v[204:207], 0
	v_mfma_f32_16x16x32_bf16 v[100:103], v[178:181], v[212:215], 0
	v_mfma_f32_16x16x32_bf16 v[96:99], v[186:189], v[212:215], 0
	v_mfma_f32_16x16x32_bf16 v[84:87], v[178:181], v[220:223], 0
	v_mfma_f32_16x16x32_bf16 v[80:83], v[186:189], v[220:223], 0
	v_mfma_f32_16x16x32_bf16 v[68:71], v[178:181], v[228:231], 0
	v_mfma_f32_16x16x32_bf16 v[64:67], v[186:189], v[228:231], 0
	v_mfma_f32_16x16x32_bf16 v[116:119], v[182:185], v[208:211], v[116:119]
	v_mfma_f32_16x16x32_bf16 v[112:115], v[200:203], v[208:211], v[112:115]
	v_mfma_f32_16x16x32_bf16 v[100:103], v[182:185], v[216:219], v[100:103]
	v_mfma_f32_16x16x32_bf16 v[96:99], v[200:203], v[216:219], v[96:99]
	v_mfma_f32_16x16x32_bf16 v[84:87], v[182:185], v[224:227], v[84:87]
	v_mfma_f32_16x16x32_bf16 v[80:83], v[200:203], v[224:227], v[80:83]
	v_mfma_f32_16x16x32_bf16 v[68:71], v[182:185], v[232:235], v[68:71]
	v_mfma_f32_16x16x32_bf16 v[64:67], v[200:203], v[232:235], v[64:67]
	s_setprio 0
	s_barrier
	s_add_i32 s71, s71, s55
	v_lshl_add_u64 v[150:151], s[24:25], 0, v[152:153]
	s_mov_b32 m0, s71
	ds_read_b128 v[204:207], v145 offset:16384
	ds_read_b128 v[208:211], v145 offset:17408
	ds_read_b128 v[212:215], v145 offset:18432
	ds_read_b128 v[216:219], v145 offset:19456
	ds_read_b128 v[220:223], v145 offset:20480
	ds_read_b128 v[224:227], v145 offset:21504
	ds_read_b128 v[228:231], v145 offset:22528
	ds_read_b128 v[232:235], v145 offset:23552
	global_load_lds_dwordx4 v[150:151], off
	s_add_i32 m0, s71, 0x2000
	s_add_u32 s72, s24, 0x20000
	v_lshl_add_u64 v[190:191], s[24:25], 0, v[132:133]
	s_addc_u32 s73, s25, 0
	s_add_i32 s71, s74, s55
	global_load_lds_dwordx4 v[190:191], off
	v_lshl_add_u64 v[236:237], s[72:73], 0, v[152:153]
	s_mov_b32 m0, s71
	v_lshl_add_u64 v[238:239], s[26:27], 0, v[130:131]
	global_load_lds_dwordx4 v[236:237], off
	v_lshl_add_u64 v[236:237], s[72:73], 0, v[132:133]
	s_add_i32 m0, s71, 0x2000
	s_nop 0
	global_load_lds_dwordx4 v[236:237], off
	v_lshl_add_u64 v[236:237], s[26:27], 0, v[128:129]
	s_mov_b32 m0, s21
	s_nop 0
	global_load_lds_dwordx4 v[236:237], off
	s_mov_b32 m0, s56
	s_nop 0
	global_load_lds_dwordx4 v[238:239], off
	s_waitcnt vmcnt(8)
	s_waitcnt lgkmcnt(0)
	s_barrier
; #define PG8_STAGE(bufoff, gbase, voff) do { _Pragma("unroll") for (int _i = 0; _i < 2; ++_i) \
;         __builtin_amdgcn_global_load_lds((const unsigned*)((const char*)(gbase) + (voff)[_i]), (LAS unsigned*)(lds + (bufoff) + ldsw + _i * 8192), 16, 0, 0); } while (0)
; #define PG8_LDA(dst, b, h) do { _Pragma("unroll") for (int m = 0; m < 4; ++m) _Pragma("unroll") for (int k = 0; k < 2; ++k) dst[m][k] = *(const LAS bf16x8*)(lds + PG8_SA(b, h) + aoff + m * 2048 + k * 1024); } while (0)
; #define PG8_LDB(dst, b, h) do { _Pragma("unroll") for (int n = 0; n < 2; ++n) _Pragma("unroll") for (int k = 0; k < 2; ++k) dst[n][k] = *(const LAS bf16x8*)(lds + PG8_SB(b, h) + boff + n * 2048 + k * 1024); } while (0)
; #define PG8_MMA(ai, bj, At, Bt) do { __builtin_amdgcn_s_setprio(1); _Pragma("unroll") for (int m = 0; m < 4; ++m) _Pragma("unroll") for (int n = 0; n < 2; ++n) _Pragma("unroll") for (int k = 0; k < 2; ++k) \
;         acc[ai][bj][m][n] = __builtin_amdgcn_mfma_f32_16x16x32_bf16(Bt[n][k], At[m][k], acc[ai][bj][m][n], 0, 0, 0); __builtin_amdgcn_s_setprio(0); } while (0)
; #define PG8_WAIT_V(n) asm volatile("s_waitcnt vmcnt(" #n ")" ::: "memory")
; #define PG8_WAIT_L(n) asm volatile("s_waitcnt lgkmcnt(" #n ")" ::: "memory")
; #define PG8_BAR __builtin_amdgcn_s_barrier()
; #define PG8_SCHED __builtin_amdgcn_sched_barrier(0)
; template <class Epi, class Sched>
; __device__ __forceinline__ void gemm_phase(const int tid, LAS unsigned char* lds, const Gemm g, const Sched& S, const Epi& E) {
;     ...
;             PG8_WAIT_V(8); PG8_WAIT_L(0); PG8_BAR; PG8_MMA(1, 0, At, B0); PG8_MMA(1, 1, At, B1); PG8_BAR; PG8_SCHED;
;             PG8_LDB(B0, 1, 0); PG8_LDB(B1, 1, 1); PG8_SCHED; PG8_LDA(At, 1, 0); PG8_STAGE(PG8_SA(0, 1), a2 + hstep, voffA);
;             PG8_WAIT_V(8); PG8_WAIT_L(0); PG8_BAR; PG8_MMA(0, 0, At, B0); PG8_MMA(0, 1, At, B1); PG8_BAR; PG8_SCHED;
;             PG8_LDA(At, 1, 1); PG8_STAGE(PG8_SB(1, 0), b3, voffB); PG8_STAGE(PG8_SB(1, 1), b3 + hstep, voffB); PG8_STAGE(PG8_SA(1, 0), a3, voffA);
;             PG8_WAIT_V(8); PG8_WAIT_L(0); PG8_BAR; PG8_MMA(1, 0, At, B0); PG8_MMA(1, 1, At, B1); PG8_BAR; PG8_SCHED;
	s_setprio 1
	s_waitcnt lgkmcnt(0)
	v_mfma_f32_16x16x32_bf16 v[60:63], v[138:141], v[204:207], 0
	v_mfma_f32_16x16x32_bf16 v[56:59], v[170:173], v[204:207], 0
	v_mfma_f32_16x16x32_bf16 v[44:47], v[138:141], v[212:215], 0
	v_mfma_f32_16x16x32_bf16 v[40:43], v[170:173], v[212:215], 0
	v_mfma_f32_16x16x32_bf16 v[28:31], v[138:141], v[220:223], 0
	v_mfma_f32_16x16x32_bf16 v[24:27], v[170:173], v[220:223], 0
	v_mfma_f32_16x16x32_bf16 v[12:15], v[138:141], v[228:231], 0
	v_mfma_f32_16x16x32_bf16 v[8:11], v[170:173], v[228:231], 0
	v_mfma_f32_16x16x32_bf16 v[60:63], v[146:149], v[208:211], v[60:63]
	v_mfma_f32_16x16x32_bf16 v[56:59], v[174:177], v[208:211], v[56:59]
	v_mfma_f32_16x16x32_bf16 v[44:47], v[146:149], v[216:219], v[44:47]
	v_mfma_f32_16x16x32_bf16 v[40:43], v[174:177], v[216:219], v[40:43]
	v_mfma_f32_16x16x32_bf16 v[28:31], v[146:149], v[224:227], v[28:31]
	v_mfma_f32_16x16x32_bf16 v[24:27], v[174:177], v[224:227], v[24:27]
	v_mfma_f32_16x16x32_bf16 v[12:15], v[146:149], v[232:235], v[12:15]
	v_mfma_f32_16x16x32_bf16 v[8:11], v[174:177], v[232:235], v[8:11]
	s_setprio 0
	s_setprio 1
	v_mfma_f32_16x16x32_bf16 v[52:55], v[178:181], v[204:207], 0
	v_mfma_f32_16x16x32_bf16 v[48:51], v[186:189], v[204:207], 0
	v_mfma_f32_16x16x32_bf16 v[36:39], v[178:181], v[212:215], 0
	v_mfma_f32_16x16x32_bf16 v[32:35], v[186:189], v[212:215], 0
	v_mfma_f32_16x16x32_bf16 v[20:23], v[178:181], v[220:223], 0
	v_mfma_f32_16x16x32_bf16 v[16:19], v[186:189], v[220:223], 0
	v_mfma_f32_16x16x32_bf16 v[4:7], v[178:181], v[228:231], 0
	v_mfma_f32_16x16x32_bf16 v[0:3], v[186:189], v[228:231], 0
	v_mfma_f32_16x16x32_bf16 v[52:55], v[182:185], v[208:211], v[52:55]
	v_mfma_f32_16x16x32_bf16 v[48:51], v[200:203], v[208:211], v[48:51]
	v_mfma_f32_16x16x32_bf16 v[36:39], v[182:185], v[216:219], v[36:39]
	v_mfma_f32_16x16x32_bf16 v[32:35], v[200:203], v[216:219], v[32:35]
	v_mfma_f32_16x16x32_bf16 v[20:23], v[182:185], v[224:227], v[20:23]
	v_mfma_f32_16x16x32_bf16 v[16:19], v[200:203], v[224:227], v[16:19]
	v_mfma_f32_16x16x32_bf16 v[4:7], v[182:185], v[232:235], v[4:7]
	v_mfma_f32_16x16x32_bf16 v[0:3], v[200:203], v[232:235], v[0:3]
	s_setprio 0
	s_barrier
	s_add_i32 s71, 0, 0x18000
	s_add_i32 s72, 0, 0x1c000
	v_add_u32_e32 v174, s71, v144
	v_add_u32_e32 v199, s72, v144
	ds_read_b128 v[138:141], v174
	ds_read_b128 v[146:149], v174 offset:1024
	ds_read_b128 v[170:173], v174 offset:2048
	ds_read_b128 v[174:177], v174 offset:3072
	ds_read_b128 v[178:181], v199
	ds_read_b128 v[182:185], v199 offset:1024
	ds_read_b128 v[186:189], v199 offset:2048
	ds_read_b128 v[200:203], v199 offset:3072
	s_add_u32 s26, s26, 0x20000
	s_addc_u32 s27, s27, 0
	s_mov_b32 m0, s57
	v_lshl_add_u64 v[240:241], s[26:27], 0, v[128:129]
	ds_read_b128 v[204:207], v145 offset:32768
	ds_read_b128 v[208:211], v145 offset:33792
	ds_read_b128 v[212:215], v145 offset:34816
	ds_read_b128 v[216:219], v145 offset:35840
	ds_read_b128 v[220:223], v145 offset:36864
	ds_read_b128 v[224:227], v145 offset:37888
	ds_read_b128 v[228:231], v145 offset:38912
	ds_read_b128 v[232:235], v145 offset:39936
	global_load_lds_dwordx4 v[240:241], off
	v_lshl_add_u64 v[240:241], s[26:27], 0, v[130:131]
	s_mov_b32 m0, s58
	s_nop 0
	global_load_lds_dwordx4 v[240:241], off
	s_waitcnt vmcnt(8)
	s_waitcnt lgkmcnt(0)
	s_barrier
	s_setprio 1
	s_waitcnt lgkmcnt(0)
	v_mfma_f32_16x16x32_bf16 v[124:127], v[138:141], v[204:207], v[124:127]
	v_mfma_f32_16x16x32_bf16 v[120:123], v[170:173], v[204:207], v[120:123]
	v_mfma_f32_16x16x32_bf16 v[108:111], v[138:141], v[212:215], v[108:111]
	v_mfma_f32_16x16x32_bf16 v[104:107], v[170:173], v[212:215], v[104:107]
	v_mfma_f32_16x16x32_bf16 v[92:95], v[138:141], v[220:223], v[92:95]
	v_mfma_f32_16x16x32_bf16 v[88:91], v[170:173], v[220:223], v[88:91]
	v_mfma_f32_16x16x32_bf16 v[76:79], v[138:141], v[228:231], v[76:79]
	v_mfma_f32_16x16x32_bf16 v[72:75], v[170:173], v[228:231], v[72:75]
	v_mfma_f32_16x16x32_bf16 v[124:127], v[146:149], v[208:211], v[124:127]
	v_mfma_f32_16x16x32_bf16 v[120:123], v[174:177], v[208:211], v[120:123]
	v_mfma_f32_16x16x32_bf16 v[108:111], v[146:149], v[216:219], v[108:111]
	v_mfma_f32_16x16x32_bf16 v[104:107], v[174:177], v[216:219], v[104:107]
	v_mfma_f32_16x16x32_bf16 v[92:95], v[146:149], v[224:227], v[92:95]
	v_mfma_f32_16x16x32_bf16 v[88:91], v[174:177], v[224:227], v[88:91]
	v_mfma_f32_16x16x32_bf16 v[76:79], v[146:149], v[232:235], v[76:79]
	v_mfma_f32_16x16x32_bf16 v[72:75], v[174:177], v[232:235], v[72:75]
	s_setprio 0
	s_setprio 1
	v_mfma_f32_16x16x32_bf16 v[116:119], v[178:181], v[204:207], v[116:119]
	v_mfma_f32_16x16x32_bf16 v[112:115], v[186:189], v[204:207], v[112:115]
	v_mfma_f32_16x16x32_bf16 v[100:103], v[178:181], v[212:215], v[100:103]
	v_mfma_f32_16x16x32_bf16 v[96:99], v[186:189], v[212:215], v[96:99]
	v_mfma_f32_16x16x32_bf16 v[84:87], v[178:181], v[220:223], v[84:87]
	v_mfma_f32_16x16x32_bf16 v[80:83], v[186:189], v[220:223], v[80:83]
	v_mfma_f32_16x16x32_bf16 v[68:71], v[178:181], v[228:231], v[68:71]
	v_mfma_f32_16x16x32_bf16 v[64:67], v[186:189], v[228:231], v[64:67]
	v_mfma_f32_16x16x32_bf16 v[116:119], v[182:185], v[208:211], v[116:119]
	v_mfma_f32_16x16x32_bf16 v[112:115], v[200:203], v[208:211], v[112:115]
	v_mfma_f32_16x16x32_bf16 v[100:103], v[182:185], v[216:219], v[100:103]
	v_mfma_f32_16x16x32_bf16 v[96:99], v[200:203], v[216:219], v[96:99]
	v_mfma_f32_16x16x32_bf16 v[84:87], v[182:185], v[224:227], v[84:87]
	v_mfma_f32_16x16x32_bf16 v[80:83], v[200:203], v[224:227], v[80:83]
	v_mfma_f32_16x16x32_bf16 v[68:71], v[182:185], v[232:235], v[68:71]
	v_mfma_f32_16x16x32_bf16 v[64:67], v[200:203], v[232:235], v[64:67]
	s_setprio 0
	s_barrier
; #define PG8_STAGE(bufoff, gbase, voff) do { _Pragma("unroll") for (int _i = 0; _i < 2; ++_i) \
;         __builtin_amdgcn_global_load_lds((const unsigned*)((const char*)(gbase) + (voff)[_i]), (LAS unsigned*)(lds + (bufoff) + ldsw + _i * 8192), 16, 0, 0); } while (0)
; #define PG8_LDA(dst, b, h) do { _Pragma("unroll") for (int m = 0; m < 4; ++m) _Pragma("unroll") for (int k = 0; k < 2; ++k) dst[m][k] = *(const LAS bf16x8*)(lds + PG8_SA(b, h) + aoff + m * 2048 + k * 1024); } while (0)
; #define PG8_LDB(dst, b, h) do { _Pragma("unroll") for (int n = 0; n < 2; ++n) _Pragma("unroll") for (int k = 0; k < 2; ++k) dst[n][k] = *(const LAS bf16x8*)(lds + PG8_SB(b, h) + boff + n * 2048 + k * 1024); } while (0)
; #define PG8_MMA(ai, bj, At, Bt) do { __builtin_amdgcn_s_setprio(1); _Pragma("unroll") for (int m = 0; m < 4; ++m) _Pragma("unroll") for (int n = 0; n < 2; ++n) _Pragma("unroll") for (int k = 0; k < 2; ++k) \
;         acc[ai][bj][m][n] = __builtin_amdgcn_mfma_f32_16x16x32_bf16(Bt[n][k], At[m][k], acc[ai][bj][m][n], 0, 0, 0); __builtin_amdgcn_s_setprio(0); } while (0)
; #define PG8_WAIT_V(n) asm volatile("s_waitcnt vmcnt(" #n ")" ::: "memory")
; #define PG8_WAIT_L(n) asm volatile("s_waitcnt lgkmcnt(" #n ")" ::: "memory")
; #define PG8_BAR __builtin_amdgcn_s_barrier()
; #define PG8_SCHED __builtin_amdgcn_sched_barrier(0)
; template <class Epi, class Sched>
; __device__ __forceinline__ void gemm_phase(const int tid, LAS unsigned char* lds, const Gemm g, const Sched& S, const Epi& E) {
;     ...
;         for (int t = 0; t < nt; t += 2) {
;             const bool last = (t == nt - 2);
;             const char* a1 = cA + (size_t)(t + 1) * kstep;
;             const char* a2 = last ? nA : cA + (size_t)(t + 2) * kstep; const char* b2 = last ? nB : cB + (size_t)(t + 2) * kstep;
;             const char* a3 = a2 + kstep; const char* b3 = b2 + kstep;
;             if (last && has_next) S.a_ready(nxt);
;             PG8_LDB(B0, 0, 0); PG8_LDB(B1, 0, 1); PG8_SCHED; PG8_LDA(At, 0, 0); PG8_STAGE(PG8_SA(1, 1), a1 + hstep, voffA);
;             PG8_WAIT_V(8); PG8_WAIT_L(0); PG8_BAR; PG8_MMA(0, 0, At, B0); PG8_MMA(0, 1, At, B1); PG8_BAR; PG8_SCHED;
;     ...
;             PG8_WAIT_V(8); PG8_WAIT_L(0); PG8_BAR; PG8_MMA(1, 0, At, B0); PG8_MMA(1, 1, At, B1); PG8_BAR; PG8_SCHED;
	s_add_i32 s26, s71, s55
	v_lshl_add_u64 v[150:151], v[150:151], 0, s[34:35]
	s_mov_b32 m0, s26
	ds_read_b128 v[204:207], v145 offset:49152
	ds_read_b128 v[208:211], v145 offset:50176
	ds_read_b128 v[212:215], v145 offset:51200
	ds_read_b128 v[216:219], v145 offset:52224
	ds_read_b128 v[220:223], v145 offset:53248
	ds_read_b128 v[224:227], v145 offset:54272
	ds_read_b128 v[228:231], v145 offset:55296
	ds_read_b128 v[232:235], v145 offset:56320
	global_load_lds_dwordx4 v[150:151], off
	s_add_i32 m0, s26, 0x2000
	s_add_u32 s24, s24, 0x20080
	v_lshl_add_u64 v[150:151], v[190:191], 0, s[34:35]
	s_addc_u32 s25, s25, 0
	s_add_i32 s26, s72, s55
	global_load_lds_dwordx4 v[150:151], off
	v_lshl_add_u64 v[150:151], s[24:25], 0, v[152:153]
	s_mov_b32 m0, s26
	s_nop 0
	global_load_lds_dwordx4 v[150:151], off
	v_lshl_add_u64 v[150:151], s[24:25], 0, v[132:133]
	s_add_i32 m0, s26, 0x2000
	s_nop 0
	global_load_lds_dwordx4 v[150:151], off
	v_lshl_add_u64 v[150:151], v[236:237], 0, s[34:35]
	s_mov_b32 m0, s61
	s_nop 0
	global_load_lds_dwordx4 v[150:151], off
	v_lshl_add_u64 v[150:151], v[238:239], 0, s[34:35]
	s_mov_b32 m0, s62
	s_nop 0
	global_load_lds_dwordx4 v[150:151], off
	s_waitcnt vmcnt(8)
	s_waitcnt lgkmcnt(0)
	s_barrier
	s_setprio 1
	s_waitcnt lgkmcnt(0)
	v_mfma_f32_16x16x32_bf16 v[60:63], v[138:141], v[204:207], v[60:63]
	v_mfma_f32_16x16x32_bf16 v[56:59], v[170:173], v[204:207], v[56:59]
	v_mfma_f32_16x16x32_bf16 v[44:47], v[138:141], v[212:215], v[44:47]
	v_mfma_f32_16x16x32_bf16 v[40:43], v[170:173], v[212:215], v[40:43]
	v_mfma_f32_16x16x32_bf16 v[28:31], v[138:141], v[220:223], v[28:31]
	v_mfma_f32_16x16x32_bf16 v[24:27], v[170:173], v[220:223], v[24:27]
	v_mfma_f32_16x16x32_bf16 v[12:15], v[138:141], v[228:231], v[12:15]
	v_mfma_f32_16x16x32_bf16 v[8:11], v[170:173], v[228:231], v[8:11]
	v_mfma_f32_16x16x32_bf16 v[60:63], v[146:149], v[208:211], v[60:63]
	v_mfma_f32_16x16x32_bf16 v[56:59], v[174:177], v[208:211], v[56:59]
	v_mfma_f32_16x16x32_bf16 v[44:47], v[146:149], v[216:219], v[44:47]
	v_mfma_f32_16x16x32_bf16 v[40:43], v[174:177], v[216:219], v[40:43]
	v_mfma_f32_16x16x32_bf16 v[28:31], v[146:149], v[224:227], v[28:31]
	v_mfma_f32_16x16x32_bf16 v[24:27], v[174:177], v[224:227], v[24:27]
	v_mfma_f32_16x16x32_bf16 v[12:15], v[146:149], v[232:235], v[12:15]
	v_mfma_f32_16x16x32_bf16 v[8:11], v[174:177], v[232:235], v[8:11]
	s_setprio 0
	s_setprio 1
	v_mfma_f32_16x16x32_bf16 v[52:55], v[178:181], v[204:207], v[52:55]
	v_mfma_f32_16x16x32_bf16 v[48:51], v[186:189], v[204:207], v[48:51]
	v_mfma_f32_16x16x32_bf16 v[36:39], v[178:181], v[212:215], v[36:39]
	v_mfma_f32_16x16x32_bf16 v[32:35], v[186:189], v[212:215], v[32:35]
	s_add_i32 s70, s70, 2
	s_add_u32 s22, s22, 0x100
	s_addc_u32 s23, s23, 0
	s_add_u32 s68, s68, 0x100
	s_addc_u32 s69, s69, 0
	v_mfma_f32_16x16x32_bf16 v[20:23], v[178:181], v[220:223], v[20:23]
	v_mfma_f32_16x16x32_bf16 v[16:19], v[186:189], v[220:223], v[16:19]
	v_mfma_f32_16x16x32_bf16 v[4:7], v[178:181], v[228:231], v[4:7]
	v_mfma_f32_16x16x32_bf16 v[0:3], v[186:189], v[228:231], v[0:3]
	v_mfma_f32_16x16x32_bf16 v[52:55], v[182:185], v[208:211], v[52:55]
	v_mfma_f32_16x16x32_bf16 v[48:51], v[200:203], v[208:211], v[48:51]
	v_mfma_f32_16x16x32_bf16 v[36:39], v[182:185], v[216:219], v[36:39]
	v_mfma_f32_16x16x32_bf16 v[32:35], v[200:203], v[216:219], v[32:35]
	v_mfma_f32_16x16x32_bf16 v[20:23], v[182:185], v[224:227], v[20:23]
	v_mfma_f32_16x16x32_bf16 v[16:19], v[200:203], v[224:227], v[16:19]
	v_mfma_f32_16x16x32_bf16 v[4:7], v[182:185], v[232:235], v[4:7]
	v_mfma_f32_16x16x32_bf16 v[0:3], v[200:203], v[232:235], v[0:3]
	s_setprio 0
	s_barrier
	s_cmp_gt_u32 s70, 5
.LBB0_395:
	s_add_u32 s24, s22, 0xfffe0080
	s_addc_u32 s25, s23, -1
	s_add_i32 s71, 0, 0x10000
	s_cmp_eq_u32 s70, 4
	s_cselect_b32 s27, s15, s25
	s_cselect_b32 s26, s66, s24
	v_add_u32_e32 v150, s71, v144
	s_cselect_b32 s25, s13, s69
	s_cselect_b32 s24, s67, s68
	s_add_i32 s74, 0, 0x14000
	ds_read_b128 v[138:141], v150
	ds_read_b128 v[146:149], v150 offset:1024
	ds_read_b128 v[170:173], v150 offset:2048
	ds_read_b128 v[174:177], v150 offset:3072
	v_add_u32_e32 v150, s74, v144
	ds_read_b128 v[178:181], v150
	ds_read_b128 v[182:185], v150 offset:1024
	ds_read_b128 v[186:189], v150 offset:2048
	ds_read_b128 v[200:203], v150 offset:3072
	v_lshl_add_u64 v[150:151], s[22:23], 0, v[134:135]
	s_add_i32 m0, s21, 0xc000
	ds_read_b128 v[204:207], v145
	ds_read_b128 v[208:211], v145 offset:1024
	ds_read_b128 v[212:215], v145 offset:2048
	ds_read_b128 v[216:219], v145 offset:3072
	ds_read_b128 v[220:223], v145 offset:4096
	ds_read_b128 v[224:227], v145 offset:5120
	ds_read_b128 v[228:231], v145 offset:6144
	ds_read_b128 v[232:235], v145 offset:7168
	global_load_lds_dwordx4 v[150:151], off
	v_lshl_add_u64 v[150:151], s[22:23], 0, v[136:137]
	s_add_i32 m0, s21, 0xe000
	s_nop 0
	global_load_lds_dwordx4 v[150:151], off
	s_waitcnt vmcnt(8)
	s_waitcnt lgkmcnt(0)
	s_barrier
; #define PG8_STAGE(bufoff, gbase, voff) do { _Pragma("unroll") for (int _i = 0; _i < 2; ++_i) \
;         __builtin_amdgcn_global_load_lds((const unsigned*)((const char*)(gbase) + (voff)[_i]), (LAS unsigned*)(lds + (bufoff) + ldsw + _i * 8192), 16, 0, 0); } while (0)
; #define PG8_LDA(dst, b, h) do { _Pragma("unroll") for (int m = 0; m < 4; ++m) _Pragma("unroll") for (int k = 0; k < 2; ++k) dst[m][k] = *(const LAS bf16x8*)(lds + PG8_SA(b, h) + aoff + m * 2048 + k * 1024); } while (0)
; #define PG8_LDB(dst, b, h) do { _Pragma("unroll") for (int n = 0; n < 2; ++n) _Pragma("unroll") for (int k = 0; k < 2; ++k) dst[n][k] = *(const LAS bf16x8*)(lds + PG8_SB(b, h) + boff + n * 2048 + k * 1024); } while (0)
; #define PG8_MMA(ai, bj, At, Bt) do { __builtin_amdgcn_s_setprio(1); _Pragma("unroll") for (int m = 0; m < 4; ++m) _Pragma("unroll") for (int n = 0; n < 2; ++n) _Pragma("unroll") for (int k = 0; k < 2; ++k) \
;         acc[ai][bj][m][n] = __builtin_amdgcn_mfma_f32_16x16x32_bf16(Bt[n][k], At[m][k], acc[ai][bj][m][n], 0, 0, 0); __builtin_amdgcn_s_setprio(0); } while (0)
; #define PG8_WAIT_V(n) asm volatile("s_waitcnt vmcnt(" #n ")" ::: "memory")
; #define PG8_WAIT_L(n) asm volatile("s_waitcnt lgkmcnt(" #n ")" ::: "memory")
; #define PG8_BAR __builtin_amdgcn_s_barrier()
; #define PG8_SCHED __builtin_amdgcn_sched_barrier(0)
; template <class Epi, class Sched>
; __device__ __forceinline__ void gemm_phase(const int tid, LAS unsigned char* lds, const Gemm g, const Sched& S, const Epi& E) {
;     ...
;             PG8_WAIT_V(8); PG8_WAIT_L(0); PG8_BAR; PG8_MMA(0, 0, At, B0); PG8_MMA(0, 1, At, B1); PG8_BAR; PG8_SCHED;
;             PG8_LDA(At, 0, 1); PG8_STAGE(PG8_SB(0, 0), b2, voffB); PG8_STAGE(PG8_SB(0, 1), b2 + hstep, voffB); PG8_STAGE(PG8_SA(0, 0), a2, voffA);
;             PG8_WAIT_V(8); PG8_WAIT_L(0); PG8_BAR; PG8_MMA(1, 0, At, B0); PG8_MMA(1, 1, At, B1); PG8_BAR; PG8_SCHED;
;             PG8_LDB(B0, 1, 0); PG8_LDB(B1, 1, 1); PG8_SCHED; PG8_LDA(At, 1, 0); PG8_STAGE(PG8_SA(0, 1), a2 + hstep, voffA);
;             PG8_WAIT_V(8); PG8_WAIT_L(0); PG8_BAR; PG8_MMA(0, 0, At, B0); PG8_MMA(0, 1, At, B1); PG8_BAR; PG8_SCHED;
	s_setprio 1
	s_waitcnt lgkmcnt(0)
	v_mfma_f32_16x16x32_bf16 v[124:127], v[138:141], v[204:207], v[124:127]
	v_mfma_f32_16x16x32_bf16 v[120:123], v[170:173], v[204:207], v[120:123]
	v_mfma_f32_16x16x32_bf16 v[108:111], v[138:141], v[212:215], v[108:111]
	v_mfma_f32_16x16x32_bf16 v[104:107], v[170:173], v[212:215], v[104:107]
	v_mfma_f32_16x16x32_bf16 v[92:95], v[138:141], v[220:223], v[92:95]
	v_mfma_f32_16x16x32_bf16 v[88:91], v[170:173], v[220:223], v[88:91]
	v_mfma_f32_16x16x32_bf16 v[76:79], v[138:141], v[228:231], v[76:79]
	v_mfma_f32_16x16x32_bf16 v[72:75], v[170:173], v[228:231], v[72:75]
	v_mfma_f32_16x16x32_bf16 v[124:127], v[146:149], v[208:211], v[124:127]
	v_mfma_f32_16x16x32_bf16 v[120:123], v[174:177], v[208:211], v[120:123]
	v_mfma_f32_16x16x32_bf16 v[108:111], v[146:149], v[216:219], v[108:111]
	v_mfma_f32_16x16x32_bf16 v[104:107], v[174:177], v[216:219], v[104:107]
	v_mfma_f32_16x16x32_bf16 v[92:95], v[146:149], v[224:227], v[92:95]
	v_mfma_f32_16x16x32_bf16 v[88:91], v[174:177], v[224:227], v[88:91]
	v_mfma_f32_16x16x32_bf16 v[76:79], v[146:149], v[232:235], v[76:79]
	v_mfma_f32_16x16x32_bf16 v[72:75], v[174:177], v[232:235], v[72:75]
	s_setprio 0
	s_setprio 1
	v_mfma_f32_16x16x32_bf16 v[116:119], v[178:181], v[204:207], v[116:119]
	v_mfma_f32_16x16x32_bf16 v[112:115], v[186:189], v[204:207], v[112:115]
	v_mfma_f32_16x16x32_bf16 v[100:103], v[178:181], v[212:215], v[100:103]
	v_mfma_f32_16x16x32_bf16 v[96:99], v[186:189], v[212:215], v[96:99]
	v_mfma_f32_16x16x32_bf16 v[84:87], v[178:181], v[220:223], v[84:87]
	v_mfma_f32_16x16x32_bf16 v[80:83], v[186:189], v[220:223], v[80:83]
	v_mfma_f32_16x16x32_bf16 v[68:71], v[178:181], v[228:231], v[68:71]
	v_mfma_f32_16x16x32_bf16 v[64:67], v[186:189], v[228:231], v[64:67]
	v_mfma_f32_16x16x32_bf16 v[116:119], v[182:185], v[208:211], v[116:119]
	v_mfma_f32_16x16x32_bf16 v[112:115], v[200:203], v[208:211], v[112:115]
	v_mfma_f32_16x16x32_bf16 v[100:103], v[182:185], v[216:219], v[100:103]
	v_mfma_f32_16x16x32_bf16 v[96:99], v[200:203], v[216:219], v[96:99]
	v_mfma_f32_16x16x32_bf16 v[84:87], v[182:185], v[224:227], v[84:87]
	v_mfma_f32_16x16x32_bf16 v[80:83], v[200:203], v[224:227], v[80:83]
	v_mfma_f32_16x16x32_bf16 v[68:71], v[182:185], v[232:235], v[68:71]
	v_mfma_f32_16x16x32_bf16 v[64:67], v[200:203], v[232:235], v[64:67]
	s_setprio 0
	s_barrier
	s_add_i32 s71, s71, s55
	v_lshl_add_u64 v[150:151], s[24:25], 0, v[152:153]
	s_mov_b32 m0, s71
	ds_read_b128 v[204:207], v145 offset:16384
	ds_read_b128 v[208:211], v145 offset:17408
	ds_read_b128 v[212:215], v145 offset:18432
	ds_read_b128 v[216:219], v145 offset:19456
	ds_read_b128 v[220:223], v145 offset:20480
	ds_read_b128 v[224:227], v145 offset:21504
	ds_read_b128 v[228:231], v145 offset:22528
	ds_read_b128 v[232:235], v145 offset:23552
	global_load_lds_dwordx4 v[150:151], off
	s_add_i32 m0, s71, 0x2000
	s_add_u32 s72, s24, 0x20000
	v_lshl_add_u64 v[190:191], s[24:25], 0, v[132:133]
	s_addc_u32 s73, s25, 0
	s_add_i32 s71, s74, s55
	global_load_lds_dwordx4 v[190:191], off
	v_lshl_add_u64 v[236:237], s[72:73], 0, v[152:153]
	s_mov_b32 m0, s71
	v_lshl_add_u64 v[238:239], s[26:27], 0, v[130:131]
	global_load_lds_dwordx4 v[236:237], off
	v_lshl_add_u64 v[236:237], s[72:73], 0, v[132:133]
	s_add_i32 m0, s71, 0x2000
	s_nop 0
	global_load_lds_dwordx4 v[236:237], off
	v_lshl_add_u64 v[236:237], s[26:27], 0, v[128:129]
	s_mov_b32 m0, s21
	s_nop 0
	global_load_lds_dwordx4 v[236:237], off
	s_mov_b32 m0, s56
	s_nop 0
	global_load_lds_dwordx4 v[238:239], off
	s_waitcnt vmcnt(8)
	s_waitcnt lgkmcnt(0)
	s_barrier
	s_setprio 1
	s_waitcnt lgkmcnt(0)
	v_mfma_f32_16x16x32_bf16 v[60:63], v[138:141], v[204:207], v[60:63]
	v_mfma_f32_16x16x32_bf16 v[56:59], v[170:173], v[204:207], v[56:59]
	v_mfma_f32_16x16x32_bf16 v[44:47], v[138:141], v[212:215], v[44:47]
	v_mfma_f32_16x16x32_bf16 v[40:43], v[170:173], v[212:215], v[40:43]
	v_mfma_f32_16x16x32_bf16 v[28:31], v[138:141], v[220:223], v[28:31]
	v_mfma_f32_16x16x32_bf16 v[24:27], v[170:173], v[220:223], v[24:27]
	v_mfma_f32_16x16x32_bf16 v[12:15], v[138:141], v[228:231], v[12:15]
	v_mfma_f32_16x16x32_bf16 v[8:11], v[170:173], v[228:231], v[8:11]
	v_mfma_f32_16x16x32_bf16 v[60:63], v[146:149], v[208:211], v[60:63]
	v_mfma_f32_16x16x32_bf16 v[56:59], v[174:177], v[208:211], v[56:59]
	v_mfma_f32_16x16x32_bf16 v[44:47], v[146:149], v[216:219], v[44:47]
	v_mfma_f32_16x16x32_bf16 v[40:43], v[174:177], v[216:219], v[40:43]
	v_mfma_f32_16x16x32_bf16 v[28:31], v[146:149], v[224:227], v[28:31]
	v_mfma_f32_16x16x32_bf16 v[24:27], v[174:177], v[224:227], v[24:27]
	v_mfma_f32_16x16x32_bf16 v[12:15], v[146:149], v[232:235], v[12:15]
	v_mfma_f32_16x16x32_bf16 v[8:11], v[174:177], v[232:235], v[8:11]
	s_setprio 0
	s_setprio 1
	v_mfma_f32_16x16x32_bf16 v[52:55], v[178:181], v[204:207], v[52:55]
	v_mfma_f32_16x16x32_bf16 v[48:51], v[186:189], v[204:207], v[48:51]
	v_mfma_f32_16x16x32_bf16 v[36:39], v[178:181], v[212:215], v[36:39]
	v_mfma_f32_16x16x32_bf16 v[32:35], v[186:189], v[212:215], v[32:35]
	v_mfma_f32_16x16x32_bf16 v[20:23], v[178:181], v[220:223], v[20:23]
	v_mfma_f32_16x16x32_bf16 v[16:19], v[186:189], v[220:223], v[16:19]
	v_mfma_f32_16x16x32_bf16 v[4:7], v[178:181], v[228:231], v[4:7]
	v_mfma_f32_16x16x32_bf16 v[0:3], v[186:189], v[228:231], v[0:3]
	v_mfma_f32_16x16x32_bf16 v[52:55], v[182:185], v[208:211], v[52:55]
	v_mfma_f32_16x16x32_bf16 v[48:51], v[200:203], v[208:211], v[48:51]
	v_mfma_f32_16x16x32_bf16 v[36:39], v[182:185], v[216:219], v[36:39]
	v_mfma_f32_16x16x32_bf16 v[32:35], v[200:203], v[216:219], v[32:35]
	v_mfma_f32_16x16x32_bf16 v[20:23], v[182:185], v[224:227], v[20:23]
	v_mfma_f32_16x16x32_bf16 v[16:19], v[200:203], v[224:227], v[16:19]
	v_mfma_f32_16x16x32_bf16 v[4:7], v[182:185], v[232:235], v[4:7]
	v_mfma_f32_16x16x32_bf16 v[0:3], v[200:203], v[232:235], v[0:3]
	s_setprio 0
	s_barrier
; #define PG8_STAGE(bufoff, gbase, voff) do { _Pragma("unroll") for (int _i = 0; _i < 2; ++_i) \
;         __builtin_amdgcn_global_load_lds((const unsigned*)((const char*)(gbase) + (voff)[_i]), (LAS unsigned*)(lds + (bufoff) + ldsw + _i * 8192), 16, 0, 0); } while (0)
; #define PG8_LDA(dst, b, h) do { _Pragma("unroll") for (int m = 0; m < 4; ++m) _Pragma("unroll") for (int k = 0; k < 2; ++k) dst[m][k] = *(const LAS bf16x8*)(lds + PG8_SA(b, h) + aoff + m * 2048 + k * 1024); } while (0)
; #define PG8_MMA(ai, bj, At, Bt) do { __builtin_amdgcn_s_setprio(1); _Pragma("unroll") for (int m = 0; m < 4; ++m) _Pragma("unroll") for (int n = 0; n < 2; ++n) _Pragma("unroll") for (int k = 0; k < 2; ++k) \
;         acc[ai][bj][m][n] = __builtin_amdgcn_mfma_f32_16x16x32_bf16(Bt[n][k], At[m][k], acc[ai][bj][m][n], 0, 0, 0); __builtin_amdgcn_s_setprio(0); } while (0)
; #define PG8_WAIT_V(n) asm volatile("s_waitcnt vmcnt(" #n ")" ::: "memory")
; #define PG8_WAIT_L(n) asm volatile("s_waitcnt lgkmcnt(" #n ")" ::: "memory")
; #define PG8_BAR __builtin_amdgcn_s_barrier()
; #define PG8_SCHED __builtin_amdgcn_sched_barrier(0)
; template <class Epi, class Sched>
; __device__ __forceinline__ void gemm_phase(const int tid, LAS unsigned char* lds, const Gemm g, const Sched& S, const Epi& E) {
;     ...
;             PG8_LDA(At, 1, 1); PG8_STAGE(PG8_SB(1, 0), b3, voffB); PG8_STAGE(PG8_SB(1, 1), b3 + hstep, voffB); PG8_STAGE(PG8_SA(1, 0), a3, voffA);
;             PG8_WAIT_V(8); PG8_WAIT_L(0); PG8_BAR; PG8_MMA(1, 0, At, B0); PG8_MMA(1, 1, At, B1); PG8_BAR; PG8_SCHED;
	s_add_i32 s71, 0, 0x18000
	s_add_i32 s72, 0, 0x1c000
	v_add_u32_e32 v174, s71, v144
	v_add_u32_e32 v199, s72, v144
	ds_read_b128 v[138:141], v174
	ds_read_b128 v[146:149], v174 offset:1024
	ds_read_b128 v[170:173], v174 offset:2048
	ds_read_b128 v[174:177], v174 offset:3072
	ds_read_b128 v[178:181], v199
	ds_read_b128 v[182:185], v199 offset:1024
	ds_read_b128 v[186:189], v199 offset:2048
	ds_read_b128 v[200:203], v199 offset:3072
	s_add_u32 s26, s26, 0x20000
	s_addc_u32 s27, s27, 0
	s_mov_b32 m0, s57
	v_lshl_add_u64 v[240:241], s[26:27], 0, v[128:129]
	ds_read_b128 v[204:207], v145 offset:32768
	ds_read_b128 v[208:211], v145 offset:33792
	ds_read_b128 v[212:215], v145 offset:34816
	ds_read_b128 v[216:219], v145 offset:35840
	ds_read_b128 v[220:223], v145 offset:36864
	ds_read_b128 v[224:227], v145 offset:37888
	ds_read_b128 v[228:231], v145 offset:38912
	ds_read_b128 v[232:235], v145 offset:39936
	global_load_lds_dwordx4 v[240:241], off
	v_lshl_add_u64 v[240:241], s[26:27], 0, v[130:131]
	s_mov_b32 m0, s58
	s_nop 0
	global_load_lds_dwordx4 v[240:241], off
	s_waitcnt vmcnt(8)
	s_waitcnt lgkmcnt(0)
	s_barrier
	s_setprio 1
	s_waitcnt lgkmcnt(0)
	v_mfma_f32_16x16x32_bf16 v[124:127], v[138:141], v[204:207], v[124:127]
	v_mfma_f32_16x16x32_bf16 v[120:123], v[170:173], v[204:207], v[120:123]
	v_mfma_f32_16x16x32_bf16 v[108:111], v[138:141], v[212:215], v[108:111]
	v_mfma_f32_16x16x32_bf16 v[104:107], v[170:173], v[212:215], v[104:107]
	v_mfma_f32_16x16x32_bf16 v[92:95], v[138:141], v[220:223], v[92:95]
	v_mfma_f32_16x16x32_bf16 v[88:91], v[170:173], v[220:223], v[88:91]
	v_mfma_f32_16x16x32_bf16 v[76:79], v[138:141], v[228:231], v[76:79]
	v_mfma_f32_16x16x32_bf16 v[72:75], v[170:173], v[228:231], v[72:75]
	v_mfma_f32_16x16x32_bf16 v[124:127], v[146:149], v[208:211], v[124:127]
	v_mfma_f32_16x16x32_bf16 v[120:123], v[174:177], v[208:211], v[120:123]
	v_mfma_f32_16x16x32_bf16 v[108:111], v[146:149], v[216:219], v[108:111]
	v_mfma_f32_16x16x32_bf16 v[104:107], v[174:177], v[216:219], v[104:107]
	v_mfma_f32_16x16x32_bf16 v[92:95], v[146:149], v[224:227], v[92:95]
	v_mfma_f32_16x16x32_bf16 v[88:91], v[174:177], v[224:227], v[88:91]
	v_mfma_f32_16x16x32_bf16 v[76:79], v[146:149], v[232:235], v[76:79]
	v_mfma_f32_16x16x32_bf16 v[72:75], v[174:177], v[232:235], v[72:75]
	s_setprio 0
	s_setprio 1
	v_mfma_f32_16x16x32_bf16 v[116:119], v[178:181], v[204:207], v[116:119]
	v_mfma_f32_16x16x32_bf16 v[112:115], v[186:189], v[204:207], v[112:115]
	v_mfma_f32_16x16x32_bf16 v[100:103], v[178:181], v[212:215], v[100:103]
	v_mfma_f32_16x16x32_bf16 v[96:99], v[186:189], v[212:215], v[96:99]
	v_mfma_f32_16x16x32_bf16 v[84:87], v[178:181], v[220:223], v[84:87]
	v_mfma_f32_16x16x32_bf16 v[80:83], v[186:189], v[220:223], v[80:83]
	v_mfma_f32_16x16x32_bf16 v[68:71], v[178:181], v[228:231], v[68:71]
	v_mfma_f32_16x16x32_bf16 v[64:67], v[186:189], v[228:231], v[64:67]
	v_mfma_f32_16x16x32_bf16 v[116:119], v[182:185], v[208:211], v[116:119]
	v_mfma_f32_16x16x32_bf16 v[112:115], v[200:203], v[208:211], v[112:115]
	v_mfma_f32_16x16x32_bf16 v[100:103], v[182:185], v[216:219], v[100:103]
	v_mfma_f32_16x16x32_bf16 v[96:99], v[200:203], v[216:219], v[96:99]
	v_mfma_f32_16x16x32_bf16 v[84:87], v[182:185], v[224:227], v[84:87]
	v_mfma_f32_16x16x32_bf16 v[80:83], v[200:203], v[224:227], v[80:83]
	v_mfma_f32_16x16x32_bf16 v[68:71], v[182:185], v[232:235], v[68:71]
	v_mfma_f32_16x16x32_bf16 v[64:67], v[200:203], v[232:235], v[64:67]
	s_setprio 0
	s_barrier
; #define PG8_STAGE(bufoff, gbase, voff) do { _Pragma("unroll") for (int _i = 0; _i < 2; ++_i) \
;         __builtin_amdgcn_global_load_lds((const unsigned*)((const char*)(gbase) + (voff)[_i]), (LAS unsigned*)(lds + (bufoff) + ldsw + _i * 8192), 16, 0, 0); } while (0)
; #define PG8_LDA(dst, b, h) do { _Pragma("unroll") for (int m = 0; m < 4; ++m) _Pragma("unroll") for (int k = 0; k < 2; ++k) dst[m][k] = *(const LAS bf16x8*)(lds + PG8_SA(b, h) + aoff + m * 2048 + k * 1024); } while (0)
; #define PG8_LDB(dst, b, h) do { _Pragma("unroll") for (int n = 0; n < 2; ++n) _Pragma("unroll") for (int k = 0; k < 2; ++k) dst[n][k] = *(const LAS bf16x8*)(lds + PG8_SB(b, h) + boff + n * 2048 + k * 1024); } while (0)
; #define PG8_MMA(ai, bj, At, Bt) do { __builtin_amdgcn_s_setprio(1); _Pragma("unroll") for (int m = 0; m < 4; ++m) _Pragma("unroll") for (int n = 0; n < 2; ++n) _Pragma("unroll") for (int k = 0; k < 2; ++k) \
;         acc[ai][bj][m][n] = __builtin_amdgcn_mfma_f32_16x16x32_bf16(Bt[n][k], At[m][k], acc[ai][bj][m][n], 0, 0, 0); __builtin_amdgcn_s_setprio(0); } while (0)
; #define PG8_WAIT_V(n) asm volatile("s_waitcnt vmcnt(" #n ")" ::: "memory")
; #define PG8_WAIT_L(n) asm volatile("s_waitcnt lgkmcnt(" #n ")" ::: "memory")
; #define PG8_BAR __builtin_amdgcn_s_barrier()
; #define PG8_SCHED __builtin_amdgcn_sched_barrier(0)
; template <class Epi, class Sched>
; __device__ __forceinline__ void gemm_phase(const int tid, LAS unsigned char* lds, const Gemm g, const Sched& S, const Epi& E) {
;     ...
;             PG8_LDB(B0, 1, 0); PG8_LDB(B1, 1, 1); PG8_SCHED; PG8_LDA(At, 1, 0); PG8_STAGE(PG8_SA(0, 1), a2 + hstep, voffA);
;             PG8_WAIT_V(8); PG8_WAIT_L(0); PG8_BAR; PG8_MMA(0, 0, At, B0); PG8_MMA(0, 1, At, B1); PG8_BAR; PG8_SCHED;
;             PG8_LDA(At, 1, 1); PG8_STAGE(PG8_SB(1, 0), b3, voffB); PG8_STAGE(PG8_SB(1, 1), b3 + hstep, voffB); PG8_STAGE(PG8_SA(1, 0), a3, voffA);
;             PG8_WAIT_V(8); PG8_WAIT_L(0); PG8_BAR; PG8_MMA(1, 0, At, B0); PG8_MMA(1, 1, At, B1); PG8_BAR; PG8_SCHED;
;         }
;         if (wr == 0) PG8_BAR;
	s_add_i32 s26, s71, s55
	v_lshl_add_u64 v[150:151], v[150:151], 0, s[34:35]
	s_mov_b32 m0, s26
	ds_read_b128 v[204:207], v145 offset:49152
	ds_read_b128 v[208:211], v145 offset:50176
	ds_read_b128 v[212:215], v145 offset:51200
	ds_read_b128 v[216:219], v145 offset:52224
	ds_read_b128 v[220:223], v145 offset:53248
	ds_read_b128 v[224:227], v145 offset:54272
	ds_read_b128 v[228:231], v145 offset:55296
	ds_read_b128 v[232:235], v145 offset:56320
	global_load_lds_dwordx4 v[150:151], off
	s_add_i32 m0, s26, 0x2000
	s_add_u32 s24, s24, 0x20080
	v_lshl_add_u64 v[150:151], v[190:191], 0, s[34:35]
	s_addc_u32 s25, s25, 0
	s_add_i32 s26, s72, s55
	global_load_lds_dwordx4 v[150:151], off
	v_lshl_add_u64 v[150:151], s[24:25], 0, v[152:153]
	s_mov_b32 m0, s26
	s_nop 0
	global_load_lds_dwordx4 v[150:151], off
	v_lshl_add_u64 v[150:151], s[24:25], 0, v[132:133]
	s_add_i32 m0, s26, 0x2000
	s_nop 0
	global_load_lds_dwordx4 v[150:151], off
	v_lshl_add_u64 v[150:151], v[236:237], 0, s[34:35]
	s_mov_b32 m0, s61
	s_nop 0
	global_load_lds_dwordx4 v[150:151], off
	v_lshl_add_u64 v[150:151], v[238:239], 0, s[34:35]
	s_mov_b32 m0, s62
	s_nop 0
	global_load_lds_dwordx4 v[150:151], off
	s_waitcnt vmcnt(8)
	s_waitcnt lgkmcnt(0)
	s_barrier
	s_setprio 1
	s_waitcnt lgkmcnt(0)
	v_mfma_f32_16x16x32_bf16 v[60:63], v[138:141], v[204:207], v[60:63]
	v_mfma_f32_16x16x32_bf16 v[56:59], v[170:173], v[204:207], v[56:59]
	v_mfma_f32_16x16x32_bf16 v[44:47], v[138:141], v[212:215], v[44:47]
	v_mfma_f32_16x16x32_bf16 v[40:43], v[170:173], v[212:215], v[40:43]
	v_mfma_f32_16x16x32_bf16 v[28:31], v[138:141], v[220:223], v[28:31]
	v_mfma_f32_16x16x32_bf16 v[24:27], v[170:173], v[220:223], v[24:27]
	v_mfma_f32_16x16x32_bf16 v[12:15], v[138:141], v[228:231], v[12:15]
	v_mfma_f32_16x16x32_bf16 v[8:11], v[170:173], v[228:231], v[8:11]
	v_mfma_f32_16x16x32_bf16 v[60:63], v[146:149], v[208:211], v[60:63]
	v_mfma_f32_16x16x32_bf16 v[56:59], v[174:177], v[208:211], v[56:59]
	v_mfma_f32_16x16x32_bf16 v[44:47], v[146:149], v[216:219], v[44:47]
	v_mfma_f32_16x16x32_bf16 v[40:43], v[174:177], v[216:219], v[40:43]
	v_mfma_f32_16x16x32_bf16 v[28:31], v[146:149], v[224:227], v[28:31]
	v_mfma_f32_16x16x32_bf16 v[24:27], v[174:177], v[224:227], v[24:27]
	v_mfma_f32_16x16x32_bf16 v[12:15], v[146:149], v[232:235], v[12:15]
	v_mfma_f32_16x16x32_bf16 v[8:11], v[174:177], v[232:235], v[8:11]
	s_setprio 0
	s_setprio 1
	v_mfma_f32_16x16x32_bf16 v[52:55], v[178:181], v[204:207], v[52:55]
	v_mfma_f32_16x16x32_bf16 v[48:51], v[186:189], v[204:207], v[48:51]
	v_mfma_f32_16x16x32_bf16 v[36:39], v[178:181], v[212:215], v[36:39]
	v_mfma_f32_16x16x32_bf16 v[32:35], v[186:189], v[212:215], v[32:35]
	s_add_i32 s70, s70, 2
	s_add_u32 s22, s22, 0x100
	s_addc_u32 s23, s23, 0
	s_add_u32 s68, s68, 0x100
	s_addc_u32 s69, s69, 0
	v_mfma_f32_16x16x32_bf16 v[20:23], v[178:181], v[220:223], v[20:23]
	v_mfma_f32_16x16x32_bf16 v[16:19], v[186:189], v[220:223], v[16:19]
	v_mfma_f32_16x16x32_bf16 v[4:7], v[178:181], v[228:231], v[4:7]
	v_mfma_f32_16x16x32_bf16 v[0:3], v[186:189], v[228:231], v[0:3]
	v_mfma_f32_16x16x32_bf16 v[52:55], v[182:185], v[208:211], v[52:55]
	v_mfma_f32_16x16x32_bf16 v[48:51], v[200:203], v[208:211], v[48:51]
	v_mfma_f32_16x16x32_bf16 v[36:39], v[182:185], v[216:219], v[36:39]
	v_mfma_f32_16x16x32_bf16 v[32:35], v[200:203], v[216:219], v[32:35]
	v_mfma_f32_16x16x32_bf16 v[20:23], v[182:185], v[224:227], v[20:23]
	v_mfma_f32_16x16x32_bf16 v[16:19], v[200:203], v[224:227], v[16:19]
	v_mfma_f32_16x16x32_bf16 v[4:7], v[182:185], v[232:235], v[4:7]
	v_mfma_f32_16x16x32_bf16 v[0:3], v[200:203], v[232:235], v[0:3]
	s_setprio 0
	s_barrier
	s_cmp_gt_u32 s70, 5
	s_cbranch_scc0 .LBB0_395
	s_and_b64 vcc, exec, s[10:11]
	s_cbranch_vccz .LBB0_398
	s_barrier

; #define PG8_STAGE(bufoff, gbase, voff) do { _Pragma("unroll") for (int _i = 0; _i < 2; ++_i) \
;         __builtin_amdgcn_global_load_lds((const unsigned*)((const char*)(gbase) + (voff)[_i]), (LAS unsigned*)(lds + (bufoff) + ldsw + _i * 8192), 16, 0, 0); } while (0)
; #define PG8_LDA(dst, b, h) do { _Pragma("unroll") for (int m = 0; m < 4; ++m) _Pragma("unroll") for (int k = 0; k < 2; ++k) dst[m][k] = *(const LAS bf16x8*)(lds + PG8_SA(b, h) + aoff + m * 2048 + k * 1024); } while (0)
; #define PG8_LDB(dst, b, h) do { _Pragma("unroll") for (int n = 0; n < 2; ++n) _Pragma("unroll") for (int k = 0; k < 2; ++k) dst[n][k] = *(const LAS bf16x8*)(lds + PG8_SB(b, h) + boff + n * 2048 + k * 1024); } while (0)
; #define PG8_MMA(ai, bj, At, Bt) do { __builtin_amdgcn_s_setprio(1); _Pragma("unroll") for (int m = 0; m < 4; ++m) _Pragma("unroll") for (int n = 0; n < 2; ++n) _Pragma("unroll") for (int k = 0; k < 2; ++k) \
;         acc[ai][bj][m][n] = __builtin_amdgcn_mfma_f32_16x16x32_bf16(Bt[n][k], At[m][k], acc[ai][bj][m][n], 0, 0, 0); __builtin_amdgcn_s_setprio(0); } while (0)
; template <class Epi, class Sched>
; __device__ __forceinline__ void gemm_phase(const int tid, LAS unsigned char* lds, const Gemm g, const Sched& S, const Epi& E) {
;     ...
;         const bool has_next = S.next(ui + 1, nxt);
;         const char* nA = has_next ? (const char*)g.A + (size_t)nxt.pm * tstep : cA; const char* nB = has_next ? (const char*)g.Bt + (size_t)nxt.pn * tstep : cB;
;         for (int t = 0; t < nt; t += 2) {
;             const bool last = (t == nt - 2);
;             const char* a1 = cA + (size_t)(t + 1) * kstep;
;             const char* a2 = last ? nA : cA + (size_t)(t + 2) * kstep; const char* b2 = last ? nB : cB + (size_t)(t + 2) * kstep;
;             const char* a3 = a2 + kstep; const char* b3 = b2 + kstep;
;             if (last && has_next) S.a_ready(nxt);
;             PG8_LDB(B0, 0, 0); PG8_LDB(B1, 0, 1); PG8_SCHED; PG8_LDA(At, 0, 0); PG8_STAGE(PG8_SA(1, 1), a1 + hstep, voffA);
;             PG8_WAIT_V(8); PG8_WAIT_L(0); PG8_BAR; PG8_MMA(0, 0, At, B0); PG8_MMA(0, 1, At, B1); PG8_BAR; PG8_SCHED;
;             PG8_LDA(At, 0, 1); PG8_STAGE(PG8_SB(0, 0), b2, voffB); PG8_STAGE(PG8_SB(0, 1), b2 + hstep, voffB); PG8_STAGE(PG8_SA(0, 0), a2, voffA);
;             PG8_WAIT_V(8); PG8_WAIT_L(0); PG8_BAR; PG8_MMA(1, 0, At, B0); PG8_MMA(1, 1, At, B1); PG8_BAR; PG8_SCHED;
.LBB0_549:
	s_ashr_i32 s17, s16, 31
	s_lshl_b64 s[18:19], s[16:17], 20
	s_add_u32 s18, s41, s18
	s_addc_u32 s19, s55, s19
	s_and_b64 s[20:21], s[0:1], exec
	s_cselect_b32 s5, s19, s25
	s_cselect_b32 s17, s18, s24
	s_ashr_i32 s15, s14, 31
	s_lshl_b64 s[20:21], s[14:15], 20
	s_add_u32 s20, s39, s20
	s_addc_u32 s21, s40, s21
	s_and_b64 s[28:29], s[0:1], exec
	s_cselect_b32 s15, s21, s27
	s_cselect_b32 s23, s20, s26
	s_add_u32 s24, s24, 0x80080
	s_addc_u32 s25, s25, 0
	s_add_u32 s69, s26, 0x100
	v_mov_b32_e32 v0, 0
	s_addc_u32 s70, s27, 0
	s_mov_b32 s71, -2
	s_waitcnt lgkmcnt(0)
	s_add_u32 s26, s24, 0xfff80080
	s_addc_u32 s27, s25, -1
	s_add_i32 s72, 0, 0x10000
	s_cmp_eq_u32 s71, 28
	s_cselect_b32 s29, s5, s27
	s_cselect_b32 s28, s17, s26
	s_cselect_b32 s27, s15, s70
	s_cselect_b32 s26, s23, s69
	s_add_i32 s74, 0, 0x14000
	v_add_u32_e32 v140, s72, v201
	v_add_u32_e32 v184, s74, v201
	ds_read_b128 v[128:131], v140
	ds_read_b128 v[132:135], v140 offset:1024
	ds_read_b128 v[136:139], v140 offset:2048
	ds_read_b128 v[140:143], v140 offset:3072
	ds_read_b128 v[144:147], v184
	ds_read_b128 v[148:151], v184 offset:1024
	ds_read_b128 v[180:183], v184 offset:2048
	ds_read_b128 v[184:187], v184 offset:3072
	v_lshl_add_u64 v[232:233], s[24:25], 0, v[176:177]
	s_add_i32 m0, s57, 0xc000
	ds_read_b128 v[188:191], v202
	ds_read_b128 v[204:207], v202 offset:1024
	ds_read_b128 v[208:211], v202 offset:2048
	ds_read_b128 v[212:215], v202 offset:3072
	ds_read_b128 v[216:219], v202 offset:4096
	ds_read_b128 v[220:223], v202 offset:5120
	ds_read_b128 v[224:227], v202 offset:6144
	ds_read_b128 v[228:231], v202 offset:7168
	global_load_lds_dwordx4 v[232:233], off
	v_lshl_add_u64 v[232:233], s[24:25], 0, v[178:179]
	s_add_i32 m0, s57, 0xe000
	s_nop 0
	global_load_lds_dwordx4 v[232:233], off
	s_waitcnt vmcnt(8)
	s_waitcnt lgkmcnt(0)
	s_barrier
	s_setprio 1
	s_waitcnt lgkmcnt(0)
	v_mfma_f32_16x16x32_bf16 v[124:127], v[128:131], v[188:191], 0
	v_mfma_f32_16x16x32_bf16 v[120:123], v[136:139], v[188:191], 0
	v_mfma_f32_16x16x32_bf16 v[108:111], v[128:131], v[208:211], 0
	v_mfma_f32_16x16x32_bf16 v[104:107], v[136:139], v[208:211], 0
	v_mfma_f32_16x16x32_bf16 v[92:95], v[128:131], v[216:219], 0
	v_mfma_f32_16x16x32_bf16 v[88:91], v[136:139], v[216:219], 0
	v_mfma_f32_16x16x32_bf16 v[76:79], v[128:131], v[224:227], 0
	v_mfma_f32_16x16x32_bf16 v[72:75], v[136:139], v[224:227], 0
	v_mfma_f32_16x16x32_bf16 v[124:127], v[132:135], v[204:207], v[124:127]
	v_mfma_f32_16x16x32_bf16 v[120:123], v[140:143], v[204:207], v[120:123]
	v_mfma_f32_16x16x32_bf16 v[108:111], v[132:135], v[212:215], v[108:111]
	v_mfma_f32_16x16x32_bf16 v[104:107], v[140:143], v[212:215], v[104:107]
	v_mfma_f32_16x16x32_bf16 v[92:95], v[132:135], v[220:223], v[92:95]
	v_mfma_f32_16x16x32_bf16 v[88:91], v[140:143], v[220:223], v[88:91]
	v_mfma_f32_16x16x32_bf16 v[76:79], v[132:135], v[228:231], v[76:79]
	v_mfma_f32_16x16x32_bf16 v[72:75], v[140:143], v[228:231], v[72:75]
	s_setprio 0
	s_setprio 1
	v_mfma_f32_16x16x32_bf16 v[116:119], v[144:147], v[188:191], 0
	v_mfma_f32_16x16x32_bf16 v[112:115], v[180:183], v[188:191], 0
	v_mfma_f32_16x16x32_bf16 v[100:103], v[144:147], v[208:211], 0
	v_mfma_f32_16x16x32_bf16 v[96:99], v[180:183], v[208:211], 0
	v_mfma_f32_16x16x32_bf16 v[84:87], v[144:147], v[216:219], 0
	v_mfma_f32_16x16x32_bf16 v[80:83], v[180:183], v[216:219], 0
	v_mfma_f32_16x16x32_bf16 v[68:71], v[144:147], v[224:227], 0
	v_mfma_f32_16x16x32_bf16 v[64:67], v[180:183], v[224:227], 0
	v_mfma_f32_16x16x32_bf16 v[116:119], v[148:151], v[204:207], v[116:119]
	v_mfma_f32_16x16x32_bf16 v[112:115], v[184:187], v[204:207], v[112:115]
	v_mfma_f32_16x16x32_bf16 v[100:103], v[148:151], v[212:215], v[100:103]
	v_mfma_f32_16x16x32_bf16 v[96:99], v[184:187], v[212:215], v[96:99]
	v_mfma_f32_16x16x32_bf16 v[84:87], v[148:151], v[220:223], v[84:87]
	v_mfma_f32_16x16x32_bf16 v[80:83], v[184:187], v[220:223], v[80:83]
	v_mfma_f32_16x16x32_bf16 v[68:71], v[148:151], v[228:231], v[68:71]
	v_mfma_f32_16x16x32_bf16 v[64:67], v[184:187], v[228:231], v[64:67]
	s_setprio 0
	s_barrier
	s_add_i32 s72, s72, s56
	v_lshl_add_u64 v[232:233], s[26:27], 0, v[152:153]
	s_mov_b32 m0, s72
	ds_read_b128 v[188:191], v202 offset:16384
	ds_read_b128 v[204:207], v202 offset:17408
	ds_read_b128 v[208:211], v202 offset:18432
	ds_read_b128 v[212:215], v202 offset:19456
	ds_read_b128 v[216:219], v202 offset:20480
	ds_read_b128 v[220:223], v202 offset:21504
	ds_read_b128 v[224:227], v202 offset:22528
	ds_read_b128 v[228:231], v202 offset:23552
	global_load_lds_dwordx4 v[232:233], off
	s_add_i32 m0, s72, 0x2000
	s_add_u32 s72, s26, 0x80000
	v_lshl_add_u64 v[234:235], s[26:27], 0, v[174:175]
	s_addc_u32 s73, s27, 0
	s_add_i32 s74, s74, s56
	global_load_lds_dwordx4 v[234:235], off
	v_lshl_add_u64 v[236:237], s[72:73], 0, v[152:153]
	s_mov_b32 m0, s74
	v_lshl_add_u64 v[238:239], s[28:29], 0, v[172:173]
	global_load_lds_dwordx4 v[236:237], off
	v_lshl_add_u64 v[236:237], s[72:73], 0, v[174:175]
	s_add_i32 m0, s74, 0x2000
	s_nop 0
	global_load_lds_dwordx4 v[236:237], off
	v_lshl_add_u64 v[236:237], s[28:29], 0, v[170:171]
	s_mov_b32 m0, s57
	s_nop 0
	global_load_lds_dwordx4 v[236:237], off
	s_mov_b32 m0, s58
	s_nop 0
	global_load_lds_dwordx4 v[238:239], off
	s_waitcnt vmcnt(8)
	s_waitcnt lgkmcnt(0)
	s_barrier
; #define PG8_STAGE(bufoff, gbase, voff) do { _Pragma("unroll") for (int _i = 0; _i < 2; ++_i) \
;         __builtin_amdgcn_global_load_lds((const unsigned*)((const char*)(gbase) + (voff)[_i]), (LAS unsigned*)(lds + (bufoff) + ldsw + _i * 8192), 16, 0, 0); } while (0)
; #define PG8_LDA(dst, b, h) do { _Pragma("unroll") for (int m = 0; m < 4; ++m) _Pragma("unroll") for (int k = 0; k < 2; ++k) dst[m][k] = *(const LAS bf16x8*)(lds + PG8_SA(b, h) + aoff + m * 2048 + k * 1024); } while (0)
; #define PG8_LDB(dst, b, h) do { _Pragma("unroll") for (int n = 0; n < 2; ++n) _Pragma("unroll") for (int k = 0; k < 2; ++k) dst[n][k] = *(const LAS bf16x8*)(lds + PG8_SB(b, h) + boff + n * 2048 + k * 1024); } while (0)
; #define PG8_MMA(ai, bj, At, Bt) do { __builtin_amdgcn_s_setprio(1); _Pragma("unroll") for (int m = 0; m < 4; ++m) _Pragma("unroll") for (int n = 0; n < 2; ++n) _Pragma("unroll") for (int k = 0; k < 2; ++k) \
;         acc[ai][bj][m][n] = __builtin_amdgcn_mfma_f32_16x16x32_bf16(Bt[n][k], At[m][k], acc[ai][bj][m][n], 0, 0, 0); __builtin_amdgcn_s_setprio(0); } while (0)
; #define PG8_WAIT_V(n) asm volatile("s_waitcnt vmcnt(" #n ")" ::: "memory")
; #define PG8_WAIT_L(n) asm volatile("s_waitcnt lgkmcnt(" #n ")" ::: "memory")
; #define PG8_BAR __builtin_amdgcn_s_barrier()
; #define PG8_SCHED __builtin_amdgcn_sched_barrier(0)
; template <class Epi, class Sched>
; __device__ __forceinline__ void gemm_phase(const int tid, LAS unsigned char* lds, const Gemm g, const Sched& S, const Epi& E) {
;     ...
;             PG8_WAIT_V(8); PG8_WAIT_L(0); PG8_BAR; PG8_MMA(1, 0, At, B0); PG8_MMA(1, 1, At, B1); PG8_BAR; PG8_SCHED;
;             PG8_LDB(B0, 1, 0); PG8_LDB(B1, 1, 1); PG8_SCHED; PG8_LDA(At, 1, 0); PG8_STAGE(PG8_SA(0, 1), a2 + hstep, voffA);
;             PG8_WAIT_V(8); PG8_WAIT_L(0); PG8_BAR; PG8_MMA(0, 0, At, B0); PG8_MMA(0, 1, At, B1); PG8_BAR; PG8_SCHED;
;             PG8_LDA(At, 1, 1); PG8_STAGE(PG8_SB(1, 0), b3, voffB); PG8_STAGE(PG8_SB(1, 1), b3 + hstep, voffB); PG8_STAGE(PG8_SA(1, 0), a3, voffA);
;             PG8_WAIT_V(8); PG8_WAIT_L(0); PG8_BAR; PG8_MMA(1, 0, At, B0); PG8_MMA(1, 1, At, B1); PG8_BAR; PG8_SCHED;
	s_setprio 1
	s_waitcnt lgkmcnt(0)
	v_mfma_f32_16x16x32_bf16 v[60:63], v[128:131], v[188:191], 0
	v_mfma_f32_16x16x32_bf16 v[56:59], v[136:139], v[188:191], 0
	v_mfma_f32_16x16x32_bf16 v[44:47], v[128:131], v[208:211], 0
	v_mfma_f32_16x16x32_bf16 v[40:43], v[136:139], v[208:211], 0
	v_mfma_f32_16x16x32_bf16 v[28:31], v[128:131], v[216:219], 0
	v_mfma_f32_16x16x32_bf16 v[24:27], v[136:139], v[216:219], 0
	v_mfma_f32_16x16x32_bf16 v[12:15], v[128:131], v[224:227], 0
	v_mfma_f32_16x16x32_bf16 v[8:11], v[136:139], v[224:227], 0
	v_mfma_f32_16x16x32_bf16 v[60:63], v[132:135], v[204:207], v[60:63]
	v_mfma_f32_16x16x32_bf16 v[56:59], v[140:143], v[204:207], v[56:59]
	v_mfma_f32_16x16x32_bf16 v[44:47], v[132:135], v[212:215], v[44:47]
	v_mfma_f32_16x16x32_bf16 v[40:43], v[140:143], v[212:215], v[40:43]
	v_mfma_f32_16x16x32_bf16 v[28:31], v[132:135], v[220:223], v[28:31]
	v_mfma_f32_16x16x32_bf16 v[24:27], v[140:143], v[220:223], v[24:27]
	v_mfma_f32_16x16x32_bf16 v[12:15], v[132:135], v[228:231], v[12:15]
	v_mfma_f32_16x16x32_bf16 v[8:11], v[140:143], v[228:231], v[8:11]
	s_setprio 0
	s_setprio 1
	v_mfma_f32_16x16x32_bf16 v[52:55], v[144:147], v[188:191], 0
	v_mfma_f32_16x16x32_bf16 v[48:51], v[180:183], v[188:191], 0
	v_mfma_f32_16x16x32_bf16 v[36:39], v[144:147], v[208:211], 0
	v_mfma_f32_16x16x32_bf16 v[32:35], v[180:183], v[208:211], 0
	v_mfma_f32_16x16x32_bf16 v[20:23], v[144:147], v[216:219], 0
	v_mfma_f32_16x16x32_bf16 v[16:19], v[180:183], v[216:219], 0
	v_mfma_f32_16x16x32_bf16 v[4:7], v[144:147], v[224:227], 0
	v_mfma_f32_16x16x32_bf16 v[0:3], v[180:183], v[224:227], 0
	v_mfma_f32_16x16x32_bf16 v[52:55], v[148:151], v[204:207], v[52:55]
	v_mfma_f32_16x16x32_bf16 v[48:51], v[184:187], v[204:207], v[48:51]
	v_mfma_f32_16x16x32_bf16 v[36:39], v[148:151], v[212:215], v[36:39]
	v_mfma_f32_16x16x32_bf16 v[32:35], v[184:187], v[212:215], v[32:35]
	v_mfma_f32_16x16x32_bf16 v[20:23], v[148:151], v[220:223], v[20:23]
	v_mfma_f32_16x16x32_bf16 v[16:19], v[184:187], v[220:223], v[16:19]
	v_mfma_f32_16x16x32_bf16 v[4:7], v[148:151], v[228:231], v[4:7]
	v_mfma_f32_16x16x32_bf16 v[0:3], v[184:187], v[228:231], v[0:3]
	s_setprio 0
	s_barrier
	s_add_i32 s72, 0, 0x18000
	s_add_i32 s73, 0, 0x1c000
	v_add_u32_e32 v140, s72, v201
	v_add_u32_e32 v184, s73, v201
	ds_read_b128 v[128:131], v140
	ds_read_b128 v[132:135], v140 offset:1024
	ds_read_b128 v[136:139], v140 offset:2048
	ds_read_b128 v[140:143], v140 offset:3072
	ds_read_b128 v[144:147], v184
	ds_read_b128 v[148:151], v184 offset:1024
	ds_read_b128 v[180:183], v184 offset:2048
	ds_read_b128 v[184:187], v184 offset:3072
	s_add_u32 s28, s28, 0x80000
	s_addc_u32 s29, s29, 0
	s_mov_b32 m0, s59
	v_lshl_add_u64 v[240:241], s[28:29], 0, v[170:171]
	ds_read_b128 v[188:191], v202 offset:32768
	ds_read_b128 v[204:207], v202 offset:33792
	ds_read_b128 v[208:211], v202 offset:34816
	ds_read_b128 v[212:215], v202 offset:35840
	ds_read_b128 v[216:219], v202 offset:36864
	ds_read_b128 v[220:223], v202 offset:37888
	ds_read_b128 v[224:227], v202 offset:38912
	ds_read_b128 v[228:231], v202 offset:39936
	global_load_lds_dwordx4 v[240:241], off
	v_lshl_add_u64 v[240:241], s[28:29], 0, v[172:173]
	s_mov_b32 m0, s60
	s_nop 0
	global_load_lds_dwordx4 v[240:241], off
	s_waitcnt vmcnt(8)
	s_waitcnt lgkmcnt(0)
	s_barrier
	s_setprio 1
	s_waitcnt lgkmcnt(0)
	v_mfma_f32_16x16x32_bf16 v[124:127], v[128:131], v[188:191], v[124:127]
	v_mfma_f32_16x16x32_bf16 v[120:123], v[136:139], v[188:191], v[120:123]
	v_mfma_f32_16x16x32_bf16 v[108:111], v[128:131], v[208:211], v[108:111]
	v_mfma_f32_16x16x32_bf16 v[104:107], v[136:139], v[208:211], v[104:107]
	v_mfma_f32_16x16x32_bf16 v[92:95], v[128:131], v[216:219], v[92:95]
	v_mfma_f32_16x16x32_bf16 v[88:91], v[136:139], v[216:219], v[88:91]
	v_mfma_f32_16x16x32_bf16 v[76:79], v[128:131], v[224:227], v[76:79]
	v_mfma_f32_16x16x32_bf16 v[72:75], v[136:139], v[224:227], v[72:75]
	v_mfma_f32_16x16x32_bf16 v[124:127], v[132:135], v[204:207], v[124:127]
	v_mfma_f32_16x16x32_bf16 v[120:123], v[140:143], v[204:207], v[120:123]
	v_mfma_f32_16x16x32_bf16 v[108:111], v[132:135], v[212:215], v[108:111]
	v_mfma_f32_16x16x32_bf16 v[104:107], v[140:143], v[212:215], v[104:107]
	v_mfma_f32_16x16x32_bf16 v[92:95], v[132:135], v[220:223], v[92:95]
	v_mfma_f32_16x16x32_bf16 v[88:91], v[140:143], v[220:223], v[88:91]
	v_mfma_f32_16x16x32_bf16 v[76:79], v[132:135], v[228:231], v[76:79]
	v_mfma_f32_16x16x32_bf16 v[72:75], v[140:143], v[228:231], v[72:75]
	s_setprio 0
	s_setprio 1
	v_mfma_f32_16x16x32_bf16 v[116:119], v[144:147], v[188:191], v[116:119]
	v_mfma_f32_16x16x32_bf16 v[112:115], v[180:183], v[188:191], v[112:115]
	v_mfma_f32_16x16x32_bf16 v[100:103], v[144:147], v[208:211], v[100:103]
	v_mfma_f32_16x16x32_bf16 v[96:99], v[180:183], v[208:211], v[96:99]
	v_mfma_f32_16x16x32_bf16 v[84:87], v[144:147], v[216:219], v[84:87]
	v_mfma_f32_16x16x32_bf16 v[80:83], v[180:183], v[216:219], v[80:83]
	v_mfma_f32_16x16x32_bf16 v[68:71], v[144:147], v[224:227], v[68:71]
	v_mfma_f32_16x16x32_bf16 v[64:67], v[180:183], v[224:227], v[64:67]
	v_mfma_f32_16x16x32_bf16 v[116:119], v[148:151], v[204:207], v[116:119]
	v_mfma_f32_16x16x32_bf16 v[112:115], v[184:187], v[204:207], v[112:115]
	v_mfma_f32_16x16x32_bf16 v[100:103], v[148:151], v[212:215], v[100:103]
	v_mfma_f32_16x16x32_bf16 v[96:99], v[184:187], v[212:215], v[96:99]
	v_mfma_f32_16x16x32_bf16 v[84:87], v[148:151], v[220:223], v[84:87]
	v_mfma_f32_16x16x32_bf16 v[80:83], v[184:187], v[220:223], v[80:83]
	v_mfma_f32_16x16x32_bf16 v[68:71], v[148:151], v[228:231], v[68:71]
	v_mfma_f32_16x16x32_bf16 v[64:67], v[184:187], v[228:231], v[64:67]
	s_setprio 0
	s_barrier
; #define PG8_STAGE(bufoff, gbase, voff) do { _Pragma("unroll") for (int _i = 0; _i < 2; ++_i) \
;         __builtin_amdgcn_global_load_lds((const unsigned*)((const char*)(gbase) + (voff)[_i]), (LAS unsigned*)(lds + (bufoff) + ldsw + _i * 8192), 16, 0, 0); } while (0)
; #define PG8_LDA(dst, b, h) do { _Pragma("unroll") for (int m = 0; m < 4; ++m) _Pragma("unroll") for (int k = 0; k < 2; ++k) dst[m][k] = *(const LAS bf16x8*)(lds + PG8_SA(b, h) + aoff + m * 2048 + k * 1024); } while (0)
; #define PG8_LDB(dst, b, h) do { _Pragma("unroll") for (int n = 0; n < 2; ++n) _Pragma("unroll") for (int k = 0; k < 2; ++k) dst[n][k] = *(const LAS bf16x8*)(lds + PG8_SB(b, h) + boff + n * 2048 + k * 1024); } while (0)
; #define PG8_MMA(ai, bj, At, Bt) do { __builtin_amdgcn_s_setprio(1); _Pragma("unroll") for (int m = 0; m < 4; ++m) _Pragma("unroll") for (int n = 0; n < 2; ++n) _Pragma("unroll") for (int k = 0; k < 2; ++k) \
;         acc[ai][bj][m][n] = __builtin_amdgcn_mfma_f32_16x16x32_bf16(Bt[n][k], At[m][k], acc[ai][bj][m][n], 0, 0, 0); __builtin_amdgcn_s_setprio(0); } while (0)
; #define PG8_WAIT_V(n) asm volatile("s_waitcnt vmcnt(" #n ")" ::: "memory")
; #define PG8_WAIT_L(n) asm volatile("s_waitcnt lgkmcnt(" #n ")" ::: "memory")
; #define PG8_BAR __builtin_amdgcn_s_barrier()
; #define PG8_SCHED __builtin_amdgcn_sched_barrier(0)
; template <class Epi, class Sched>
; __device__ __forceinline__ void gemm_phase(const int tid, LAS unsigned char* lds, const Gemm g, const Sched& S, const Epi& E) {
;     ...
;         for (int t = 0; t < nt; t += 2) {
;             const bool last = (t == nt - 2);
;             const char* a1 = cA + (size_t)(t + 1) * kstep;
;             const char* a2 = last ? nA : cA + (size_t)(t + 2) * kstep; const char* b2 = last ? nB : cB + (size_t)(t + 2) * kstep;
;             const char* a3 = a2 + kstep; const char* b3 = b2 + kstep;
;             if (last && has_next) S.a_ready(nxt);
;             PG8_LDB(B0, 0, 0); PG8_LDB(B1, 0, 1); PG8_SCHED; PG8_LDA(At, 0, 0); PG8_STAGE(PG8_SA(1, 1), a1 + hstep, voffA);
;             PG8_WAIT_V(8); PG8_WAIT_L(0); PG8_BAR; PG8_MMA(0, 0, At, B0); PG8_MMA(0, 1, At, B1); PG8_BAR; PG8_SCHED;
;     ...
;             PG8_WAIT_V(8); PG8_WAIT_L(0); PG8_BAR; PG8_MMA(1, 0, At, B0); PG8_MMA(1, 1, At, B1); PG8_BAR; PG8_SCHED;
	s_add_i32 s28, s72, s56
	v_lshl_add_u64 v[232:233], v[232:233], 0, s[34:35]
	s_mov_b32 m0, s28
	ds_read_b128 v[188:191], v202 offset:49152
	ds_read_b128 v[204:207], v202 offset:50176
	ds_read_b128 v[208:211], v202 offset:51200
	ds_read_b128 v[212:215], v202 offset:52224
	ds_read_b128 v[216:219], v202 offset:53248
	ds_read_b128 v[220:223], v202 offset:54272
	ds_read_b128 v[224:227], v202 offset:55296
	ds_read_b128 v[228:231], v202 offset:56320
	global_load_lds_dwordx4 v[232:233], off
	s_add_i32 m0, s28, 0x2000
	s_add_u32 s26, s26, 0x80080
	v_lshl_add_u64 v[232:233], v[234:235], 0, s[34:35]
	s_addc_u32 s27, s27, 0
	s_add_i32 s28, s73, s56
	global_load_lds_dwordx4 v[232:233], off
	v_lshl_add_u64 v[232:233], s[26:27], 0, v[152:153]
	s_mov_b32 m0, s28
	s_nop 0
	global_load_lds_dwordx4 v[232:233], off
	v_lshl_add_u64 v[232:233], s[26:27], 0, v[174:175]
	s_add_i32 m0, s28, 0x2000
	s_nop 0
	global_load_lds_dwordx4 v[232:233], off
	v_lshl_add_u64 v[232:233], v[236:237], 0, s[34:35]
	s_mov_b32 m0, s64
	s_nop 0
	global_load_lds_dwordx4 v[232:233], off
	v_lshl_add_u64 v[232:233], v[238:239], 0, s[34:35]
	s_mov_b32 m0, s65
	s_nop 0
	global_load_lds_dwordx4 v[232:233], off
	s_waitcnt vmcnt(8)
	s_waitcnt lgkmcnt(0)
	s_barrier
	s_setprio 1
	s_waitcnt lgkmcnt(0)
	v_mfma_f32_16x16x32_bf16 v[60:63], v[128:131], v[188:191], v[60:63]
	v_mfma_f32_16x16x32_bf16 v[56:59], v[136:139], v[188:191], v[56:59]
	v_mfma_f32_16x16x32_bf16 v[44:47], v[128:131], v[208:211], v[44:47]
	v_mfma_f32_16x16x32_bf16 v[40:43], v[136:139], v[208:211], v[40:43]
	v_mfma_f32_16x16x32_bf16 v[28:31], v[128:131], v[216:219], v[28:31]
	v_mfma_f32_16x16x32_bf16 v[24:27], v[136:139], v[216:219], v[24:27]
	v_mfma_f32_16x16x32_bf16 v[12:15], v[128:131], v[224:227], v[12:15]
	v_mfma_f32_16x16x32_bf16 v[8:11], v[136:139], v[224:227], v[8:11]
	v_mfma_f32_16x16x32_bf16 v[60:63], v[132:135], v[204:207], v[60:63]
	v_mfma_f32_16x16x32_bf16 v[56:59], v[140:143], v[204:207], v[56:59]
	v_mfma_f32_16x16x32_bf16 v[44:47], v[132:135], v[212:215], v[44:47]
	v_mfma_f32_16x16x32_bf16 v[40:43], v[140:143], v[212:215], v[40:43]
	v_mfma_f32_16x16x32_bf16 v[28:31], v[132:135], v[220:223], v[28:31]
	v_mfma_f32_16x16x32_bf16 v[24:27], v[140:143], v[220:223], v[24:27]
	v_mfma_f32_16x16x32_bf16 v[12:15], v[132:135], v[228:231], v[12:15]
	v_mfma_f32_16x16x32_bf16 v[8:11], v[140:143], v[228:231], v[8:11]
	s_setprio 0
	s_setprio 1
	v_mfma_f32_16x16x32_bf16 v[52:55], v[144:147], v[188:191], v[52:55]
	v_mfma_f32_16x16x32_bf16 v[48:51], v[180:183], v[188:191], v[48:51]
	v_mfma_f32_16x16x32_bf16 v[36:39], v[144:147], v[208:211], v[36:39]
	v_mfma_f32_16x16x32_bf16 v[32:35], v[180:183], v[208:211], v[32:35]
	s_add_i32 s71, s71, 2
	s_add_u32 s24, s24, 0x100
	s_addc_u32 s25, s25, 0
	s_add_u32 s69, s69, 0x100
	s_addc_u32 s70, s70, 0
	v_mfma_f32_16x16x32_bf16 v[20:23], v[144:147], v[216:219], v[20:23]
	v_mfma_f32_16x16x32_bf16 v[16:19], v[180:183], v[216:219], v[16:19]
	v_mfma_f32_16x16x32_bf16 v[4:7], v[144:147], v[224:227], v[4:7]
	v_mfma_f32_16x16x32_bf16 v[0:3], v[180:183], v[224:227], v[0:3]
	v_mfma_f32_16x16x32_bf16 v[52:55], v[148:151], v[204:207], v[52:55]
	v_mfma_f32_16x16x32_bf16 v[48:51], v[184:187], v[204:207], v[48:51]
	v_mfma_f32_16x16x32_bf16 v[36:39], v[148:151], v[212:215], v[36:39]
	v_mfma_f32_16x16x32_bf16 v[32:35], v[184:187], v[212:215], v[32:35]
	v_mfma_f32_16x16x32_bf16 v[20:23], v[148:151], v[220:223], v[20:23]
	v_mfma_f32_16x16x32_bf16 v[16:19], v[184:187], v[220:223], v[16:19]
	v_mfma_f32_16x16x32_bf16 v[4:7], v[148:151], v[228:231], v[4:7]
	v_mfma_f32_16x16x32_bf16 v[0:3], v[184:187], v[228:231], v[0:3]
	s_setprio 0
	s_barrier
	s_cmp_gt_u32 s71, 29
.LBB0_550:
	s_add_u32 s26, s24, 0xfff80080
	s_addc_u32 s27, s25, -1
	s_add_i32 s72, 0, 0x10000
	s_cmp_eq_u32 s71, 28
	s_cselect_b32 s29, s5, s27
	s_cselect_b32 s28, s17, s26
	s_cselect_b32 s27, s15, s70
	s_cselect_b32 s26, s23, s69
	s_add_i32 s74, 0, 0x14000
	v_add_u32_e32 v140, s72, v201
	v_add_u32_e32 v184, s74, v201
	ds_read_b128 v[128:131], v140
	ds_read_b128 v[132:135], v140 offset:1024
	ds_read_b128 v[136:139], v140 offset:2048
	ds_read_b128 v[140:143], v140 offset:3072
	ds_read_b128 v[144:147], v184
	ds_read_b128 v[148:151], v184 offset:1024
	ds_read_b128 v[180:183], v184 offset:2048
	ds_read_b128 v[184:187], v184 offset:3072
	v_lshl_add_u64 v[232:233], s[24:25], 0, v[176:177]
	s_add_i32 m0, s57, 0xc000
	ds_read_b128 v[188:191], v202
	ds_read_b128 v[204:207], v202 offset:1024
	ds_read_b128 v[208:211], v202 offset:2048
	ds_read_b128 v[212:215], v202 offset:3072
	ds_read_b128 v[216:219], v202 offset:4096
	ds_read_b128 v[220:223], v202 offset:5120
	ds_read_b128 v[224:227], v202 offset:6144
	ds_read_b128 v[228:231], v202 offset:7168
	global_load_lds_dwordx4 v[232:233], off
	v_lshl_add_u64 v[232:233], s[24:25], 0, v[178:179]
	s_add_i32 m0, s57, 0xe000
	s_nop 0
	global_load_lds_dwordx4 v[232:233], off
	s_waitcnt vmcnt(8)
	s_waitcnt lgkmcnt(0)
	s_barrier
; #define PG8_STAGE(bufoff, gbase, voff) do { _Pragma("unroll") for (int _i = 0; _i < 2; ++_i) \
;         __builtin_amdgcn_global_load_lds((const unsigned*)((const char*)(gbase) + (voff)[_i]), (LAS unsigned*)(lds + (bufoff) + ldsw + _i * 8192), 16, 0, 0); } while (0)
; #define PG8_LDA(dst, b, h) do { _Pragma("unroll") for (int m = 0; m < 4; ++m) _Pragma("unroll") for (int k = 0; k < 2; ++k) dst[m][k] = *(const LAS bf16x8*)(lds + PG8_SA(b, h) + aoff + m * 2048 + k * 1024); } while (0)
; #define PG8_LDB(dst, b, h) do { _Pragma("unroll") for (int n = 0; n < 2; ++n) _Pragma("unroll") for (int k = 0; k < 2; ++k) dst[n][k] = *(const LAS bf16x8*)(lds + PG8_SB(b, h) + boff + n * 2048 + k * 1024); } while (0)
; #define PG8_MMA(ai, bj, At, Bt) do { __builtin_amdgcn_s_setprio(1); _Pragma("unroll") for (int m = 0; m < 4; ++m) _Pragma("unroll") for (int n = 0; n < 2; ++n) _Pragma("unroll") for (int k = 0; k < 2; ++k) \
;         acc[ai][bj][m][n] = __builtin_amdgcn_mfma_f32_16x16x32_bf16(Bt[n][k], At[m][k], acc[ai][bj][m][n], 0, 0, 0); __builtin_amdgcn_s_setprio(0); } while (0)
; #define PG8_WAIT_V(n) asm volatile("s_waitcnt vmcnt(" #n ")" ::: "memory")
; #define PG8_WAIT_L(n) asm volatile("s_waitcnt lgkmcnt(" #n ")" ::: "memory")
; #define PG8_BAR __builtin_amdgcn_s_barrier()
; #define PG8_SCHED __builtin_amdgcn_sched_barrier(0)
; template <class Epi, class Sched>
; __device__ __forceinline__ void gemm_phase(const int tid, LAS unsigned char* lds, const Gemm g, const Sched& S, const Epi& E) {
;     ...
;             PG8_WAIT_V(8); PG8_WAIT_L(0); PG8_BAR; PG8_MMA(0, 0, At, B0); PG8_MMA(0, 1, At, B1); PG8_BAR; PG8_SCHED;
;             PG8_LDA(At, 0, 1); PG8_STAGE(PG8_SB(0, 0), b2, voffB); PG8_STAGE(PG8_SB(0, 1), b2 + hstep, voffB); PG8_STAGE(PG8_SA(0, 0), a2, voffA);
;             PG8_WAIT_V(8); PG8_WAIT_L(0); PG8_BAR; PG8_MMA(1, 0, At, B0); PG8_MMA(1, 1, At, B1); PG8_BAR; PG8_SCHED;
;             PG8_LDB(B0, 1, 0); PG8_LDB(B1, 1, 1); PG8_SCHED; PG8_LDA(At, 1, 0); PG8_STAGE(PG8_SA(0, 1), a2 + hstep, voffA);
;             PG8_WAIT_V(8); PG8_WAIT_L(0); PG8_BAR; PG8_MMA(0, 0, At, B0); PG8_MMA(0, 1, At, B1); PG8_BAR; PG8_SCHED;
	s_setprio 1
	s_waitcnt lgkmcnt(0)
	v_mfma_f32_16x16x32_bf16 v[124:127], v[128:131], v[188:191], v[124:127]
	v_mfma_f32_16x16x32_bf16 v[120:123], v[136:139], v[188:191], v[120:123]
	v_mfma_f32_16x16x32_bf16 v[108:111], v[128:131], v[208:211], v[108:111]
	v_mfma_f32_16x16x32_bf16 v[104:107], v[136:139], v[208:211], v[104:107]
	v_mfma_f32_16x16x32_bf16 v[92:95], v[128:131], v[216:219], v[92:95]
	v_mfma_f32_16x16x32_bf16 v[88:91], v[136:139], v[216:219], v[88:91]
	v_mfma_f32_16x16x32_bf16 v[76:79], v[128:131], v[224:227], v[76:79]
	v_mfma_f32_16x16x32_bf16 v[72:75], v[136:139], v[224:227], v[72:75]
	v_mfma_f32_16x16x32_bf16 v[124:127], v[132:135], v[204:207], v[124:127]
	v_mfma_f32_16x16x32_bf16 v[120:123], v[140:143], v[204:207], v[120:123]
	v_mfma_f32_16x16x32_bf16 v[108:111], v[132:135], v[212:215], v[108:111]
	v_mfma_f32_16x16x32_bf16 v[104:107], v[140:143], v[212:215], v[104:107]
	v_mfma_f32_16x16x32_bf16 v[92:95], v[132:135], v[220:223], v[92:95]
	v_mfma_f32_16x16x32_bf16 v[88:91], v[140:143], v[220:223], v[88:91]
	v_mfma_f32_16x16x32_bf16 v[76:79], v[132:135], v[228:231], v[76:79]
	v_mfma_f32_16x16x32_bf16 v[72:75], v[140:143], v[228:231], v[72:75]
	s_setprio 0
	s_setprio 1
	v_mfma_f32_16x16x32_bf16 v[116:119], v[144:147], v[188:191], v[116:119]
	v_mfma_f32_16x16x32_bf16 v[112:115], v[180:183], v[188:191], v[112:115]
	v_mfma_f32_16x16x32_bf16 v[100:103], v[144:147], v[208:211], v[100:103]
	v_mfma_f32_16x16x32_bf16 v[96:99], v[180:183], v[208:211], v[96:99]
	v_mfma_f32_16x16x32_bf16 v[84:87], v[144:147], v[216:219], v[84:87]
	v_mfma_f32_16x16x32_bf16 v[80:83], v[180:183], v[216:219], v[80:83]
	v_mfma_f32_16x16x32_bf16 v[68:71], v[144:147], v[224:227], v[68:71]
	v_mfma_f32_16x16x32_bf16 v[64:67], v[180:183], v[224:227], v[64:67]
	v_mfma_f32_16x16x32_bf16 v[116:119], v[148:151], v[204:207], v[116:119]
	v_mfma_f32_16x16x32_bf16 v[112:115], v[184:187], v[204:207], v[112:115]
	v_mfma_f32_16x16x32_bf16 v[100:103], v[148:151], v[212:215], v[100:103]
	v_mfma_f32_16x16x32_bf16 v[96:99], v[184:187], v[212:215], v[96:99]
	v_mfma_f32_16x16x32_bf16 v[84:87], v[148:151], v[220:223], v[84:87]
	v_mfma_f32_16x16x32_bf16 v[80:83], v[184:187], v[220:223], v[80:83]
	v_mfma_f32_16x16x32_bf16 v[68:71], v[148:151], v[228:231], v[68:71]
	v_mfma_f32_16x16x32_bf16 v[64:67], v[184:187], v[228:231], v[64:67]
	s_setprio 0
	s_barrier
	s_add_i32 s72, s72, s56
	v_lshl_add_u64 v[232:233], s[26:27], 0, v[152:153]
	s_mov_b32 m0, s72
	ds_read_b128 v[188:191], v202 offset:16384
	ds_read_b128 v[204:207], v202 offset:17408
	ds_read_b128 v[208:211], v202 offset:18432
	ds_read_b128 v[212:215], v202 offset:19456
	ds_read_b128 v[216:219], v202 offset:20480
	ds_read_b128 v[220:223], v202 offset:21504
	ds_read_b128 v[224:227], v202 offset:22528
	ds_read_b128 v[228:231], v202 offset:23552
	global_load_lds_dwordx4 v[232:233], off
	s_add_i32 m0, s72, 0x2000
	s_add_u32 s72, s26, 0x80000
	v_lshl_add_u64 v[234:235], s[26:27], 0, v[174:175]
	s_addc_u32 s73, s27, 0
	s_add_i32 s74, s74, s56
	global_load_lds_dwordx4 v[234:235], off
	v_lshl_add_u64 v[236:237], s[72:73], 0, v[152:153]
	s_mov_b32 m0, s74
	v_lshl_add_u64 v[238:239], s[28:29], 0, v[172:173]
	global_load_lds_dwordx4 v[236:237], off
	v_lshl_add_u64 v[236:237], s[72:73], 0, v[174:175]
	s_add_i32 m0, s74, 0x2000
	s_nop 0
	global_load_lds_dwordx4 v[236:237], off
	v_lshl_add_u64 v[236:237], s[28:29], 0, v[170:171]
	s_mov_b32 m0, s57
	s_nop 0
	global_load_lds_dwordx4 v[236:237], off
	s_mov_b32 m0, s58
	s_nop 0
	global_load_lds_dwordx4 v[238:239], off
	s_waitcnt vmcnt(8)
	s_waitcnt lgkmcnt(0)
	s_barrier
	s_setprio 1
	s_waitcnt lgkmcnt(0)
	v_mfma_f32_16x16x32_bf16 v[60:63], v[128:131], v[188:191], v[60:63]
	v_mfma_f32_16x16x32_bf16 v[56:59], v[136:139], v[188:191], v[56:59]
	v_mfma_f32_16x16x32_bf16 v[44:47], v[128:131], v[208:211], v[44:47]
	v_mfma_f32_16x16x32_bf16 v[40:43], v[136:139], v[208:211], v[40:43]
	v_mfma_f32_16x16x32_bf16 v[28:31], v[128:131], v[216:219], v[28:31]
	v_mfma_f32_16x16x32_bf16 v[24:27], v[136:139], v[216:219], v[24:27]
	v_mfma_f32_16x16x32_bf16 v[12:15], v[128:131], v[224:227], v[12:15]
	v_mfma_f32_16x16x32_bf16 v[8:11], v[136:139], v[224:227], v[8:11]
	v_mfma_f32_16x16x32_bf16 v[60:63], v[132:135], v[204:207], v[60:63]
	v_mfma_f32_16x16x32_bf16 v[56:59], v[140:143], v[204:207], v[56:59]
	v_mfma_f32_16x16x32_bf16 v[44:47], v[132:135], v[212:215], v[44:47]
	v_mfma_f32_16x16x32_bf16 v[40:43], v[140:143], v[212:215], v[40:43]
	v_mfma_f32_16x16x32_bf16 v[28:31], v[132:135], v[220:223], v[28:31]
	v_mfma_f32_16x16x32_bf16 v[24:27], v[140:143], v[220:223], v[24:27]
	v_mfma_f32_16x16x32_bf16 v[12:15], v[132:135], v[228:231], v[12:15]
	v_mfma_f32_16x16x32_bf16 v[8:11], v[140:143], v[228:231], v[8:11]
	s_setprio 0
	s_setprio 1
	v_mfma_f32_16x16x32_bf16 v[52:55], v[144:147], v[188:191], v[52:55]
	v_mfma_f32_16x16x32_bf16 v[48:51], v[180:183], v[188:191], v[48:51]
	v_mfma_f32_16x16x32_bf16 v[36:39], v[144:147], v[208:211], v[36:39]
	v_mfma_f32_16x16x32_bf16 v[32:35], v[180:183], v[208:211], v[32:35]
	v_mfma_f32_16x16x32_bf16 v[20:23], v[144:147], v[216:219], v[20:23]
	v_mfma_f32_16x16x32_bf16 v[16:19], v[180:183], v[216:219], v[16:19]
	v_mfma_f32_16x16x32_bf16 v[4:7], v[144:147], v[224:227], v[4:7]
	v_mfma_f32_16x16x32_bf16 v[0:3], v[180:183], v[224:227], v[0:3]
	v_mfma_f32_16x16x32_bf16 v[52:55], v[148:151], v[204:207], v[52:55]
	v_mfma_f32_16x16x32_bf16 v[48:51], v[184:187], v[204:207], v[48:51]
	v_mfma_f32_16x16x32_bf16 v[36:39], v[148:151], v[212:215], v[36:39]
	v_mfma_f32_16x16x32_bf16 v[32:35], v[184:187], v[212:215], v[32:35]
	v_mfma_f32_16x16x32_bf16 v[20:23], v[148:151], v[220:223], v[20:23]
	v_mfma_f32_16x16x32_bf16 v[16:19], v[184:187], v[220:223], v[16:19]
	v_mfma_f32_16x16x32_bf16 v[4:7], v[148:151], v[228:231], v[4:7]
	v_mfma_f32_16x16x32_bf16 v[0:3], v[184:187], v[228:231], v[0:3]
	s_setprio 0
	s_barrier
; #define PG8_STAGE(bufoff, gbase, voff) do { _Pragma("unroll") for (int _i = 0; _i < 2; ++_i) \
;         __builtin_amdgcn_global_load_lds((const unsigned*)((const char*)(gbase) + (voff)[_i]), (LAS unsigned*)(lds + (bufoff) + ldsw + _i * 8192), 16, 0, 0); } while (0)
; #define PG8_LDA(dst, b, h) do { _Pragma("unroll") for (int m = 0; m < 4; ++m) _Pragma("unroll") for (int k = 0; k < 2; ++k) dst[m][k] = *(const LAS bf16x8*)(lds + PG8_SA(b, h) + aoff + m * 2048 + k * 1024); } while (0)
; #define PG8_MMA(ai, bj, At, Bt) do { __builtin_amdgcn_s_setprio(1); _Pragma("unroll") for (int m = 0; m < 4; ++m) _Pragma("unroll") for (int n = 0; n < 2; ++n) _Pragma("unroll") for (int k = 0; k < 2; ++k) \
;         acc[ai][bj][m][n] = __builtin_amdgcn_mfma_f32_16x16x32_bf16(Bt[n][k], At[m][k], acc[ai][bj][m][n], 0, 0, 0); __builtin_amdgcn_s_setprio(0); } while (0)
; #define PG8_WAIT_V(n) asm volatile("s_waitcnt vmcnt(" #n ")" ::: "memory")
; #define PG8_WAIT_L(n) asm volatile("s_waitcnt lgkmcnt(" #n ")" ::: "memory")
; #define PG8_BAR __builtin_amdgcn_s_barrier()
; #define PG8_SCHED __builtin_amdgcn_sched_barrier(0)
; template <class Epi, class Sched>
; __device__ __forceinline__ void gemm_phase(const int tid, LAS unsigned char* lds, const Gemm g, const Sched& S, const Epi& E) {
;     ...
;             PG8_LDA(At, 1, 1); PG8_STAGE(PG8_SB(1, 0), b3, voffB); PG8_STAGE(PG8_SB(1, 1), b3 + hstep, voffB); PG8_STAGE(PG8_SA(1, 0), a3, voffA);
;             PG8_WAIT_V(8); PG8_WAIT_L(0); PG8_BAR; PG8_MMA(1, 0, At, B0); PG8_MMA(1, 1, At, B1); PG8_BAR; PG8_SCHED;
	s_add_i32 s72, 0, 0x18000
	s_add_i32 s73, 0, 0x1c000
	v_add_u32_e32 v140, s72, v201
	v_add_u32_e32 v184, s73, v201
	ds_read_b128 v[128:131], v140
	ds_read_b128 v[132:135], v140 offset:1024
	ds_read_b128 v[136:139], v140 offset:2048
	ds_read_b128 v[140:143], v140 offset:3072
	ds_read_b128 v[144:147], v184
	ds_read_b128 v[148:151], v184 offset:1024
	ds_read_b128 v[180:183], v184 offset:2048
	ds_read_b128 v[184:187], v184 offset:3072
	s_add_u32 s28, s28, 0x80000
	s_addc_u32 s29, s29, 0
	s_mov_b32 m0, s59
	v_lshl_add_u64 v[240:241], s[28:29], 0, v[170:171]
	ds_read_b128 v[188:191], v202 offset:32768
	ds_read_b128 v[204:207], v202 offset:33792
	ds_read_b128 v[208:211], v202 offset:34816
	ds_read_b128 v[212:215], v202 offset:35840
	ds_read_b128 v[216:219], v202 offset:36864
	ds_read_b128 v[220:223], v202 offset:37888
	ds_read_b128 v[224:227], v202 offset:38912
	ds_read_b128 v[228:231], v202 offset:39936
	global_load_lds_dwordx4 v[240:241], off
	v_lshl_add_u64 v[240:241], s[28:29], 0, v[172:173]
	s_mov_b32 m0, s60
	s_nop 0
	global_load_lds_dwordx4 v[240:241], off
	s_waitcnt vmcnt(8)
	s_waitcnt lgkmcnt(0)
	s_barrier
	s_setprio 1
	s_waitcnt lgkmcnt(0)
	v_mfma_f32_16x16x32_bf16 v[124:127], v[128:131], v[188:191], v[124:127]
	v_mfma_f32_16x16x32_bf16 v[120:123], v[136:139], v[188:191], v[120:123]
	v_mfma_f32_16x16x32_bf16 v[108:111], v[128:131], v[208:211], v[108:111]
	v_mfma_f32_16x16x32_bf16 v[104:107], v[136:139], v[208:211], v[104:107]
	v_mfma_f32_16x16x32_bf16 v[92:95], v[128:131], v[216:219], v[92:95]
	v_mfma_f32_16x16x32_bf16 v[88:91], v[136:139], v[216:219], v[88:91]
	v_mfma_f32_16x16x32_bf16 v[76:79], v[128:131], v[224:227], v[76:79]
	v_mfma_f32_16x16x32_bf16 v[72:75], v[136:139], v[224:227], v[72:75]
	v_mfma_f32_16x16x32_bf16 v[124:127], v[132:135], v[204:207], v[124:127]
	v_mfma_f32_16x16x32_bf16 v[120:123], v[140:143], v[204:207], v[120:123]
	v_mfma_f32_16x16x32_bf16 v[108:111], v[132:135], v[212:215], v[108:111]
	v_mfma_f32_16x16x32_bf16 v[104:107], v[140:143], v[212:215], v[104:107]
	v_mfma_f32_16x16x32_bf16 v[92:95], v[132:135], v[220:223], v[92:95]
	v_mfma_f32_16x16x32_bf16 v[88:91], v[140:143], v[220:223], v[88:91]
	v_mfma_f32_16x16x32_bf16 v[76:79], v[132:135], v[228:231], v[76:79]
	v_mfma_f32_16x16x32_bf16 v[72:75], v[140:143], v[228:231], v[72:75]
	s_setprio 0
	s_setprio 1
	v_mfma_f32_16x16x32_bf16 v[116:119], v[144:147], v[188:191], v[116:119]
	v_mfma_f32_16x16x32_bf16 v[112:115], v[180:183], v[188:191], v[112:115]
	v_mfma_f32_16x16x32_bf16 v[100:103], v[144:147], v[208:211], v[100:103]
	v_mfma_f32_16x16x32_bf16 v[96:99], v[180:183], v[208:211], v[96:99]
	v_mfma_f32_16x16x32_bf16 v[84:87], v[144:147], v[216:219], v[84:87]
	v_mfma_f32_16x16x32_bf16 v[80:83], v[180:183], v[216:219], v[80:83]
	v_mfma_f32_16x16x32_bf16 v[68:71], v[144:147], v[224:227], v[68:71]
	v_mfma_f32_16x16x32_bf16 v[64:67], v[180:183], v[224:227], v[64:67]
	v_mfma_f32_16x16x32_bf16 v[116:119], v[148:151], v[204:207], v[116:119]
	v_mfma_f32_16x16x32_bf16 v[112:115], v[184:187], v[204:207], v[112:115]
	v_mfma_f32_16x16x32_bf16 v[100:103], v[148:151], v[212:215], v[100:103]
	v_mfma_f32_16x16x32_bf16 v[96:99], v[184:187], v[212:215], v[96:99]
	v_mfma_f32_16x16x32_bf16 v[84:87], v[148:151], v[220:223], v[84:87]
	v_mfma_f32_16x16x32_bf16 v[80:83], v[184:187], v[220:223], v[80:83]
	v_mfma_f32_16x16x32_bf16 v[68:71], v[148:151], v[228:231], v[68:71]
	v_mfma_f32_16x16x32_bf16 v[64:67], v[184:187], v[228:231], v[64:67]
	s_setprio 0
	s_barrier
; #define PG8_STAGE(bufoff, gbase, voff) do { _Pragma("unroll") for (int _i = 0; _i < 2; ++_i) \
;         __builtin_amdgcn_global_load_lds((const unsigned*)((const char*)(gbase) + (voff)[_i]), (LAS unsigned*)(lds + (bufoff) + ldsw + _i * 8192), 16, 0, 0); } while (0)
; #define PG8_LDA(dst, b, h) do { _Pragma("unroll") for (int m = 0; m < 4; ++m) _Pragma("unroll") for (int k = 0; k < 2; ++k) dst[m][k] = *(const LAS bf16x8*)(lds + PG8_SA(b, h) + aoff + m * 2048 + k * 1024); } while (0)
; #define PG8_LDB(dst, b, h) do { _Pragma("unroll") for (int n = 0; n < 2; ++n) _Pragma("unroll") for (int k = 0; k < 2; ++k) dst[n][k] = *(const LAS bf16x8*)(lds + PG8_SB(b, h) + boff + n * 2048 + k * 1024); } while (0)
; #define PG8_MMA(ai, bj, At, Bt) do { __builtin_amdgcn_s_setprio(1); _Pragma("unroll") for (int m = 0; m < 4; ++m) _Pragma("unroll") for (int n = 0; n < 2; ++n) _Pragma("unroll") for (int k = 0; k < 2; ++k) \
;         acc[ai][bj][m][n] = __builtin_amdgcn_mfma_f32_16x16x32_bf16(Bt[n][k], At[m][k], acc[ai][bj][m][n], 0, 0, 0); __builtin_amdgcn_s_setprio(0); } while (0)
; #define PG8_WAIT_V(n) asm volatile("s_waitcnt vmcnt(" #n ")" ::: "memory")
; #define PG8_WAIT_L(n) asm volatile("s_waitcnt lgkmcnt(" #n ")" ::: "memory")
; #define PG8_BAR __builtin_amdgcn_s_barrier()
; #define PG8_SCHED __builtin_amdgcn_sched_barrier(0)
; template <class Epi, class Sched>
; __device__ __forceinline__ void gemm_phase(const int tid, LAS unsigned char* lds, const Gemm g, const Sched& S, const Epi& E) {
;     ...
;             PG8_LDB(B0, 1, 0); PG8_LDB(B1, 1, 1); PG8_SCHED; PG8_LDA(At, 1, 0); PG8_STAGE(PG8_SA(0, 1), a2 + hstep, voffA);
;             PG8_WAIT_V(8); PG8_WAIT_L(0); PG8_BAR; PG8_MMA(0, 0, At, B0); PG8_MMA(0, 1, At, B1); PG8_BAR; PG8_SCHED;
;             PG8_LDA(At, 1, 1); PG8_STAGE(PG8_SB(1, 0), b3, voffB); PG8_STAGE(PG8_SB(1, 1), b3 + hstep, voffB); PG8_STAGE(PG8_SA(1, 0), a3, voffA);
;             PG8_WAIT_V(8); PG8_WAIT_L(0); PG8_BAR; PG8_MMA(1, 0, At, B0); PG8_MMA(1, 1, At, B1); PG8_BAR; PG8_SCHED;
;         }
;         if (wr == 0) PG8_BAR;
	s_add_i32 s28, s72, s56
	v_lshl_add_u64 v[232:233], v[232:233], 0, s[34:35]
	s_mov_b32 m0, s28
	ds_read_b128 v[188:191], v202 offset:49152
	ds_read_b128 v[204:207], v202 offset:50176
	ds_read_b128 v[208:211], v202 offset:51200
	ds_read_b128 v[212:215], v202 offset:52224
	ds_read_b128 v[216:219], v202 offset:53248
	ds_read_b128 v[220:223], v202 offset:54272
	ds_read_b128 v[224:227], v202 offset:55296
	ds_read_b128 v[228:231], v202 offset:56320
	global_load_lds_dwordx4 v[232:233], off
	s_add_i32 m0, s28, 0x2000
	s_add_u32 s26, s26, 0x80080
	v_lshl_add_u64 v[232:233], v[234:235], 0, s[34:35]
	s_addc_u32 s27, s27, 0
	s_add_i32 s28, s73, s56
	global_load_lds_dwordx4 v[232:233], off
	v_lshl_add_u64 v[232:233], s[26:27], 0, v[152:153]
	s_mov_b32 m0, s28
	s_nop 0
	global_load_lds_dwordx4 v[232:233], off
	v_lshl_add_u64 v[232:233], s[26:27], 0, v[174:175]
	s_add_i32 m0, s28, 0x2000
	s_nop 0
	global_load_lds_dwordx4 v[232:233], off
	v_lshl_add_u64 v[232:233], v[236:237], 0, s[34:35]
	s_mov_b32 m0, s64
	s_nop 0
	global_load_lds_dwordx4 v[232:233], off
	v_lshl_add_u64 v[232:233], v[238:239], 0, s[34:35]
	s_mov_b32 m0, s65
	s_nop 0
	global_load_lds_dwordx4 v[232:233], off
	s_waitcnt vmcnt(8)
	s_waitcnt lgkmcnt(0)
	s_barrier
	s_setprio 1
	s_waitcnt lgkmcnt(0)
	v_mfma_f32_16x16x32_bf16 v[60:63], v[128:131], v[188:191], v[60:63]
	v_mfma_f32_16x16x32_bf16 v[56:59], v[136:139], v[188:191], v[56:59]
	v_mfma_f32_16x16x32_bf16 v[44:47], v[128:131], v[208:211], v[44:47]
	v_mfma_f32_16x16x32_bf16 v[40:43], v[136:139], v[208:211], v[40:43]
	v_mfma_f32_16x16x32_bf16 v[28:31], v[128:131], v[216:219], v[28:31]
	v_mfma_f32_16x16x32_bf16 v[24:27], v[136:139], v[216:219], v[24:27]
	v_mfma_f32_16x16x32_bf16 v[12:15], v[128:131], v[224:227], v[12:15]
	v_mfma_f32_16x16x32_bf16 v[8:11], v[136:139], v[224:227], v[8:11]
	v_mfma_f32_16x16x32_bf16 v[60:63], v[132:135], v[204:207], v[60:63]
	v_mfma_f32_16x16x32_bf16 v[56:59], v[140:143], v[204:207], v[56:59]
	v_mfma_f32_16x16x32_bf16 v[44:47], v[132:135], v[212:215], v[44:47]
	v_mfma_f32_16x16x32_bf16 v[40:43], v[140:143], v[212:215], v[40:43]
	v_mfma_f32_16x16x32_bf16 v[28:31], v[132:135], v[220:223], v[28:31]
	v_mfma_f32_16x16x32_bf16 v[24:27], v[140:143], v[220:223], v[24:27]
	v_mfma_f32_16x16x32_bf16 v[12:15], v[132:135], v[228:231], v[12:15]
	v_mfma_f32_16x16x32_bf16 v[8:11], v[140:143], v[228:231], v[8:11]
	s_setprio 0
	s_setprio 1
	v_mfma_f32_16x16x32_bf16 v[52:55], v[144:147], v[188:191], v[52:55]
	v_mfma_f32_16x16x32_bf16 v[48:51], v[180:183], v[188:191], v[48:51]
	v_mfma_f32_16x16x32_bf16 v[36:39], v[144:147], v[208:211], v[36:39]
	v_mfma_f32_16x16x32_bf16 v[32:35], v[180:183], v[208:211], v[32:35]
	s_add_i32 s71, s71, 2
	s_add_u32 s24, s24, 0x100
	s_addc_u32 s25, s25, 0
	s_add_u32 s69, s69, 0x100
	s_addc_u32 s70, s70, 0
	v_mfma_f32_16x16x32_bf16 v[20:23], v[144:147], v[216:219], v[20:23]
	v_mfma_f32_16x16x32_bf16 v[16:19], v[180:183], v[216:219], v[16:19]
	v_mfma_f32_16x16x32_bf16 v[4:7], v[144:147], v[224:227], v[4:7]
	v_mfma_f32_16x16x32_bf16 v[0:3], v[180:183], v[224:227], v[0:3]
	v_mfma_f32_16x16x32_bf16 v[52:55], v[148:151], v[204:207], v[52:55]
	v_mfma_f32_16x16x32_bf16 v[48:51], v[184:187], v[204:207], v[48:51]
	v_mfma_f32_16x16x32_bf16 v[36:39], v[148:151], v[212:215], v[36:39]
	v_mfma_f32_16x16x32_bf16 v[32:35], v[184:187], v[212:215], v[32:35]
	v_mfma_f32_16x16x32_bf16 v[20:23], v[148:151], v[220:223], v[20:23]
	v_mfma_f32_16x16x32_bf16 v[16:19], v[184:187], v[220:223], v[16:19]
	v_mfma_f32_16x16x32_bf16 v[4:7], v[148:151], v[228:231], v[4:7]
	v_mfma_f32_16x16x32_bf16 v[0:3], v[184:187], v[228:231], v[0:3]
	s_setprio 0
	s_barrier
	s_cmp_gt_u32 s71, 29
	s_cbranch_scc0 .LBB0_550
	s_and_b64 vcc, exec, s[12:13]
	s_cbranch_vccz .LBB0_553
	s_barrier

; #define PG8_STAGE(bufoff, gbase, voff) do { _Pragma("unroll") for (int _i = 0; _i < 2; ++_i) \
;         __builtin_amdgcn_global_load_lds((const unsigned*)((const char*)(gbase) + (voff)[_i]), (LAS unsigned*)(lds + (bufoff) + ldsw + _i * 8192), 16, 0, 0); } while (0)
; #define PG8_LDA(dst, b, h) do { _Pragma("unroll") for (int m = 0; m < 4; ++m) _Pragma("unroll") for (int k = 0; k < 2; ++k) dst[m][k] = *(const LAS bf16x8*)(lds + PG8_SA(b, h) + aoff + m * 2048 + k * 1024); } while (0)
; #define PG8_LDB(dst, b, h) do { _Pragma("unroll") for (int n = 0; n < 2; ++n) _Pragma("unroll") for (int k = 0; k < 2; ++k) dst[n][k] = *(const LAS bf16x8*)(lds + PG8_SB(b, h) + boff + n * 2048 + k * 1024); } while (0)
; #define PG8_MMA(ai, bj, At, Bt) do { __builtin_amdgcn_s_setprio(1); _Pragma("unroll") for (int m = 0; m < 4; ++m) _Pragma("unroll") for (int n = 0; n < 2; ++n) _Pragma("unroll") for (int k = 0; k < 2; ++k) \
;         acc[ai][bj][m][n] = __builtin_amdgcn_mfma_f32_16x16x32_bf16(Bt[n][k], At[m][k], acc[ai][bj][m][n], 0, 0, 0); __builtin_amdgcn_s_setprio(0); } while (0)
; #define PG8_BAR __builtin_amdgcn_s_barrier()
; template <class Epi, class Sched>
; __device__ __forceinline__ void gemm_phase(const int tid, LAS unsigned char* lds, const Gemm g, const Sched& S, const Epi& E) {
;     ...
;         const char* nA = has_next ? (const char*)g.A + (size_t)nxt.pm * tstep : cA; const char* nB = has_next ? (const char*)g.Bt + (size_t)nxt.pn * tstep : cB;
;         for (int t = 0; t < nt; t += 2) {
;             const bool last = (t == nt - 2);
;             const char* a1 = cA + (size_t)(t + 1) * kstep;
;             const char* a2 = last ? nA : cA + (size_t)(t + 2) * kstep; const char* b2 = last ? nB : cB + (size_t)(t + 2) * kstep;
;             const char* a3 = a2 + kstep; const char* b3 = b2 + kstep;
;             if (last && has_next) S.a_ready(nxt);
;             PG8_LDB(B0, 0, 0); PG8_LDB(B1, 0, 1); PG8_SCHED; PG8_LDA(At, 0, 0); PG8_STAGE(PG8_SA(1, 1), a1 + hstep, voffA);
;             PG8_WAIT_V(8); PG8_WAIT_L(0); PG8_BAR; PG8_MMA(0, 0, At, B0); PG8_MMA(0, 1, At, B1); PG8_BAR; PG8_SCHED;
;             PG8_LDA(At, 0, 1); PG8_STAGE(PG8_SB(0, 0), b2, voffB); PG8_STAGE(PG8_SB(0, 1), b2 + hstep, voffB); PG8_STAGE(PG8_SA(0, 0), a2, voffA);
;             PG8_WAIT_V(8); PG8_WAIT_L(0); PG8_BAR; PG8_MMA(1, 0, At, B0); PG8_MMA(1, 1, At, B1); PG8_BAR; PG8_SCHED;
.LBB0_669:
	s_ashr_i32 s15, s14, 31
	s_lshl_b64 s[16:17], s[14:15], 20
	s_add_u32 s16, s56, s16
	s_addc_u32 s17, s57, s17
	s_and_b64 s[18:19], s[0:1], exec
	s_cselect_b32 s15, s17, s87
	s_cselect_b32 s68, s16, s86
	s_ashr_i32 s13, s12, 31
	s_lshl_b64 s[18:19], s[12:13], 20
	s_add_u32 s18, s41, s18
	s_addc_u32 s19, s55, s19
	s_and_b64 s[90:91], s[0:1], exec
	s_cselect_b32 s13, s19, s89
	s_cselect_b32 s69, s18, s88
	s_waitcnt vmcnt(8)
	s_waitcnt lgkmcnt(0)
	s_barrier
	s_setprio 1
	s_waitcnt lgkmcnt(0)
	v_mfma_f32_16x16x32_bf16 v[124:127], v[138:141], v[200:203], 0
	v_mfma_f32_16x16x32_bf16 v[116:119], v[146:149], v[200:203], 0
	v_mfma_f32_16x16x32_bf16 v[108:111], v[138:141], v[208:211], 0
	v_mfma_f32_16x16x32_bf16 v[100:103], v[146:149], v[208:211], 0
	v_mfma_f32_16x16x32_bf16 v[92:95], v[138:141], v[216:219], 0
	v_mfma_f32_16x16x32_bf16 v[84:87], v[146:149], v[216:219], 0
	v_mfma_f32_16x16x32_bf16 v[76:79], v[138:141], v[224:227], 0
	v_mfma_f32_16x16x32_bf16 v[68:71], v[146:149], v[224:227], 0
	v_mfma_f32_16x16x32_bf16 v[124:127], v[142:145], v[204:207], v[124:127]
	v_mfma_f32_16x16x32_bf16 v[116:119], v[172:175], v[204:207], v[116:119]
	v_mfma_f32_16x16x32_bf16 v[108:111], v[142:145], v[212:215], v[108:111]
	v_mfma_f32_16x16x32_bf16 v[100:103], v[172:175], v[212:215], v[100:103]
	v_mfma_f32_16x16x32_bf16 v[92:95], v[142:145], v[220:223], v[92:95]
	v_mfma_f32_16x16x32_bf16 v[84:87], v[172:175], v[220:223], v[84:87]
	v_mfma_f32_16x16x32_bf16 v[76:79], v[142:145], v[228:231], v[76:79]
	v_mfma_f32_16x16x32_bf16 v[68:71], v[172:175], v[228:231], v[68:71]
	s_setprio 0
	s_setprio 1
	v_mfma_f32_16x16x32_bf16 v[120:123], v[176:179], v[200:203], 0
	v_mfma_f32_16x16x32_bf16 v[112:115], v[184:187], v[200:203], 0
	v_mfma_f32_16x16x32_bf16 v[104:107], v[176:179], v[208:211], 0
	v_mfma_f32_16x16x32_bf16 v[96:99], v[184:187], v[208:211], 0
	v_mfma_f32_16x16x32_bf16 v[88:91], v[176:179], v[216:219], 0
	v_mfma_f32_16x16x32_bf16 v[80:83], v[184:187], v[216:219], 0
	v_mfma_f32_16x16x32_bf16 v[72:75], v[176:179], v[224:227], 0
	v_mfma_f32_16x16x32_bf16 v[64:67], v[184:187], v[224:227], 0
	v_mfma_f32_16x16x32_bf16 v[120:123], v[180:183], v[204:207], v[120:123]
	v_mfma_f32_16x16x32_bf16 v[112:115], v[188:191], v[204:207], v[112:115]
	v_mfma_f32_16x16x32_bf16 v[104:107], v[180:183], v[212:215], v[104:107]
	v_mfma_f32_16x16x32_bf16 v[96:99], v[188:191], v[212:215], v[96:99]
	v_mfma_f32_16x16x32_bf16 v[88:91], v[180:183], v[220:223], v[88:91]
	v_mfma_f32_16x16x32_bf16 v[80:83], v[188:191], v[220:223], v[80:83]
	v_mfma_f32_16x16x32_bf16 v[72:75], v[180:183], v[228:231], v[72:75]
	v_mfma_f32_16x16x32_bf16 v[64:67], v[188:191], v[228:231], v[64:67]
	s_setprio 0
	s_barrier
	s_add_i32 s73, s73, s40
	v_lshl_add_u64 v[232:233], s[24:25], 0, v[152:153]
	s_mov_b32 m0, s73
	ds_read_b128 v[200:203], v171 offset:16384
	ds_read_b128 v[204:207], v171 offset:17408
	ds_read_b128 v[208:211], v171 offset:18432
	ds_read_b128 v[212:215], v171 offset:19456
	ds_read_b128 v[216:219], v171 offset:20480
	ds_read_b128 v[220:223], v171 offset:21504
	ds_read_b128 v[224:227], v171 offset:22528
	ds_read_b128 v[228:231], v171 offset:23552
	global_load_lds_dwordx4 v[232:233], off
	s_add_i32 m0, s73, 0x2000
	s_add_u32 s74, s24, 0x80000
	v_lshl_add_u64 v[234:235], s[24:25], 0, v[128:129]
	s_addc_u32 s75, s25, 0
	s_add_i32 s73, s76, s40
	global_load_lds_dwordx4 v[234:235], off
	v_lshl_add_u64 v[236:237], s[74:75], 0, v[152:153]
	s_mov_b32 m0, s73
	v_lshl_add_u64 v[238:239], s[26:27], 0, v[130:131]
	global_load_lds_dwordx4 v[236:237], off
	v_lshl_add_u64 v[236:237], s[74:75], 0, v[128:129]
	s_add_i32 m0, s73, 0x2000
	s_nop 0
	global_load_lds_dwordx4 v[236:237], off
	v_lshl_add_u64 v[236:237], s[26:27], 0, v[132:133]
	s_mov_b32 m0, s58
	s_nop 0
	global_load_lds_dwordx4 v[236:237], off
	s_mov_b32 m0, s59
	s_nop 0
	global_load_lds_dwordx4 v[238:239], off
	s_waitcnt vmcnt(8)
	s_waitcnt lgkmcnt(0)
	s_barrier
	s_setprio 1
	s_waitcnt lgkmcnt(0)
	v_mfma_f32_16x16x32_bf16 v[60:63], v[138:141], v[200:203], 0
	v_mfma_f32_16x16x32_bf16 v[52:55], v[146:149], v[200:203], 0
	v_mfma_f32_16x16x32_bf16 v[44:47], v[138:141], v[208:211], 0
	v_mfma_f32_16x16x32_bf16 v[36:39], v[146:149], v[208:211], 0
	v_mfma_f32_16x16x32_bf16 v[28:31], v[138:141], v[216:219], 0
	v_mfma_f32_16x16x32_bf16 v[20:23], v[146:149], v[216:219], 0
	v_mfma_f32_16x16x32_bf16 v[12:15], v[138:141], v[224:227], 0
	v_mfma_f32_16x16x32_bf16 v[4:7], v[146:149], v[224:227], 0
	v_mfma_f32_16x16x32_bf16 v[60:63], v[142:145], v[204:207], v[60:63]
	v_mfma_f32_16x16x32_bf16 v[52:55], v[172:175], v[204:207], v[52:55]
	v_mfma_f32_16x16x32_bf16 v[44:47], v[142:145], v[212:215], v[44:47]
	v_mfma_f32_16x16x32_bf16 v[36:39], v[172:175], v[212:215], v[36:39]
	v_mfma_f32_16x16x32_bf16 v[28:31], v[142:145], v[220:223], v[28:31]
	v_mfma_f32_16x16x32_bf16 v[20:23], v[172:175], v[220:223], v[20:23]
	v_mfma_f32_16x16x32_bf16 v[12:15], v[142:145], v[228:231], v[12:15]
	v_mfma_f32_16x16x32_bf16 v[4:7], v[172:175], v[228:231], v[4:7]
	s_setprio 0
	s_setprio 1
	v_mfma_f32_16x16x32_bf16 v[56:59], v[176:179], v[200:203], 0
	v_mfma_f32_16x16x32_bf16 v[48:51], v[184:187], v[200:203], 0
	v_mfma_f32_16x16x32_bf16 v[40:43], v[176:179], v[208:211], 0
	v_mfma_f32_16x16x32_bf16 v[32:35], v[184:187], v[208:211], 0
	v_mfma_f32_16x16x32_bf16 v[24:27], v[176:179], v[216:219], 0
	v_mfma_f32_16x16x32_bf16 v[16:19], v[184:187], v[216:219], 0
	v_mfma_f32_16x16x32_bf16 v[8:11], v[176:179], v[224:227], 0
	v_mfma_f32_16x16x32_bf16 v[0:3], v[184:187], v[224:227], 0
	v_mfma_f32_16x16x32_bf16 v[56:59], v[180:183], v[204:207], v[56:59]
	v_mfma_f32_16x16x32_bf16 v[48:51], v[188:191], v[204:207], v[48:51]
	v_mfma_f32_16x16x32_bf16 v[40:43], v[180:183], v[212:215], v[40:43]
	v_mfma_f32_16x16x32_bf16 v[32:35], v[188:191], v[212:215], v[32:35]
	v_mfma_f32_16x16x32_bf16 v[24:27], v[180:183], v[220:223], v[24:27]
	v_mfma_f32_16x16x32_bf16 v[16:19], v[188:191], v[220:223], v[16:19]
	v_mfma_f32_16x16x32_bf16 v[8:11], v[180:183], v[228:231], v[8:11]
	v_mfma_f32_16x16x32_bf16 v[0:3], v[188:191], v[228:231], v[0:3]
	s_setprio 0
	s_barrier
; #define PG8_STAGE(bufoff, gbase, voff) do { _Pragma("unroll") for (int _i = 0; _i < 2; ++_i) \
;         __builtin_amdgcn_global_load_lds((const unsigned*)((const char*)(gbase) + (voff)[_i]), (LAS unsigned*)(lds + (bufoff) + ldsw + _i * 8192), 16, 0, 0); } while (0)
; #define PG8_LDA(dst, b, h) do { _Pragma("unroll") for (int m = 0; m < 4; ++m) _Pragma("unroll") for (int k = 0; k < 2; ++k) dst[m][k] = *(const LAS bf16x8*)(lds + PG8_SA(b, h) + aoff + m * 2048 + k * 1024); } while (0)
; #define PG8_LDB(dst, b, h) do { _Pragma("unroll") for (int n = 0; n < 2; ++n) _Pragma("unroll") for (int k = 0; k < 2; ++k) dst[n][k] = *(const LAS bf16x8*)(lds + PG8_SB(b, h) + boff + n * 2048 + k * 1024); } while (0)
; #define PG8_MMA(ai, bj, At, Bt) do { __builtin_amdgcn_s_setprio(1); _Pragma("unroll") for (int m = 0; m < 4; ++m) _Pragma("unroll") for (int n = 0; n < 2; ++n) _Pragma("unroll") for (int k = 0; k < 2; ++k) \
;         acc[ai][bj][m][n] = __builtin_amdgcn_mfma_f32_16x16x32_bf16(Bt[n][k], At[m][k], acc[ai][bj][m][n], 0, 0, 0); __builtin_amdgcn_s_setprio(0); } while (0)
; #define PG8_WAIT_V(n) asm volatile("s_waitcnt vmcnt(" #n ")" ::: "memory")
; #define PG8_WAIT_L(n) asm volatile("s_waitcnt lgkmcnt(" #n ")" ::: "memory")
; #define PG8_BAR __builtin_amdgcn_s_barrier()
; #define PG8_SCHED __builtin_amdgcn_sched_barrier(0)
; template <class Epi, class Sched>
; __device__ __forceinline__ void gemm_phase(const int tid, LAS unsigned char* lds, const Gemm g, const Sched& S, const Epi& E) {
;     ...
;             PG8_LDB(B0, 1, 0); PG8_LDB(B1, 1, 1); PG8_SCHED; PG8_LDA(At, 1, 0); PG8_STAGE(PG8_SA(0, 1), a2 + hstep, voffA);
;             PG8_WAIT_V(8); PG8_WAIT_L(0); PG8_BAR; PG8_MMA(0, 0, At, B0); PG8_MMA(0, 1, At, B1); PG8_BAR; PG8_SCHED;
;             PG8_LDA(At, 1, 1); PG8_STAGE(PG8_SB(1, 0), b3, voffB); PG8_STAGE(PG8_SB(1, 1), b3 + hstep, voffB); PG8_STAGE(PG8_SA(1, 0), a3, voffA);
;             PG8_WAIT_V(8); PG8_WAIT_L(0); PG8_BAR; PG8_MMA(1, 0, At, B0); PG8_MMA(1, 1, At, B1); PG8_BAR; PG8_SCHED;
	s_add_i32 s73, 0, 0x18000
	s_add_i32 s74, 0, 0x1c000
	v_add_u32_e32 v172, s73, v170
	v_add_u32_e32 v188, s74, v170
	ds_read_b128 v[138:141], v172
	ds_read_b128 v[142:145], v172 offset:1024
	ds_read_b128 v[146:149], v172 offset:2048
	ds_read_b128 v[172:175], v172 offset:3072
	ds_read_b128 v[176:179], v188
	ds_read_b128 v[180:183], v188 offset:1024
	ds_read_b128 v[184:187], v188 offset:2048
	ds_read_b128 v[188:191], v188 offset:3072
	s_add_u32 s26, s26, 0x80000
	s_addc_u32 s27, s27, 0
	s_mov_b32 m0, s60
	v_lshl_add_u64 v[240:241], s[26:27], 0, v[132:133]
	ds_read_b128 v[200:203], v171 offset:32768
	ds_read_b128 v[204:207], v171 offset:33792
	ds_read_b128 v[208:211], v171 offset:34816
	ds_read_b128 v[212:215], v171 offset:35840
	ds_read_b128 v[216:219], v171 offset:36864
	ds_read_b128 v[220:223], v171 offset:37888
	ds_read_b128 v[224:227], v171 offset:38912
	ds_read_b128 v[228:231], v171 offset:39936
	global_load_lds_dwordx4 v[240:241], off
	v_lshl_add_u64 v[240:241], s[26:27], 0, v[130:131]
	s_mov_b32 m0, s61
	s_nop 0
	global_load_lds_dwordx4 v[240:241], off
	s_waitcnt vmcnt(8)
	s_waitcnt lgkmcnt(0)
	s_barrier
	s_setprio 1
	s_waitcnt lgkmcnt(0)
	v_mfma_f32_16x16x32_bf16 v[124:127], v[138:141], v[200:203], v[124:127]
	v_mfma_f32_16x16x32_bf16 v[116:119], v[146:149], v[200:203], v[116:119]
	v_mfma_f32_16x16x32_bf16 v[108:111], v[138:141], v[208:211], v[108:111]
	v_mfma_f32_16x16x32_bf16 v[100:103], v[146:149], v[208:211], v[100:103]
	v_mfma_f32_16x16x32_bf16 v[92:95], v[138:141], v[216:219], v[92:95]
	v_mfma_f32_16x16x32_bf16 v[84:87], v[146:149], v[216:219], v[84:87]
	v_mfma_f32_16x16x32_bf16 v[76:79], v[138:141], v[224:227], v[76:79]
	v_mfma_f32_16x16x32_bf16 v[68:71], v[146:149], v[224:227], v[68:71]
	v_mfma_f32_16x16x32_bf16 v[124:127], v[142:145], v[204:207], v[124:127]
	v_mfma_f32_16x16x32_bf16 v[116:119], v[172:175], v[204:207], v[116:119]
	v_mfma_f32_16x16x32_bf16 v[108:111], v[142:145], v[212:215], v[108:111]
	v_mfma_f32_16x16x32_bf16 v[100:103], v[172:175], v[212:215], v[100:103]
	v_mfma_f32_16x16x32_bf16 v[92:95], v[142:145], v[220:223], v[92:95]
	v_mfma_f32_16x16x32_bf16 v[84:87], v[172:175], v[220:223], v[84:87]
	v_mfma_f32_16x16x32_bf16 v[76:79], v[142:145], v[228:231], v[76:79]
	v_mfma_f32_16x16x32_bf16 v[68:71], v[172:175], v[228:231], v[68:71]
	s_setprio 0
	s_setprio 1
	v_mfma_f32_16x16x32_bf16 v[120:123], v[176:179], v[200:203], v[120:123]
	v_mfma_f32_16x16x32_bf16 v[112:115], v[184:187], v[200:203], v[112:115]
	v_mfma_f32_16x16x32_bf16 v[104:107], v[176:179], v[208:211], v[104:107]
	v_mfma_f32_16x16x32_bf16 v[96:99], v[184:187], v[208:211], v[96:99]
	v_mfma_f32_16x16x32_bf16 v[88:91], v[176:179], v[216:219], v[88:91]
	v_mfma_f32_16x16x32_bf16 v[80:83], v[184:187], v[216:219], v[80:83]
	v_mfma_f32_16x16x32_bf16 v[72:75], v[176:179], v[224:227], v[72:75]
	v_mfma_f32_16x16x32_bf16 v[64:67], v[184:187], v[224:227], v[64:67]
	v_mfma_f32_16x16x32_bf16 v[120:123], v[180:183], v[204:207], v[120:123]
	v_mfma_f32_16x16x32_bf16 v[112:115], v[188:191], v[204:207], v[112:115]
	v_mfma_f32_16x16x32_bf16 v[104:107], v[180:183], v[212:215], v[104:107]
	v_mfma_f32_16x16x32_bf16 v[96:99], v[188:191], v[212:215], v[96:99]
	v_mfma_f32_16x16x32_bf16 v[88:91], v[180:183], v[220:223], v[88:91]
	v_mfma_f32_16x16x32_bf16 v[80:83], v[188:191], v[220:223], v[80:83]
	v_mfma_f32_16x16x32_bf16 v[72:75], v[180:183], v[228:231], v[72:75]
	v_mfma_f32_16x16x32_bf16 v[64:67], v[188:191], v[228:231], v[64:67]
	s_setprio 0
	s_barrier
	s_add_i32 s26, s73, s40
	v_lshl_add_u64 v[232:233], v[232:233], 0, s[34:35]
	s_mov_b32 m0, s26
	ds_read_b128 v[200:203], v171 offset:49152
	ds_read_b128 v[204:207], v171 offset:50176
	ds_read_b128 v[208:211], v171 offset:51200
	ds_read_b128 v[212:215], v171 offset:52224
	ds_read_b128 v[216:219], v171 offset:53248
	ds_read_b128 v[220:223], v171 offset:54272
	ds_read_b128 v[224:227], v171 offset:55296
	ds_read_b128 v[228:231], v171 offset:56320
	global_load_lds_dwordx4 v[232:233], off
	s_add_i32 m0, s26, 0x2000
	s_add_u32 s24, s24, 0x80080
	v_lshl_add_u64 v[232:233], v[234:235], 0, s[34:35]
	s_addc_u32 s25, s25, 0
	s_add_i32 s26, s74, s40
	global_load_lds_dwordx4 v[232:233], off
	v_lshl_add_u64 v[232:233], s[24:25], 0, v[152:153]
	s_mov_b32 m0, s26
	s_nop 0
	global_load_lds_dwordx4 v[232:233], off
	v_lshl_add_u64 v[232:233], s[24:25], 0, v[128:129]
	s_add_i32 m0, s26, 0x2000
	s_nop 0
	global_load_lds_dwordx4 v[232:233], off
	v_lshl_add_u64 v[232:233], v[236:237], 0, s[34:35]
	s_mov_b32 m0, s64
	s_nop 0
	global_load_lds_dwordx4 v[232:233], off
	v_lshl_add_u64 v[232:233], v[238:239], 0, s[34:35]
	s_mov_b32 m0, s65
	s_nop 0
	global_load_lds_dwordx4 v[232:233], off
	s_waitcnt vmcnt(8)
	s_waitcnt lgkmcnt(0)
	s_barrier
; #define PG8_STAGE(bufoff, gbase, voff) do { _Pragma("unroll") for (int _i = 0; _i < 2; ++_i) \
;         __builtin_amdgcn_global_load_lds((const unsigned*)((const char*)(gbase) + (voff)[_i]), (LAS unsigned*)(lds + (bufoff) + ldsw + _i * 8192), 16, 0, 0); } while (0)
; #define PG8_LDA(dst, b, h) do { _Pragma("unroll") for (int m = 0; m < 4; ++m) _Pragma("unroll") for (int k = 0; k < 2; ++k) dst[m][k] = *(const LAS bf16x8*)(lds + PG8_SA(b, h) + aoff + m * 2048 + k * 1024); } while (0)
; #define PG8_LDB(dst, b, h) do { _Pragma("unroll") for (int n = 0; n < 2; ++n) _Pragma("unroll") for (int k = 0; k < 2; ++k) dst[n][k] = *(const LAS bf16x8*)(lds + PG8_SB(b, h) + boff + n * 2048 + k * 1024); } while (0)
; #define PG8_MMA(ai, bj, At, Bt) do { __builtin_amdgcn_s_setprio(1); _Pragma("unroll") for (int m = 0; m < 4; ++m) _Pragma("unroll") for (int n = 0; n < 2; ++n) _Pragma("unroll") for (int k = 0; k < 2; ++k) \
;         acc[ai][bj][m][n] = __builtin_amdgcn_mfma_f32_16x16x32_bf16(Bt[n][k], At[m][k], acc[ai][bj][m][n], 0, 0, 0); __builtin_amdgcn_s_setprio(0); } while (0)
; #define PG8_WAIT_V(n) asm volatile("s_waitcnt vmcnt(" #n ")" ::: "memory")
; #define PG8_WAIT_L(n) asm volatile("s_waitcnt lgkmcnt(" #n ")" ::: "memory")
; #define PG8_BAR __builtin_amdgcn_s_barrier()
; #define PG8_SCHED __builtin_amdgcn_sched_barrier(0)
; template <class Epi, class Sched>
; __device__ __forceinline__ void gemm_phase(const int tid, LAS unsigned char* lds, const Gemm g, const Sched& S, const Epi& E) {
;     ...
;         for (int t = 0; t < nt; t += 2) {
;             const bool last = (t == nt - 2);
;             const char* a1 = cA + (size_t)(t + 1) * kstep;
;             const char* a2 = last ? nA : cA + (size_t)(t + 2) * kstep; const char* b2 = last ? nB : cB + (size_t)(t + 2) * kstep;
;             const char* a3 = a2 + kstep; const char* b3 = b2 + kstep;
;             if (last && has_next) S.a_ready(nxt);
;             PG8_LDB(B0, 0, 0); PG8_LDB(B1, 0, 1); PG8_SCHED; PG8_LDA(At, 0, 0); PG8_STAGE(PG8_SA(1, 1), a1 + hstep, voffA);
;             PG8_WAIT_V(8); PG8_WAIT_L(0); PG8_BAR; PG8_MMA(0, 0, At, B0); PG8_MMA(0, 1, At, B1); PG8_BAR; PG8_SCHED;
;     ...
;             PG8_WAIT_V(8); PG8_WAIT_L(0); PG8_BAR; PG8_MMA(1, 0, At, B0); PG8_MMA(1, 1, At, B1); PG8_BAR; PG8_SCHED;
	s_setprio 1
	s_waitcnt lgkmcnt(0)
	v_mfma_f32_16x16x32_bf16 v[60:63], v[138:141], v[200:203], v[60:63]
	v_mfma_f32_16x16x32_bf16 v[52:55], v[146:149], v[200:203], v[52:55]
	v_mfma_f32_16x16x32_bf16 v[44:47], v[138:141], v[208:211], v[44:47]
	v_mfma_f32_16x16x32_bf16 v[36:39], v[146:149], v[208:211], v[36:39]
	v_mfma_f32_16x16x32_bf16 v[28:31], v[138:141], v[216:219], v[28:31]
	v_mfma_f32_16x16x32_bf16 v[20:23], v[146:149], v[216:219], v[20:23]
	v_mfma_f32_16x16x32_bf16 v[12:15], v[138:141], v[224:227], v[12:15]
	v_mfma_f32_16x16x32_bf16 v[4:7], v[146:149], v[224:227], v[4:7]
	v_mfma_f32_16x16x32_bf16 v[60:63], v[142:145], v[204:207], v[60:63]
	v_mfma_f32_16x16x32_bf16 v[52:55], v[172:175], v[204:207], v[52:55]
	v_mfma_f32_16x16x32_bf16 v[44:47], v[142:145], v[212:215], v[44:47]
	v_mfma_f32_16x16x32_bf16 v[36:39], v[172:175], v[212:215], v[36:39]
	v_mfma_f32_16x16x32_bf16 v[28:31], v[142:145], v[220:223], v[28:31]
	v_mfma_f32_16x16x32_bf16 v[20:23], v[172:175], v[220:223], v[20:23]
	v_mfma_f32_16x16x32_bf16 v[12:15], v[142:145], v[228:231], v[12:15]
	v_mfma_f32_16x16x32_bf16 v[4:7], v[172:175], v[228:231], v[4:7]
	s_setprio 0
	s_setprio 1
	v_mfma_f32_16x16x32_bf16 v[56:59], v[176:179], v[200:203], v[56:59]
	v_mfma_f32_16x16x32_bf16 v[48:51], v[184:187], v[200:203], v[48:51]
	v_mfma_f32_16x16x32_bf16 v[40:43], v[176:179], v[208:211], v[40:43]
	v_mfma_f32_16x16x32_bf16 v[32:35], v[184:187], v[208:211], v[32:35]
	s_add_i32 s72, s72, 2
	s_add_u32 s22, s22, 0x100
	s_addc_u32 s23, s23, 0
	s_add_u32 s70, s70, 0x100
	s_addc_u32 s71, s71, 0
	v_mfma_f32_16x16x32_bf16 v[24:27], v[176:179], v[216:219], v[24:27]
	v_mfma_f32_16x16x32_bf16 v[16:19], v[184:187], v[216:219], v[16:19]
	v_mfma_f32_16x16x32_bf16 v[8:11], v[176:179], v[224:227], v[8:11]
	v_mfma_f32_16x16x32_bf16 v[0:3], v[184:187], v[224:227], v[0:3]
	v_mfma_f32_16x16x32_bf16 v[56:59], v[180:183], v[204:207], v[56:59]
	v_mfma_f32_16x16x32_bf16 v[48:51], v[188:191], v[204:207], v[48:51]
	v_mfma_f32_16x16x32_bf16 v[40:43], v[180:183], v[212:215], v[40:43]
	v_mfma_f32_16x16x32_bf16 v[32:35], v[188:191], v[212:215], v[32:35]
	v_mfma_f32_16x16x32_bf16 v[24:27], v[180:183], v[220:223], v[24:27]
	v_mfma_f32_16x16x32_bf16 v[16:19], v[188:191], v[220:223], v[16:19]
	v_mfma_f32_16x16x32_bf16 v[8:11], v[180:183], v[228:231], v[8:11]
	v_mfma_f32_16x16x32_bf16 v[0:3], v[188:191], v[228:231], v[0:3]
	s_setprio 0
	s_barrier
	s_cmp_gt_u32 s72, 29
.LBB0_670:
	s_add_u32 s24, s22, 0xfff80080
	s_addc_u32 s25, s23, -1
	s_add_i32 s73, 0, 0x10000
	s_cmp_eq_u32 s72, 28
	s_cselect_b32 s27, s15, s25
	s_cselect_b32 s26, s68, s24
	s_cselect_b32 s25, s13, s71
	s_cselect_b32 s24, s69, s70
	s_add_i32 s76, 0, 0x14000
	v_add_u32_e32 v172, s73, v170
	v_add_u32_e32 v188, s76, v170
	ds_read_b128 v[138:141], v172
	ds_read_b128 v[142:145], v172 offset:1024
	ds_read_b128 v[146:149], v172 offset:2048
	ds_read_b128 v[172:175], v172 offset:3072
	ds_read_b128 v[176:179], v188
	ds_read_b128 v[180:183], v188 offset:1024
	ds_read_b128 v[184:187], v188 offset:2048
	ds_read_b128 v[188:191], v188 offset:3072
	v_lshl_add_u64 v[232:233], s[22:23], 0, v[134:135]
	s_add_i32 m0, s58, 0xc000
	ds_read_b128 v[200:203], v171
	ds_read_b128 v[204:207], v171 offset:1024
	ds_read_b128 v[208:211], v171 offset:2048
	ds_read_b128 v[212:215], v171 offset:3072
	ds_read_b128 v[216:219], v171 offset:4096
	ds_read_b128 v[220:223], v171 offset:5120
	ds_read_b128 v[224:227], v171 offset:6144
	ds_read_b128 v[228:231], v171 offset:7168
	global_load_lds_dwordx4 v[232:233], off
	v_lshl_add_u64 v[232:233], s[22:23], 0, v[136:137]
	s_add_i32 m0, s58, 0xe000
	s_nop 0
	global_load_lds_dwordx4 v[232:233], off
	s_waitcnt vmcnt(8)
	s_waitcnt lgkmcnt(0)
	s_barrier
	s_setprio 1
	s_waitcnt lgkmcnt(0)
	v_mfma_f32_16x16x32_bf16 v[124:127], v[138:141], v[200:203], v[124:127]
	v_mfma_f32_16x16x32_bf16 v[116:119], v[146:149], v[200:203], v[116:119]
	v_mfma_f32_16x16x32_bf16 v[108:111], v[138:141], v[208:211], v[108:111]
	v_mfma_f32_16x16x32_bf16 v[100:103], v[146:149], v[208:211], v[100:103]
	v_mfma_f32_16x16x32_bf16 v[92:95], v[138:141], v[216:219], v[92:95]
	v_mfma_f32_16x16x32_bf16 v[84:87], v[146:149], v[216:219], v[84:87]
	v_mfma_f32_16x16x32_bf16 v[76:79], v[138:141], v[224:227], v[76:79]
	v_mfma_f32_16x16x32_bf16 v[68:71], v[146:149], v[224:227], v[68:71]
	v_mfma_f32_16x16x32_bf16 v[124:127], v[142:145], v[204:207], v[124:127]
	v_mfma_f32_16x16x32_bf16 v[116:119], v[172:175], v[204:207], v[116:119]
	v_mfma_f32_16x16x32_bf16 v[108:111], v[142:145], v[212:215], v[108:111]
	v_mfma_f32_16x16x32_bf16 v[100:103], v[172:175], v[212:215], v[100:103]
	v_mfma_f32_16x16x32_bf16 v[92:95], v[142:145], v[220:223], v[92:95]
	v_mfma_f32_16x16x32_bf16 v[84:87], v[172:175], v[220:223], v[84:87]
	v_mfma_f32_16x16x32_bf16 v[76:79], v[142:145], v[228:231], v[76:79]
	v_mfma_f32_16x16x32_bf16 v[68:71], v[172:175], v[228:231], v[68:71]
	s_setprio 0
	s_setprio 1
	v_mfma_f32_16x16x32_bf16 v[120:123], v[176:179], v[200:203], v[120:123]
	v_mfma_f32_16x16x32_bf16 v[112:115], v[184:187], v[200:203], v[112:115]
	v_mfma_f32_16x16x32_bf16 v[104:107], v[176:179], v[208:211], v[104:107]
	v_mfma_f32_16x16x32_bf16 v[96:99], v[184:187], v[208:211], v[96:99]
	v_mfma_f32_16x16x32_bf16 v[88:91], v[176:179], v[216:219], v[88:91]
	v_mfma_f32_16x16x32_bf16 v[80:83], v[184:187], v[216:219], v[80:83]
	v_mfma_f32_16x16x32_bf16 v[72:75], v[176:179], v[224:227], v[72:75]
	v_mfma_f32_16x16x32_bf16 v[64:67], v[184:187], v[224:227], v[64:67]
	v_mfma_f32_16x16x32_bf16 v[120:123], v[180:183], v[204:207], v[120:123]
	v_mfma_f32_16x16x32_bf16 v[112:115], v[188:191], v[204:207], v[112:115]
	v_mfma_f32_16x16x32_bf16 v[104:107], v[180:183], v[212:215], v[104:107]
	v_mfma_f32_16x16x32_bf16 v[96:99], v[188:191], v[212:215], v[96:99]
	v_mfma_f32_16x16x32_bf16 v[88:91], v[180:183], v[220:223], v[88:91]
	v_mfma_f32_16x16x32_bf16 v[80:83], v[188:191], v[220:223], v[80:83]
	v_mfma_f32_16x16x32_bf16 v[72:75], v[180:183], v[228:231], v[72:75]
	v_mfma_f32_16x16x32_bf16 v[64:67], v[188:191], v[228:231], v[64:67]
	s_setprio 0
	s_barrier
; #define PG8_STAGE(bufoff, gbase, voff) do { _Pragma("unroll") for (int _i = 0; _i < 2; ++_i) \
;         __builtin_amdgcn_global_load_lds((const unsigned*)((const char*)(gbase) + (voff)[_i]), (LAS unsigned*)(lds + (bufoff) + ldsw + _i * 8192), 16, 0, 0); } while (0)
; #define PG8_LDA(dst, b, h) do { _Pragma("unroll") for (int m = 0; m < 4; ++m) _Pragma("unroll") for (int k = 0; k < 2; ++k) dst[m][k] = *(const LAS bf16x8*)(lds + PG8_SA(b, h) + aoff + m * 2048 + k * 1024); } while (0)
; #define PG8_LDB(dst, b, h) do { _Pragma("unroll") for (int n = 0; n < 2; ++n) _Pragma("unroll") for (int k = 0; k < 2; ++k) dst[n][k] = *(const LAS bf16x8*)(lds + PG8_SB(b, h) + boff + n * 2048 + k * 1024); } while (0)
; #define PG8_MMA(ai, bj, At, Bt) do { __builtin_amdgcn_s_setprio(1); _Pragma("unroll") for (int m = 0; m < 4; ++m) _Pragma("unroll") for (int n = 0; n < 2; ++n) _Pragma("unroll") for (int k = 0; k < 2; ++k) \
;         acc[ai][bj][m][n] = __builtin_amdgcn_mfma_f32_16x16x32_bf16(Bt[n][k], At[m][k], acc[ai][bj][m][n], 0, 0, 0); __builtin_amdgcn_s_setprio(0); } while (0)
; #define PG8_WAIT_V(n) asm volatile("s_waitcnt vmcnt(" #n ")" ::: "memory")
; #define PG8_WAIT_L(n) asm volatile("s_waitcnt lgkmcnt(" #n ")" ::: "memory")
; #define PG8_BAR __builtin_amdgcn_s_barrier()
; #define PG8_SCHED __builtin_amdgcn_sched_barrier(0)
; template <class Epi, class Sched>
; __device__ __forceinline__ void gemm_phase(const int tid, LAS unsigned char* lds, const Gemm g, const Sched& S, const Epi& E) {
;     ...
;             PG8_LDA(At, 0, 1); PG8_STAGE(PG8_SB(0, 0), b2, voffB); PG8_STAGE(PG8_SB(0, 1), b2 + hstep, voffB); PG8_STAGE(PG8_SA(0, 0), a2, voffA);
;             PG8_WAIT_V(8); PG8_WAIT_L(0); PG8_BAR; PG8_MMA(1, 0, At, B0); PG8_MMA(1, 1, At, B1); PG8_BAR; PG8_SCHED;
;             PG8_LDB(B0, 1, 0); PG8_LDB(B1, 1, 1); PG8_SCHED; PG8_LDA(At, 1, 0); PG8_STAGE(PG8_SA(0, 1), a2 + hstep, voffA);
;             PG8_WAIT_V(8); PG8_WAIT_L(0); PG8_BAR; PG8_MMA(0, 0, At, B0); PG8_MMA(0, 1, At, B1); PG8_BAR; PG8_SCHED;
;             PG8_LDA(At, 1, 1); PG8_STAGE(PG8_SB(1, 0), b3, voffB); PG8_STAGE(PG8_SB(1, 1), b3 + hstep, voffB); PG8_STAGE(PG8_SA(1, 0), a3, voffA);
	s_add_i32 s73, s73, s40
	v_lshl_add_u64 v[232:233], s[24:25], 0, v[152:153]
	s_mov_b32 m0, s73
	ds_read_b128 v[200:203], v171 offset:16384
	ds_read_b128 v[204:207], v171 offset:17408
	ds_read_b128 v[208:211], v171 offset:18432
	ds_read_b128 v[212:215], v171 offset:19456
	ds_read_b128 v[216:219], v171 offset:20480
	ds_read_b128 v[220:223], v171 offset:21504
	ds_read_b128 v[224:227], v171 offset:22528
	ds_read_b128 v[228:231], v171 offset:23552
	global_load_lds_dwordx4 v[232:233], off
	s_add_i32 m0, s73, 0x2000
	s_add_u32 s74, s24, 0x80000
	v_lshl_add_u64 v[234:235], s[24:25], 0, v[128:129]
	s_addc_u32 s75, s25, 0
	s_add_i32 s73, s76, s40
	global_load_lds_dwordx4 v[234:235], off
	v_lshl_add_u64 v[236:237], s[74:75], 0, v[152:153]
	s_mov_b32 m0, s73
	v_lshl_add_u64 v[238:239], s[26:27], 0, v[130:131]
	global_load_lds_dwordx4 v[236:237], off
	v_lshl_add_u64 v[236:237], s[74:75], 0, v[128:129]
	s_add_i32 m0, s73, 0x2000
	s_nop 0
	global_load_lds_dwordx4 v[236:237], off
	v_lshl_add_u64 v[236:237], s[26:27], 0, v[132:133]
	s_mov_b32 m0, s58
	s_nop 0
	global_load_lds_dwordx4 v[236:237], off
	s_mov_b32 m0, s59
	s_nop 0
	global_load_lds_dwordx4 v[238:239], off
	s_waitcnt vmcnt(8)
	s_waitcnt lgkmcnt(0)
	s_barrier
	s_setprio 1
	s_waitcnt lgkmcnt(0)
	v_mfma_f32_16x16x32_bf16 v[60:63], v[138:141], v[200:203], v[60:63]
	v_mfma_f32_16x16x32_bf16 v[52:55], v[146:149], v[200:203], v[52:55]
	v_mfma_f32_16x16x32_bf16 v[44:47], v[138:141], v[208:211], v[44:47]
	v_mfma_f32_16x16x32_bf16 v[36:39], v[146:149], v[208:211], v[36:39]
	v_mfma_f32_16x16x32_bf16 v[28:31], v[138:141], v[216:219], v[28:31]
	v_mfma_f32_16x16x32_bf16 v[20:23], v[146:149], v[216:219], v[20:23]
	v_mfma_f32_16x16x32_bf16 v[12:15], v[138:141], v[224:227], v[12:15]
	v_mfma_f32_16x16x32_bf16 v[4:7], v[146:149], v[224:227], v[4:7]
	v_mfma_f32_16x16x32_bf16 v[60:63], v[142:145], v[204:207], v[60:63]
	v_mfma_f32_16x16x32_bf16 v[52:55], v[172:175], v[204:207], v[52:55]
	v_mfma_f32_16x16x32_bf16 v[44:47], v[142:145], v[212:215], v[44:47]
	v_mfma_f32_16x16x32_bf16 v[36:39], v[172:175], v[212:215], v[36:39]
	v_mfma_f32_16x16x32_bf16 v[28:31], v[142:145], v[220:223], v[28:31]
	v_mfma_f32_16x16x32_bf16 v[20:23], v[172:175], v[220:223], v[20:23]
	v_mfma_f32_16x16x32_bf16 v[12:15], v[142:145], v[228:231], v[12:15]
	v_mfma_f32_16x16x32_bf16 v[4:7], v[172:175], v[228:231], v[4:7]
	s_setprio 0
	s_setprio 1
	v_mfma_f32_16x16x32_bf16 v[56:59], v[176:179], v[200:203], v[56:59]
	v_mfma_f32_16x16x32_bf16 v[48:51], v[184:187], v[200:203], v[48:51]
	v_mfma_f32_16x16x32_bf16 v[40:43], v[176:179], v[208:211], v[40:43]
	v_mfma_f32_16x16x32_bf16 v[32:35], v[184:187], v[208:211], v[32:35]
	v_mfma_f32_16x16x32_bf16 v[24:27], v[176:179], v[216:219], v[24:27]
	v_mfma_f32_16x16x32_bf16 v[16:19], v[184:187], v[216:219], v[16:19]
	v_mfma_f32_16x16x32_bf16 v[8:11], v[176:179], v[224:227], v[8:11]
	v_mfma_f32_16x16x32_bf16 v[0:3], v[184:187], v[224:227], v[0:3]
	v_mfma_f32_16x16x32_bf16 v[56:59], v[180:183], v[204:207], v[56:59]
	v_mfma_f32_16x16x32_bf16 v[48:51], v[188:191], v[204:207], v[48:51]
	v_mfma_f32_16x16x32_bf16 v[40:43], v[180:183], v[212:215], v[40:43]
	v_mfma_f32_16x16x32_bf16 v[32:35], v[188:191], v[212:215], v[32:35]
	v_mfma_f32_16x16x32_bf16 v[24:27], v[180:183], v[220:223], v[24:27]
	v_mfma_f32_16x16x32_bf16 v[16:19], v[188:191], v[220:223], v[16:19]
	v_mfma_f32_16x16x32_bf16 v[8:11], v[180:183], v[228:231], v[8:11]
	v_mfma_f32_16x16x32_bf16 v[0:3], v[188:191], v[228:231], v[0:3]
	s_setprio 0
	s_barrier
	s_add_i32 s73, 0, 0x18000
	s_add_i32 s74, 0, 0x1c000
	v_add_u32_e32 v172, s73, v170
	v_add_u32_e32 v188, s74, v170
	ds_read_b128 v[138:141], v172
	ds_read_b128 v[142:145], v172 offset:1024
	ds_read_b128 v[146:149], v172 offset:2048
	ds_read_b128 v[172:175], v172 offset:3072
	ds_read_b128 v[176:179], v188
	ds_read_b128 v[180:183], v188 offset:1024
	ds_read_b128 v[184:187], v188 offset:2048
	ds_read_b128 v[188:191], v188 offset:3072
	s_add_u32 s26, s26, 0x80000
	s_addc_u32 s27, s27, 0
	s_mov_b32 m0, s60
	v_lshl_add_u64 v[240:241], s[26:27], 0, v[132:133]
	ds_read_b128 v[200:203], v171 offset:32768
	ds_read_b128 v[204:207], v171 offset:33792
	ds_read_b128 v[208:211], v171 offset:34816
	ds_read_b128 v[212:215], v171 offset:35840
	ds_read_b128 v[216:219], v171 offset:36864
	ds_read_b128 v[220:223], v171 offset:37888
	ds_read_b128 v[224:227], v171 offset:38912
	ds_read_b128 v[228:231], v171 offset:39936
	global_load_lds_dwordx4 v[240:241], off
	v_lshl_add_u64 v[240:241], s[26:27], 0, v[130:131]
	s_mov_b32 m0, s61
	s_nop 0
	global_load_lds_dwordx4 v[240:241], off
	s_waitcnt vmcnt(8)
	s_waitcnt lgkmcnt(0)
	s_barrier
; #define PG8_MMA(ai, bj, At, Bt) do { __builtin_amdgcn_s_setprio(1); _Pragma("unroll") for (int m = 0; m < 4; ++m) _Pragma("unroll") for (int n = 0; n < 2; ++n) _Pragma("unroll") for (int k = 0; k < 2; ++k) \
;         acc[ai][bj][m][n] = __builtin_amdgcn_mfma_f32_16x16x32_bf16(Bt[n][k], At[m][k], acc[ai][bj][m][n], 0, 0, 0); __builtin_amdgcn_s_setprio(0); } while (0)
; #define PG8_WAIT_V(n) asm volatile("s_waitcnt vmcnt(" #n ")" ::: "memory")
; #define PG8_WAIT_L(n) asm volatile("s_waitcnt lgkmcnt(" #n ")" ::: "memory")
; #define PG8_BAR __builtin_amdgcn_s_barrier()
; #define PG8_SCHED __builtin_amdgcn_sched_barrier(0)
; template <class Epi, class Sched>
; __device__ __forceinline__ void gemm_phase(const int tid, LAS unsigned char* lds, const Gemm g, const Sched& S, const Epi& E) {
;     ...
;             PG8_WAIT_V(8); PG8_WAIT_L(0); PG8_BAR; PG8_MMA(1, 0, At, B0); PG8_MMA(1, 1, At, B1); PG8_BAR; PG8_SCHED;
;         }
;         if (wr == 0) PG8_BAR;
	s_setprio 1
	s_waitcnt lgkmcnt(0)
	v_mfma_f32_16x16x32_bf16 v[124:127], v[138:141], v[200:203], v[124:127]
	v_mfma_f32_16x16x32_bf16 v[116:119], v[146:149], v[200:203], v[116:119]
	v_mfma_f32_16x16x32_bf16 v[108:111], v[138:141], v[208:211], v[108:111]
	v_mfma_f32_16x16x32_bf16 v[100:103], v[146:149], v[208:211], v[100:103]
	v_mfma_f32_16x16x32_bf16 v[92:95], v[138:141], v[216:219], v[92:95]
	v_mfma_f32_16x16x32_bf16 v[84:87], v[146:149], v[216:219], v[84:87]
	v_mfma_f32_16x16x32_bf16 v[76:79], v[138:141], v[224:227], v[76:79]
	v_mfma_f32_16x16x32_bf16 v[68:71], v[146:149], v[224:227], v[68:71]
	v_mfma_f32_16x16x32_bf16 v[124:127], v[142:145], v[204:207], v[124:127]
	v_mfma_f32_16x16x32_bf16 v[116:119], v[172:175], v[204:207], v[116:119]
	v_mfma_f32_16x16x32_bf16 v[108:111], v[142:145], v[212:215], v[108:111]
	v_mfma_f32_16x16x32_bf16 v[100:103], v[172:175], v[212:215], v[100:103]
	v_mfma_f32_16x16x32_bf16 v[92:95], v[142:145], v[220:223], v[92:95]
	v_mfma_f32_16x16x32_bf16 v[84:87], v[172:175], v[220:223], v[84:87]
	v_mfma_f32_16x16x32_bf16 v[76:79], v[142:145], v[228:231], v[76:79]
	v_mfma_f32_16x16x32_bf16 v[68:71], v[172:175], v[228:231], v[68:71]
	s_setprio 0
	s_setprio 1
	v_mfma_f32_16x16x32_bf16 v[120:123], v[176:179], v[200:203], v[120:123]
	v_mfma_f32_16x16x32_bf16 v[112:115], v[184:187], v[200:203], v[112:115]
	v_mfma_f32_16x16x32_bf16 v[104:107], v[176:179], v[208:211], v[104:107]
	v_mfma_f32_16x16x32_bf16 v[96:99], v[184:187], v[208:211], v[96:99]
	v_mfma_f32_16x16x32_bf16 v[88:91], v[176:179], v[216:219], v[88:91]
	v_mfma_f32_16x16x32_bf16 v[80:83], v[184:187], v[216:219], v[80:83]
	v_mfma_f32_16x16x32_bf16 v[72:75], v[176:179], v[224:227], v[72:75]
	v_mfma_f32_16x16x32_bf16 v[64:67], v[184:187], v[224:227], v[64:67]
	v_mfma_f32_16x16x32_bf16 v[120:123], v[180:183], v[204:207], v[120:123]
	v_mfma_f32_16x16x32_bf16 v[112:115], v[188:191], v[204:207], v[112:115]
	v_mfma_f32_16x16x32_bf16 v[104:107], v[180:183], v[212:215], v[104:107]
	v_mfma_f32_16x16x32_bf16 v[96:99], v[188:191], v[212:215], v[96:99]
	v_mfma_f32_16x16x32_bf16 v[88:91], v[180:183], v[220:223], v[88:91]
	v_mfma_f32_16x16x32_bf16 v[80:83], v[188:191], v[220:223], v[80:83]
	v_mfma_f32_16x16x32_bf16 v[72:75], v[180:183], v[228:231], v[72:75]
	v_mfma_f32_16x16x32_bf16 v[64:67], v[188:191], v[228:231], v[64:67]
	s_setprio 0
	s_barrier
	s_add_i32 s26, s73, s40
	v_lshl_add_u64 v[232:233], v[232:233], 0, s[34:35]
	s_mov_b32 m0, s26
	ds_read_b128 v[200:203], v171 offset:49152
	ds_read_b128 v[204:207], v171 offset:50176
	ds_read_b128 v[208:211], v171 offset:51200
	ds_read_b128 v[212:215], v171 offset:52224
	ds_read_b128 v[216:219], v171 offset:53248
	ds_read_b128 v[220:223], v171 offset:54272
	ds_read_b128 v[224:227], v171 offset:55296
	ds_read_b128 v[228:231], v171 offset:56320
	global_load_lds_dwordx4 v[232:233], off
	s_add_i32 m0, s26, 0x2000
	s_add_u32 s24, s24, 0x80080
	v_lshl_add_u64 v[232:233], v[234:235], 0, s[34:35]
	s_addc_u32 s25, s25, 0
	s_add_i32 s26, s74, s40
	global_load_lds_dwordx4 v[232:233], off
	v_lshl_add_u64 v[232:233], s[24:25], 0, v[152:153]
	s_mov_b32 m0, s26
	s_nop 0
	global_load_lds_dwordx4 v[232:233], off
	v_lshl_add_u64 v[232:233], s[24:25], 0, v[128:129]
	s_add_i32 m0, s26, 0x2000
	s_nop 0
	global_load_lds_dwordx4 v[232:233], off
	v_lshl_add_u64 v[232:233], v[236:237], 0, s[34:35]
	s_mov_b32 m0, s64
	s_nop 0
	global_load_lds_dwordx4 v[232:233], off
	v_lshl_add_u64 v[232:233], v[238:239], 0, s[34:35]
	s_mov_b32 m0, s65
	s_nop 0
	global_load_lds_dwordx4 v[232:233], off
	s_waitcnt vmcnt(8)
	s_waitcnt lgkmcnt(0)
	s_barrier
	s_setprio 1
	s_waitcnt lgkmcnt(0)
	v_mfma_f32_16x16x32_bf16 v[60:63], v[138:141], v[200:203], v[60:63]
	v_mfma_f32_16x16x32_bf16 v[52:55], v[146:149], v[200:203], v[52:55]
	v_mfma_f32_16x16x32_bf16 v[44:47], v[138:141], v[208:211], v[44:47]
	v_mfma_f32_16x16x32_bf16 v[36:39], v[146:149], v[208:211], v[36:39]
	v_mfma_f32_16x16x32_bf16 v[28:31], v[138:141], v[216:219], v[28:31]
	v_mfma_f32_16x16x32_bf16 v[20:23], v[146:149], v[216:219], v[20:23]
	v_mfma_f32_16x16x32_bf16 v[12:15], v[138:141], v[224:227], v[12:15]
	v_mfma_f32_16x16x32_bf16 v[4:7], v[146:149], v[224:227], v[4:7]
	v_mfma_f32_16x16x32_bf16 v[60:63], v[142:145], v[204:207], v[60:63]
	v_mfma_f32_16x16x32_bf16 v[52:55], v[172:175], v[204:207], v[52:55]
	v_mfma_f32_16x16x32_bf16 v[44:47], v[142:145], v[212:215], v[44:47]
	v_mfma_f32_16x16x32_bf16 v[36:39], v[172:175], v[212:215], v[36:39]
	v_mfma_f32_16x16x32_bf16 v[28:31], v[142:145], v[220:223], v[28:31]
	v_mfma_f32_16x16x32_bf16 v[20:23], v[172:175], v[220:223], v[20:23]
	v_mfma_f32_16x16x32_bf16 v[12:15], v[142:145], v[228:231], v[12:15]
	v_mfma_f32_16x16x32_bf16 v[4:7], v[172:175], v[228:231], v[4:7]
	s_setprio 0
	s_setprio 1
	v_mfma_f32_16x16x32_bf16 v[56:59], v[176:179], v[200:203], v[56:59]
	v_mfma_f32_16x16x32_bf16 v[48:51], v[184:187], v[200:203], v[48:51]
	v_mfma_f32_16x16x32_bf16 v[40:43], v[176:179], v[208:211], v[40:43]
	v_mfma_f32_16x16x32_bf16 v[32:35], v[184:187], v[208:211], v[32:35]
	s_add_i32 s72, s72, 2
	s_add_u32 s22, s22, 0x100
	s_addc_u32 s23, s23, 0
	s_add_u32 s70, s70, 0x100
	s_addc_u32 s71, s71, 0
	v_mfma_f32_16x16x32_bf16 v[24:27], v[176:179], v[216:219], v[24:27]
	v_mfma_f32_16x16x32_bf16 v[16:19], v[184:187], v[216:219], v[16:19]
	v_mfma_f32_16x16x32_bf16 v[8:11], v[176:179], v[224:227], v[8:11]
	v_mfma_f32_16x16x32_bf16 v[0:3], v[184:187], v[224:227], v[0:3]
	v_mfma_f32_16x16x32_bf16 v[56:59], v[180:183], v[204:207], v[56:59]
	v_mfma_f32_16x16x32_bf16 v[48:51], v[188:191], v[204:207], v[48:51]
	v_mfma_f32_16x16x32_bf16 v[40:43], v[180:183], v[212:215], v[40:43]
	v_mfma_f32_16x16x32_bf16 v[32:35], v[188:191], v[212:215], v[32:35]
	v_mfma_f32_16x16x32_bf16 v[24:27], v[180:183], v[220:223], v[24:27]
	v_mfma_f32_16x16x32_bf16 v[16:19], v[188:191], v[220:223], v[16:19]
	v_mfma_f32_16x16x32_bf16 v[8:11], v[180:183], v[228:231], v[8:11]
	v_mfma_f32_16x16x32_bf16 v[0:3], v[188:191], v[228:231], v[0:3]
	s_setprio 0
	s_barrier
	s_cmp_gt_u32 s72, 29
	s_cbranch_scc0 .LBB0_670
	s_and_b64 vcc, exec, s[10:11]
	s_cbranch_vccz .LBB0_673
	s_barrier
